# skinny16 loops: operands fetched as 8 rows x 128 B per load (full lines) + DPP row-shift fix-up into MFMA fragments (was 16 rows x 64 B per load)
# speedup vs baseline: 1.0026x; 1.0026x over previous
; __device__ __forceinline__ f32x4 skinny16(const bf16_t* A, int lda, const bf16_t* Bt, int ldb, int K, int lane) {
;     const int r = lane & 15, q = lane >> 4;
;     const bf16x8* ap = (const bf16x8*)(A + (size_t)r * lda + q * 8);
;     const bf16x8* bp = (const bf16x8*)(Bt + (size_t)r * ldb + q * 8);
;     f32x4 acc0 = {0.f, 0.f, 0.f, 0.f}, acc1 = {0.f, 0.f, 0.f, 0.f};
; #pragma unroll 1
;     for (int k = 0; k < K / 32; k += 16) {
;         bf16x8 a[16], b[16];
; #pragma unroll
;         for (int i = 0; i < 16; ++i) { a[i] = ap[(k + i) * 4]; b[i] = bp[(k + i) * 4]; }
; #pragma unroll
;         for (int i = 0; i < 16; i += 2) { acc0 = __builtin_amdgcn_mfma_f32_16x16x32_bf16(a[i], b[i], acc0, 0, 0, 0); acc1 = __builtin_amdgcn_mfma_f32_16x16x32_bf16(a[i + 1], b[i + 1], acc1, 0, 0, 0); }
.LBB0_363:
	v_bfe_u32 v252, v200, 3, 1
	v_mul_u32_u24_e32 v252, 0x7fc0, v252
	v_sub_u32_e32 v252, 0, v252
	v_ashrrev_i32_e32 v253, 31, v252
	v_lshl_add_u64 v[244:245], v[16:17], 0, v[252:253]
	v_lshl_add_u64 v[248:249], v[18:19], 0, v[252:253]
	v_mov_b32_e32 v252, 0x8000
	v_mov_b32_e32 v253, 0
	v_lshl_add_u64 v[246:247], v[244:245], 0, v[252:253]
	v_lshl_add_u64 v[250:251], v[248:249], 0, v[252:253]
	global_load_dwordx4 v[68:71], v[244:245], off offset:-512
	global_load_dwordx4 v[72:75], v[246:247], off offset:-512
	global_load_dwordx4 v[76:79], v[248:249], off offset:-512
	global_load_dwordx4 v[80:83], v[250:251], off offset:-512
	global_load_dwordx4 v[84:87], v[244:245], off offset:-384
	global_load_dwordx4 v[88:91], v[246:247], off offset:-384
	global_load_dwordx4 v[92:95], v[248:249], off offset:-384
	global_load_dwordx4 v[96:99], v[250:251], off offset:-384
	global_load_dwordx4 v[100:103], v[244:245], off offset:-256
	global_load_dwordx4 v[104:107], v[246:247], off offset:-256
	global_load_dwordx4 v[108:111], v[248:249], off offset:-256
	global_load_dwordx4 v[112:115], v[250:251], off offset:-256
	global_load_dwordx4 v[116:119], v[244:245], off offset:-128
	global_load_dwordx4 v[120:123], v[246:247], off offset:-128
	global_load_dwordx4 v[124:127], v[248:249], off offset:-128
	global_load_dwordx4 v[128:131], v[250:251], off offset:-128
	global_load_dwordx4 v[132:135], v[244:245], off offset:0
	global_load_dwordx4 v[136:139], v[246:247], off offset:0
	global_load_dwordx4 v[140:143], v[248:249], off offset:0
	global_load_dwordx4 v[144:147], v[250:251], off offset:0
	global_load_dwordx4 v[148:151], v[244:245], off offset:128
	global_load_dwordx4 v[164:167], v[246:247], off offset:128
	global_load_dwordx4 v[168:171], v[248:249], off offset:128
	global_load_dwordx4 v[172:175], v[250:251], off offset:128
	global_load_dwordx4 v[176:179], v[244:245], off offset:256
	global_load_dwordx4 v[180:183], v[246:247], off offset:256
	global_load_dwordx4 v[184:187], v[248:249], off offset:256
	global_load_dwordx4 v[188:191], v[250:251], off offset:256
	global_load_dwordx4 v[204:207], v[244:245], off offset:384
	global_load_dwordx4 v[208:211], v[246:247], off offset:384
	global_load_dwordx4 v[212:215], v[248:249], off offset:384
	global_load_dwordx4 v[216:219], v[250:251], off offset:384
	global_load_dwordx4 v[220:223], v[244:245], off offset:512
	global_load_dwordx4 v[224:227], v[246:247], off offset:512
	global_load_dwordx4 v[228:231], v[248:249], off offset:512
	global_load_dwordx4 v[232:235], v[250:251], off offset:512
	s_waitcnt vmcnt(32)
	v_mov_b32_e32 v236, v68
	v_mov_b32_e32 v237, v69
	v_mov_b32_e32 v238, v70
	v_mov_b32_e32 v239, v71
	v_mov_b32_e32 v240, v76
	v_mov_b32_e32 v241, v77
	v_mov_b32_e32 v242, v78
	v_mov_b32_e32 v243, v79
	v_mov_b32_dpp v236, v72 row_shr:8 row_mask:0xf bank_mask:0xc
	v_mov_b32_dpp v237, v73 row_shr:8 row_mask:0xf bank_mask:0xc
	v_mov_b32_dpp v238, v74 row_shr:8 row_mask:0xf bank_mask:0xc
	v_mov_b32_dpp v239, v75 row_shr:8 row_mask:0xf bank_mask:0xc
	v_mov_b32_dpp v240, v80 row_shr:8 row_mask:0xf bank_mask:0xc
	v_mov_b32_dpp v241, v81 row_shr:8 row_mask:0xf bank_mask:0xc
	v_mov_b32_dpp v242, v82 row_shr:8 row_mask:0xf bank_mask:0xc
	v_mov_b32_dpp v243, v83 row_shr:8 row_mask:0xf bank_mask:0xc
	v_mov_b32_dpp v72, v68 row_shl:8 row_mask:0xf bank_mask:0x3
	v_mov_b32_dpp v73, v69 row_shl:8 row_mask:0xf bank_mask:0x3
	v_mov_b32_dpp v74, v70 row_shl:8 row_mask:0xf bank_mask:0x3
	v_mov_b32_dpp v75, v71 row_shl:8 row_mask:0xf bank_mask:0x3
	v_mov_b32_dpp v80, v76 row_shl:8 row_mask:0xf bank_mask:0x3
	v_mov_b32_dpp v81, v77 row_shl:8 row_mask:0xf bank_mask:0x3
	v_mov_b32_dpp v82, v78 row_shl:8 row_mask:0xf bank_mask:0x3
	v_mov_b32_dpp v83, v79 row_shl:8 row_mask:0xf bank_mask:0x3
	v_mfma_f32_16x16x32_bf16 v[4:7], v[236:239], v[240:243], v[4:7]
	s_nop 0
	v_mfma_f32_16x16x32_bf16 v[0:3], v[72:75], v[80:83], v[0:3]
	global_load_dwordx4 v[68:71], v[244:245], off offset:640
	global_load_dwordx4 v[72:75], v[246:247], off offset:640
	global_load_dwordx4 v[76:79], v[248:249], off offset:640
	global_load_dwordx4 v[80:83], v[250:251], off offset:640
	s_waitcnt vmcnt(32)
	v_mov_b32_e32 v236, v84
	v_mov_b32_e32 v237, v85
	v_mov_b32_e32 v238, v86
	v_mov_b32_e32 v239, v87
	v_mov_b32_e32 v240, v92
	v_mov_b32_e32 v241, v93
	v_mov_b32_e32 v242, v94
	v_mov_b32_e32 v243, v95
	v_mov_b32_dpp v236, v88 row_shr:8 row_mask:0xf bank_mask:0xc
	v_mov_b32_dpp v237, v89 row_shr:8 row_mask:0xf bank_mask:0xc
	v_mov_b32_dpp v238, v90 row_shr:8 row_mask:0xf bank_mask:0xc
	v_mov_b32_dpp v239, v91 row_shr:8 row_mask:0xf bank_mask:0xc
	v_mov_b32_dpp v240, v96 row_shr:8 row_mask:0xf bank_mask:0xc
	v_mov_b32_dpp v241, v97 row_shr:8 row_mask:0xf bank_mask:0xc
	v_mov_b32_dpp v242, v98 row_shr:8 row_mask:0xf bank_mask:0xc
	v_mov_b32_dpp v243, v99 row_shr:8 row_mask:0xf bank_mask:0xc
	v_mov_b32_dpp v88, v84 row_shl:8 row_mask:0xf bank_mask:0x3
	v_mov_b32_dpp v89, v85 row_shl:8 row_mask:0xf bank_mask:0x3
	v_mov_b32_dpp v90, v86 row_shl:8 row_mask:0xf bank_mask:0x3
	v_mov_b32_dpp v91, v87 row_shl:8 row_mask:0xf bank_mask:0x3
	v_mov_b32_dpp v96, v92 row_shl:8 row_mask:0xf bank_mask:0x3
	v_mov_b32_dpp v97, v93 row_shl:8 row_mask:0xf bank_mask:0x3
	v_mov_b32_dpp v98, v94 row_shl:8 row_mask:0xf bank_mask:0x3
	v_mov_b32_dpp v99, v95 row_shl:8 row_mask:0xf bank_mask:0x3
	v_mfma_f32_16x16x32_bf16 v[4:7], v[236:239], v[240:243], v[4:7]
	s_nop 0
	v_mfma_f32_16x16x32_bf16 v[0:3], v[88:91], v[96:99], v[0:3]
	global_load_dwordx4 v[84:87], v[244:245], off offset:768
	global_load_dwordx4 v[88:91], v[246:247], off offset:768
	global_load_dwordx4 v[92:95], v[248:249], off offset:768
	global_load_dwordx4 v[96:99], v[250:251], off offset:768
	s_waitcnt vmcnt(32)
; __device__ __forceinline__ f32x4 skinny16(const bf16_t* A, int lda, const bf16_t* Bt, int ldb, int K, int lane) {
;     ...
;     for (int k = 0; k < K / 32; k += 16) {
;         bf16x8 a[16], b[16];
; #pragma unroll
;         for (int i = 0; i < 16; ++i) { a[i] = ap[(k + i) * 4]; b[i] = bp[(k + i) * 4]; }
; #pragma unroll
;         for (int i = 0; i < 16; i += 2) { acc0 = __builtin_amdgcn_mfma_f32_16x16x32_bf16(a[i], b[i], acc0, 0, 0, 0); acc1 = __builtin_amdgcn_mfma_f32_16x16x32_bf16(a[i + 1], b[i + 1], acc1, 0, 0, 0); }
	v_mov_b32_e32 v236, v100
	v_mov_b32_e32 v237, v101
	v_mov_b32_e32 v238, v102
	v_mov_b32_e32 v239, v103
	v_mov_b32_e32 v240, v108
	v_mov_b32_e32 v241, v109
	v_mov_b32_e32 v242, v110
	v_mov_b32_e32 v243, v111
	v_mov_b32_dpp v236, v104 row_shr:8 row_mask:0xf bank_mask:0xc
	v_mov_b32_dpp v237, v105 row_shr:8 row_mask:0xf bank_mask:0xc
	v_mov_b32_dpp v238, v106 row_shr:8 row_mask:0xf bank_mask:0xc
	v_mov_b32_dpp v239, v107 row_shr:8 row_mask:0xf bank_mask:0xc
	v_mov_b32_dpp v240, v112 row_shr:8 row_mask:0xf bank_mask:0xc
	v_mov_b32_dpp v241, v113 row_shr:8 row_mask:0xf bank_mask:0xc
	v_mov_b32_dpp v242, v114 row_shr:8 row_mask:0xf bank_mask:0xc
	v_mov_b32_dpp v243, v115 row_shr:8 row_mask:0xf bank_mask:0xc
	v_mov_b32_dpp v104, v100 row_shl:8 row_mask:0xf bank_mask:0x3
	v_mov_b32_dpp v105, v101 row_shl:8 row_mask:0xf bank_mask:0x3
	v_mov_b32_dpp v106, v102 row_shl:8 row_mask:0xf bank_mask:0x3
	v_mov_b32_dpp v107, v103 row_shl:8 row_mask:0xf bank_mask:0x3
	v_mov_b32_dpp v112, v108 row_shl:8 row_mask:0xf bank_mask:0x3
	v_mov_b32_dpp v113, v109 row_shl:8 row_mask:0xf bank_mask:0x3
	v_mov_b32_dpp v114, v110 row_shl:8 row_mask:0xf bank_mask:0x3
	v_mov_b32_dpp v115, v111 row_shl:8 row_mask:0xf bank_mask:0x3
	v_mfma_f32_16x16x32_bf16 v[4:7], v[236:239], v[240:243], v[4:7]
	s_nop 0
	v_mfma_f32_16x16x32_bf16 v[0:3], v[104:107], v[112:115], v[0:3]
	global_load_dwordx4 v[100:103], v[244:245], off offset:896
	global_load_dwordx4 v[104:107], v[246:247], off offset:896
	global_load_dwordx4 v[108:111], v[248:249], off offset:896
	global_load_dwordx4 v[112:115], v[250:251], off offset:896
	s_waitcnt vmcnt(32)
	v_mov_b32_e32 v236, v116
	v_mov_b32_e32 v237, v117
	v_mov_b32_e32 v238, v118
	v_mov_b32_e32 v239, v119
	v_mov_b32_e32 v240, v124
	v_mov_b32_e32 v241, v125
	v_mov_b32_e32 v242, v126
	v_mov_b32_e32 v243, v127
	v_mov_b32_dpp v236, v120 row_shr:8 row_mask:0xf bank_mask:0xc
	v_mov_b32_dpp v237, v121 row_shr:8 row_mask:0xf bank_mask:0xc
	v_mov_b32_dpp v238, v122 row_shr:8 row_mask:0xf bank_mask:0xc
	v_mov_b32_dpp v239, v123 row_shr:8 row_mask:0xf bank_mask:0xc
	v_mov_b32_dpp v240, v128 row_shr:8 row_mask:0xf bank_mask:0xc
	v_mov_b32_dpp v241, v129 row_shr:8 row_mask:0xf bank_mask:0xc
	v_mov_b32_dpp v242, v130 row_shr:8 row_mask:0xf bank_mask:0xc
	v_mov_b32_dpp v243, v131 row_shr:8 row_mask:0xf bank_mask:0xc
	v_mov_b32_dpp v120, v116 row_shl:8 row_mask:0xf bank_mask:0x3
	v_mov_b32_dpp v121, v117 row_shl:8 row_mask:0xf bank_mask:0x3
	v_mov_b32_dpp v122, v118 row_shl:8 row_mask:0xf bank_mask:0x3
	v_mov_b32_dpp v123, v119 row_shl:8 row_mask:0xf bank_mask:0x3
	v_mov_b32_dpp v128, v124 row_shl:8 row_mask:0xf bank_mask:0x3
	v_mov_b32_dpp v129, v125 row_shl:8 row_mask:0xf bank_mask:0x3
	v_mov_b32_dpp v130, v126 row_shl:8 row_mask:0xf bank_mask:0x3
	v_mov_b32_dpp v131, v127 row_shl:8 row_mask:0xf bank_mask:0x3
	v_mfma_f32_16x16x32_bf16 v[4:7], v[236:239], v[240:243], v[4:7]
	s_nop 0
	v_mfma_f32_16x16x32_bf16 v[0:3], v[120:123], v[128:131], v[0:3]
	global_load_dwordx4 v[116:119], v[244:245], off offset:1024
	global_load_dwordx4 v[120:123], v[246:247], off offset:1024
	global_load_dwordx4 v[124:127], v[248:249], off offset:1024
	global_load_dwordx4 v[128:131], v[250:251], off offset:1024
	s_waitcnt vmcnt(32)
	v_mov_b32_e32 v236, v132
	v_mov_b32_e32 v237, v133
	v_mov_b32_e32 v238, v134
	v_mov_b32_e32 v239, v135
	v_mov_b32_e32 v240, v140
	v_mov_b32_e32 v241, v141
	v_mov_b32_e32 v242, v142
	v_mov_b32_e32 v243, v143
	v_mov_b32_dpp v236, v136 row_shr:8 row_mask:0xf bank_mask:0xc
	v_mov_b32_dpp v237, v137 row_shr:8 row_mask:0xf bank_mask:0xc
	v_mov_b32_dpp v238, v138 row_shr:8 row_mask:0xf bank_mask:0xc
	v_mov_b32_dpp v239, v139 row_shr:8 row_mask:0xf bank_mask:0xc
	v_mov_b32_dpp v240, v144 row_shr:8 row_mask:0xf bank_mask:0xc
	v_mov_b32_dpp v241, v145 row_shr:8 row_mask:0xf bank_mask:0xc
	v_mov_b32_dpp v242, v146 row_shr:8 row_mask:0xf bank_mask:0xc
	v_mov_b32_dpp v243, v147 row_shr:8 row_mask:0xf bank_mask:0xc
	v_mov_b32_dpp v136, v132 row_shl:8 row_mask:0xf bank_mask:0x3
	v_mov_b32_dpp v137, v133 row_shl:8 row_mask:0xf bank_mask:0x3
	v_mov_b32_dpp v138, v134 row_shl:8 row_mask:0xf bank_mask:0x3
	v_mov_b32_dpp v139, v135 row_shl:8 row_mask:0xf bank_mask:0x3
	v_mov_b32_dpp v144, v140 row_shl:8 row_mask:0xf bank_mask:0x3
	v_mov_b32_dpp v145, v141 row_shl:8 row_mask:0xf bank_mask:0x3
	v_mov_b32_dpp v146, v142 row_shl:8 row_mask:0xf bank_mask:0x3
	v_mov_b32_dpp v147, v143 row_shl:8 row_mask:0xf bank_mask:0x3
	v_mfma_f32_16x16x32_bf16 v[4:7], v[236:239], v[240:243], v[4:7]
	s_nop 0
	v_mfma_f32_16x16x32_bf16 v[0:3], v[136:139], v[144:147], v[0:3]
	global_load_dwordx4 v[132:135], v[244:245], off offset:1152
	global_load_dwordx4 v[136:139], v[246:247], off offset:1152
	global_load_dwordx4 v[140:143], v[248:249], off offset:1152
	global_load_dwordx4 v[144:147], v[250:251], off offset:1152
	s_waitcnt vmcnt(32)
; __device__ __forceinline__ f32x4 skinny16(const bf16_t* A, int lda, const bf16_t* Bt, int ldb, int K, int lane) {
;     ...
;     for (int k = 0; k < K / 32; k += 16) {
;         bf16x8 a[16], b[16];
; #pragma unroll
;         for (int i = 0; i < 16; ++i) { a[i] = ap[(k + i) * 4]; b[i] = bp[(k + i) * 4]; }
; #pragma unroll
;         for (int i = 0; i < 16; i += 2) { acc0 = __builtin_amdgcn_mfma_f32_16x16x32_bf16(a[i], b[i], acc0, 0, 0, 0); acc1 = __builtin_amdgcn_mfma_f32_16x16x32_bf16(a[i + 1], b[i + 1], acc1, 0, 0, 0); }
	v_mov_b32_e32 v236, v148
	v_mov_b32_e32 v237, v149
	v_mov_b32_e32 v238, v150
	v_mov_b32_e32 v239, v151
	v_mov_b32_e32 v240, v168
	v_mov_b32_e32 v241, v169
	v_mov_b32_e32 v242, v170
	v_mov_b32_e32 v243, v171
	v_mov_b32_dpp v236, v164 row_shr:8 row_mask:0xf bank_mask:0xc
	v_mov_b32_dpp v237, v165 row_shr:8 row_mask:0xf bank_mask:0xc
	v_mov_b32_dpp v238, v166 row_shr:8 row_mask:0xf bank_mask:0xc
	v_mov_b32_dpp v239, v167 row_shr:8 row_mask:0xf bank_mask:0xc
	v_mov_b32_dpp v240, v172 row_shr:8 row_mask:0xf bank_mask:0xc
	v_mov_b32_dpp v241, v173 row_shr:8 row_mask:0xf bank_mask:0xc
	v_mov_b32_dpp v242, v174 row_shr:8 row_mask:0xf bank_mask:0xc
	v_mov_b32_dpp v243, v175 row_shr:8 row_mask:0xf bank_mask:0xc
	v_mov_b32_dpp v164, v148 row_shl:8 row_mask:0xf bank_mask:0x3
	v_mov_b32_dpp v165, v149 row_shl:8 row_mask:0xf bank_mask:0x3
	v_mov_b32_dpp v166, v150 row_shl:8 row_mask:0xf bank_mask:0x3
	v_mov_b32_dpp v167, v151 row_shl:8 row_mask:0xf bank_mask:0x3
	v_mov_b32_dpp v172, v168 row_shl:8 row_mask:0xf bank_mask:0x3
	v_mov_b32_dpp v173, v169 row_shl:8 row_mask:0xf bank_mask:0x3
	v_mov_b32_dpp v174, v170 row_shl:8 row_mask:0xf bank_mask:0x3
	v_mov_b32_dpp v175, v171 row_shl:8 row_mask:0xf bank_mask:0x3
	v_mfma_f32_16x16x32_bf16 v[4:7], v[236:239], v[240:243], v[4:7]
	s_nop 0
	v_mfma_f32_16x16x32_bf16 v[0:3], v[164:167], v[172:175], v[0:3]
	global_load_dwordx4 v[148:151], v[244:245], off offset:1280
	global_load_dwordx4 v[164:167], v[246:247], off offset:1280
	global_load_dwordx4 v[168:171], v[248:249], off offset:1280
	global_load_dwordx4 v[172:175], v[250:251], off offset:1280
	s_waitcnt vmcnt(32)
	v_mov_b32_e32 v236, v176
	v_mov_b32_e32 v237, v177
	v_mov_b32_e32 v238, v178
	v_mov_b32_e32 v239, v179
	v_mov_b32_e32 v240, v184
	v_mov_b32_e32 v241, v185
	v_mov_b32_e32 v242, v186
	v_mov_b32_e32 v243, v187
	v_mov_b32_dpp v236, v180 row_shr:8 row_mask:0xf bank_mask:0xc
	v_mov_b32_dpp v237, v181 row_shr:8 row_mask:0xf bank_mask:0xc
	v_mov_b32_dpp v238, v182 row_shr:8 row_mask:0xf bank_mask:0xc
	v_mov_b32_dpp v239, v183 row_shr:8 row_mask:0xf bank_mask:0xc
	v_mov_b32_dpp v240, v188 row_shr:8 row_mask:0xf bank_mask:0xc
	v_mov_b32_dpp v241, v189 row_shr:8 row_mask:0xf bank_mask:0xc
	v_mov_b32_dpp v242, v190 row_shr:8 row_mask:0xf bank_mask:0xc
	v_mov_b32_dpp v243, v191 row_shr:8 row_mask:0xf bank_mask:0xc
	v_mov_b32_dpp v180, v176 row_shl:8 row_mask:0xf bank_mask:0x3
	v_mov_b32_dpp v181, v177 row_shl:8 row_mask:0xf bank_mask:0x3
	v_mov_b32_dpp v182, v178 row_shl:8 row_mask:0xf bank_mask:0x3
	v_mov_b32_dpp v183, v179 row_shl:8 row_mask:0xf bank_mask:0x3
	v_mov_b32_dpp v188, v184 row_shl:8 row_mask:0xf bank_mask:0x3
	v_mov_b32_dpp v189, v185 row_shl:8 row_mask:0xf bank_mask:0x3
	v_mov_b32_dpp v190, v186 row_shl:8 row_mask:0xf bank_mask:0x3
	v_mov_b32_dpp v191, v187 row_shl:8 row_mask:0xf bank_mask:0x3
	v_mfma_f32_16x16x32_bf16 v[4:7], v[236:239], v[240:243], v[4:7]
	s_nop 0
	v_mfma_f32_16x16x32_bf16 v[0:3], v[180:183], v[188:191], v[0:3]
	global_load_dwordx4 v[176:179], v[244:245], off offset:1408
	global_load_dwordx4 v[180:183], v[246:247], off offset:1408
	global_load_dwordx4 v[184:187], v[248:249], off offset:1408
	global_load_dwordx4 v[188:191], v[250:251], off offset:1408
	s_waitcnt vmcnt(32)
	v_mov_b32_e32 v236, v204
	v_mov_b32_e32 v237, v205
	v_mov_b32_e32 v238, v206
	v_mov_b32_e32 v239, v207
	v_mov_b32_e32 v240, v212
	v_mov_b32_e32 v241, v213
	v_mov_b32_e32 v242, v214
	v_mov_b32_e32 v243, v215
	v_mov_b32_dpp v236, v208 row_shr:8 row_mask:0xf bank_mask:0xc
	v_mov_b32_dpp v237, v209 row_shr:8 row_mask:0xf bank_mask:0xc
	v_mov_b32_dpp v238, v210 row_shr:8 row_mask:0xf bank_mask:0xc
	v_mov_b32_dpp v239, v211 row_shr:8 row_mask:0xf bank_mask:0xc
	v_mov_b32_dpp v240, v216 row_shr:8 row_mask:0xf bank_mask:0xc
	v_mov_b32_dpp v241, v217 row_shr:8 row_mask:0xf bank_mask:0xc
	v_mov_b32_dpp v242, v218 row_shr:8 row_mask:0xf bank_mask:0xc
	v_mov_b32_dpp v243, v219 row_shr:8 row_mask:0xf bank_mask:0xc
	v_mov_b32_dpp v208, v204 row_shl:8 row_mask:0xf bank_mask:0x3
	v_mov_b32_dpp v209, v205 row_shl:8 row_mask:0xf bank_mask:0x3
	v_mov_b32_dpp v210, v206 row_shl:8 row_mask:0xf bank_mask:0x3
	v_mov_b32_dpp v211, v207 row_shl:8 row_mask:0xf bank_mask:0x3
	v_mov_b32_dpp v216, v212 row_shl:8 row_mask:0xf bank_mask:0x3
	v_mov_b32_dpp v217, v213 row_shl:8 row_mask:0xf bank_mask:0x3
	v_mov_b32_dpp v218, v214 row_shl:8 row_mask:0xf bank_mask:0x3
	v_mov_b32_dpp v219, v215 row_shl:8 row_mask:0xf bank_mask:0x3
	v_mfma_f32_16x16x32_bf16 v[4:7], v[236:239], v[240:243], v[4:7]
	s_nop 0
	v_mfma_f32_16x16x32_bf16 v[0:3], v[208:211], v[216:219], v[0:3]
	global_load_dwordx4 v[204:207], v[244:245], off offset:1536
	global_load_dwordx4 v[208:211], v[246:247], off offset:1536
	global_load_dwordx4 v[212:215], v[248:249], off offset:1536
	global_load_dwordx4 v[216:219], v[250:251], off offset:1536
	s_waitcnt vmcnt(32)
; __device__ __forceinline__ f32x4 skinny16(const bf16_t* A, int lda, const bf16_t* Bt, int ldb, int K, int lane) {
;     ...
;     for (int k = 0; k < K / 32; k += 16) {
;         bf16x8 a[16], b[16];
; #pragma unroll
;         for (int i = 0; i < 16; ++i) { a[i] = ap[(k + i) * 4]; b[i] = bp[(k + i) * 4]; }
; #pragma unroll
;         for (int i = 0; i < 16; i += 2) { acc0 = __builtin_amdgcn_mfma_f32_16x16x32_bf16(a[i], b[i], acc0, 0, 0, 0); acc1 = __builtin_amdgcn_mfma_f32_16x16x32_bf16(a[i + 1], b[i + 1], acc1, 0, 0, 0); }
	v_mov_b32_e32 v236, v220
	v_mov_b32_e32 v237, v221
	v_mov_b32_e32 v238, v222
	v_mov_b32_e32 v239, v223
	v_mov_b32_e32 v240, v228
	v_mov_b32_e32 v241, v229
	v_mov_b32_e32 v242, v230
	v_mov_b32_e32 v243, v231
	v_mov_b32_dpp v236, v224 row_shr:8 row_mask:0xf bank_mask:0xc
	v_mov_b32_dpp v237, v225 row_shr:8 row_mask:0xf bank_mask:0xc
	v_mov_b32_dpp v238, v226 row_shr:8 row_mask:0xf bank_mask:0xc
	v_mov_b32_dpp v239, v227 row_shr:8 row_mask:0xf bank_mask:0xc
	v_mov_b32_dpp v240, v232 row_shr:8 row_mask:0xf bank_mask:0xc
	v_mov_b32_dpp v241, v233 row_shr:8 row_mask:0xf bank_mask:0xc
	v_mov_b32_dpp v242, v234 row_shr:8 row_mask:0xf bank_mask:0xc
	v_mov_b32_dpp v243, v235 row_shr:8 row_mask:0xf bank_mask:0xc
	v_mov_b32_dpp v224, v220 row_shl:8 row_mask:0xf bank_mask:0x3
	v_mov_b32_dpp v225, v221 row_shl:8 row_mask:0xf bank_mask:0x3
	v_mov_b32_dpp v226, v222 row_shl:8 row_mask:0xf bank_mask:0x3
	v_mov_b32_dpp v227, v223 row_shl:8 row_mask:0xf bank_mask:0x3
	v_mov_b32_dpp v232, v228 row_shl:8 row_mask:0xf bank_mask:0x3
	v_mov_b32_dpp v233, v229 row_shl:8 row_mask:0xf bank_mask:0x3
	v_mov_b32_dpp v234, v230 row_shl:8 row_mask:0xf bank_mask:0x3
	v_mov_b32_dpp v235, v231 row_shl:8 row_mask:0xf bank_mask:0x3
	v_mfma_f32_16x16x32_bf16 v[4:7], v[236:239], v[240:243], v[4:7]
	s_nop 0
	v_mfma_f32_16x16x32_bf16 v[0:3], v[224:227], v[232:235], v[0:3]
	global_load_dwordx4 v[220:223], v[244:245], off offset:1664
	global_load_dwordx4 v[224:227], v[246:247], off offset:1664
	global_load_dwordx4 v[228:231], v[248:249], off offset:1664
	global_load_dwordx4 v[232:235], v[250:251], off offset:1664
	s_waitcnt vmcnt(32)
	v_mov_b32_e32 v236, v68
	v_mov_b32_e32 v237, v69
	v_mov_b32_e32 v238, v70
	v_mov_b32_e32 v239, v71
	v_mov_b32_e32 v240, v76
	v_mov_b32_e32 v241, v77
	v_mov_b32_e32 v242, v78
	v_mov_b32_e32 v243, v79
	v_mov_b32_dpp v236, v72 row_shr:8 row_mask:0xf bank_mask:0xc
	v_mov_b32_dpp v237, v73 row_shr:8 row_mask:0xf bank_mask:0xc
	v_mov_b32_dpp v238, v74 row_shr:8 row_mask:0xf bank_mask:0xc
	v_mov_b32_dpp v239, v75 row_shr:8 row_mask:0xf bank_mask:0xc
	v_mov_b32_dpp v240, v80 row_shr:8 row_mask:0xf bank_mask:0xc
	v_mov_b32_dpp v241, v81 row_shr:8 row_mask:0xf bank_mask:0xc
	v_mov_b32_dpp v242, v82 row_shr:8 row_mask:0xf bank_mask:0xc
	v_mov_b32_dpp v243, v83 row_shr:8 row_mask:0xf bank_mask:0xc
	v_mov_b32_dpp v72, v68 row_shl:8 row_mask:0xf bank_mask:0x3
	v_mov_b32_dpp v73, v69 row_shl:8 row_mask:0xf bank_mask:0x3
	v_mov_b32_dpp v74, v70 row_shl:8 row_mask:0xf bank_mask:0x3
	v_mov_b32_dpp v75, v71 row_shl:8 row_mask:0xf bank_mask:0x3
	v_mov_b32_dpp v80, v76 row_shl:8 row_mask:0xf bank_mask:0x3
	v_mov_b32_dpp v81, v77 row_shl:8 row_mask:0xf bank_mask:0x3
	v_mov_b32_dpp v82, v78 row_shl:8 row_mask:0xf bank_mask:0x3
	v_mov_b32_dpp v83, v79 row_shl:8 row_mask:0xf bank_mask:0x3
	v_mfma_f32_16x16x32_bf16 v[4:7], v[236:239], v[240:243], v[4:7]
	s_nop 0
	v_mfma_f32_16x16x32_bf16 v[0:3], v[72:75], v[80:83], v[0:3]
	global_load_dwordx4 v[68:71], v[244:245], off offset:1792
	global_load_dwordx4 v[72:75], v[246:247], off offset:1792
	global_load_dwordx4 v[76:79], v[248:249], off offset:1792
	global_load_dwordx4 v[80:83], v[250:251], off offset:1792
	s_waitcnt vmcnt(32)
	v_mov_b32_e32 v236, v84
	v_mov_b32_e32 v237, v85
	v_mov_b32_e32 v238, v86
	v_mov_b32_e32 v239, v87
	v_mov_b32_e32 v240, v92
	v_mov_b32_e32 v241, v93
	v_mov_b32_e32 v242, v94
	v_mov_b32_e32 v243, v95
	v_mov_b32_dpp v236, v88 row_shr:8 row_mask:0xf bank_mask:0xc
	v_mov_b32_dpp v237, v89 row_shr:8 row_mask:0xf bank_mask:0xc
	v_mov_b32_dpp v238, v90 row_shr:8 row_mask:0xf bank_mask:0xc
	v_mov_b32_dpp v239, v91 row_shr:8 row_mask:0xf bank_mask:0xc
	v_mov_b32_dpp v240, v96 row_shr:8 row_mask:0xf bank_mask:0xc
	v_mov_b32_dpp v241, v97 row_shr:8 row_mask:0xf bank_mask:0xc
	v_mov_b32_dpp v242, v98 row_shr:8 row_mask:0xf bank_mask:0xc
	v_mov_b32_dpp v243, v99 row_shr:8 row_mask:0xf bank_mask:0xc
	v_mov_b32_dpp v88, v84 row_shl:8 row_mask:0xf bank_mask:0x3
	v_mov_b32_dpp v89, v85 row_shl:8 row_mask:0xf bank_mask:0x3
	v_mov_b32_dpp v90, v86 row_shl:8 row_mask:0xf bank_mask:0x3
	v_mov_b32_dpp v91, v87 row_shl:8 row_mask:0xf bank_mask:0x3
	v_mov_b32_dpp v96, v92 row_shl:8 row_mask:0xf bank_mask:0x3
	v_mov_b32_dpp v97, v93 row_shl:8 row_mask:0xf bank_mask:0x3
	v_mov_b32_dpp v98, v94 row_shl:8 row_mask:0xf bank_mask:0x3
	v_mov_b32_dpp v99, v95 row_shl:8 row_mask:0xf bank_mask:0x3
	v_mfma_f32_16x16x32_bf16 v[4:7], v[236:239], v[240:243], v[4:7]
	s_nop 0
	v_mfma_f32_16x16x32_bf16 v[0:3], v[88:91], v[96:99], v[0:3]
	global_load_dwordx4 v[84:87], v[244:245], off offset:1920
	global_load_dwordx4 v[88:91], v[246:247], off offset:1920
	global_load_dwordx4 v[92:95], v[248:249], off offset:1920
	global_load_dwordx4 v[96:99], v[250:251], off offset:1920
	s_waitcnt vmcnt(32)
	v_mov_b32_e32 v236, v100
	v_mov_b32_e32 v237, v101
	v_mov_b32_e32 v238, v102
	v_mov_b32_e32 v239, v103
	v_mov_b32_e32 v240, v108
	v_mov_b32_e32 v241, v109
	v_mov_b32_e32 v242, v110
	v_mov_b32_e32 v243, v111
	v_mov_b32_dpp v236, v104 row_shr:8 row_mask:0xf bank_mask:0xc
	v_mov_b32_dpp v237, v105 row_shr:8 row_mask:0xf bank_mask:0xc
	v_mov_b32_dpp v238, v106 row_shr:8 row_mask:0xf bank_mask:0xc
	v_mov_b32_dpp v239, v107 row_shr:8 row_mask:0xf bank_mask:0xc
	v_mov_b32_dpp v240, v112 row_shr:8 row_mask:0xf bank_mask:0xc
	v_mov_b32_dpp v241, v113 row_shr:8 row_mask:0xf bank_mask:0xc
	v_mov_b32_dpp v242, v114 row_shr:8 row_mask:0xf bank_mask:0xc
	v_mov_b32_dpp v243, v115 row_shr:8 row_mask:0xf bank_mask:0xc
	v_mov_b32_dpp v104, v100 row_shl:8 row_mask:0xf bank_mask:0x3
	v_mov_b32_dpp v105, v101 row_shl:8 row_mask:0xf bank_mask:0x3
	v_mov_b32_dpp v106, v102 row_shl:8 row_mask:0xf bank_mask:0x3
	v_mov_b32_dpp v107, v103 row_shl:8 row_mask:0xf bank_mask:0x3
	v_mov_b32_dpp v112, v108 row_shl:8 row_mask:0xf bank_mask:0x3
	v_mov_b32_dpp v113, v109 row_shl:8 row_mask:0xf bank_mask:0x3
	v_mov_b32_dpp v114, v110 row_shl:8 row_mask:0xf bank_mask:0x3
	v_mov_b32_dpp v115, v111 row_shl:8 row_mask:0xf bank_mask:0x3
	v_mfma_f32_16x16x32_bf16 v[4:7], v[236:239], v[240:243], v[4:7]
	s_nop 0
	v_mfma_f32_16x16x32_bf16 v[0:3], v[104:107], v[112:115], v[0:3]
	global_load_dwordx4 v[100:103], v[244:245], off offset:2048
	global_load_dwordx4 v[104:107], v[246:247], off offset:2048
	global_load_dwordx4 v[108:111], v[248:249], off offset:2048
	global_load_dwordx4 v[112:115], v[250:251], off offset:2048
	s_waitcnt vmcnt(32)
; __device__ __forceinline__ f32x4 skinny16(const bf16_t* A, int lda, const bf16_t* Bt, int ldb, int K, int lane) {
;     ...
;     for (int k = 0; k < K / 32; k += 16) {
;         bf16x8 a[16], b[16];
; #pragma unroll
;         for (int i = 0; i < 16; ++i) { a[i] = ap[(k + i) * 4]; b[i] = bp[(k + i) * 4]; }
; #pragma unroll
;         for (int i = 0; i < 16; i += 2) { acc0 = __builtin_amdgcn_mfma_f32_16x16x32_bf16(a[i], b[i], acc0, 0, 0, 0); acc1 = __builtin_amdgcn_mfma_f32_16x16x32_bf16(a[i + 1], b[i + 1], acc1, 0, 0, 0); }
	v_mov_b32_e32 v236, v116
	v_mov_b32_e32 v237, v117
	v_mov_b32_e32 v238, v118
	v_mov_b32_e32 v239, v119
	v_mov_b32_e32 v240, v124
	v_mov_b32_e32 v241, v125
	v_mov_b32_e32 v242, v126
	v_mov_b32_e32 v243, v127
	v_mov_b32_dpp v236, v120 row_shr:8 row_mask:0xf bank_mask:0xc
	v_mov_b32_dpp v237, v121 row_shr:8 row_mask:0xf bank_mask:0xc
	v_mov_b32_dpp v238, v122 row_shr:8 row_mask:0xf bank_mask:0xc
	v_mov_b32_dpp v239, v123 row_shr:8 row_mask:0xf bank_mask:0xc
	v_mov_b32_dpp v240, v128 row_shr:8 row_mask:0xf bank_mask:0xc
	v_mov_b32_dpp v241, v129 row_shr:8 row_mask:0xf bank_mask:0xc
	v_mov_b32_dpp v242, v130 row_shr:8 row_mask:0xf bank_mask:0xc
	v_mov_b32_dpp v243, v131 row_shr:8 row_mask:0xf bank_mask:0xc
	v_mov_b32_dpp v120, v116 row_shl:8 row_mask:0xf bank_mask:0x3
	v_mov_b32_dpp v121, v117 row_shl:8 row_mask:0xf bank_mask:0x3
	v_mov_b32_dpp v122, v118 row_shl:8 row_mask:0xf bank_mask:0x3
	v_mov_b32_dpp v123, v119 row_shl:8 row_mask:0xf bank_mask:0x3
	v_mov_b32_dpp v128, v124 row_shl:8 row_mask:0xf bank_mask:0x3
	v_mov_b32_dpp v129, v125 row_shl:8 row_mask:0xf bank_mask:0x3
	v_mov_b32_dpp v130, v126 row_shl:8 row_mask:0xf bank_mask:0x3
	v_mov_b32_dpp v131, v127 row_shl:8 row_mask:0xf bank_mask:0x3
	v_mfma_f32_16x16x32_bf16 v[4:7], v[236:239], v[240:243], v[4:7]
	s_nop 0
	v_mfma_f32_16x16x32_bf16 v[0:3], v[120:123], v[128:131], v[0:3]
	global_load_dwordx4 v[116:119], v[244:245], off offset:2176
	global_load_dwordx4 v[120:123], v[246:247], off offset:2176
	global_load_dwordx4 v[124:127], v[248:249], off offset:2176
	global_load_dwordx4 v[128:131], v[250:251], off offset:2176
	s_waitcnt vmcnt(32)
	v_mov_b32_e32 v236, v132
	v_mov_b32_e32 v237, v133
	v_mov_b32_e32 v238, v134
	v_mov_b32_e32 v239, v135
	v_mov_b32_e32 v240, v140
	v_mov_b32_e32 v241, v141
	v_mov_b32_e32 v242, v142
	v_mov_b32_e32 v243, v143
	v_mov_b32_dpp v236, v136 row_shr:8 row_mask:0xf bank_mask:0xc
	v_mov_b32_dpp v237, v137 row_shr:8 row_mask:0xf bank_mask:0xc
	v_mov_b32_dpp v238, v138 row_shr:8 row_mask:0xf bank_mask:0xc
	v_mov_b32_dpp v239, v139 row_shr:8 row_mask:0xf bank_mask:0xc
	v_mov_b32_dpp v240, v144 row_shr:8 row_mask:0xf bank_mask:0xc
	v_mov_b32_dpp v241, v145 row_shr:8 row_mask:0xf bank_mask:0xc
	v_mov_b32_dpp v242, v146 row_shr:8 row_mask:0xf bank_mask:0xc
	v_mov_b32_dpp v243, v147 row_shr:8 row_mask:0xf bank_mask:0xc
	v_mov_b32_dpp v136, v132 row_shl:8 row_mask:0xf bank_mask:0x3
	v_mov_b32_dpp v137, v133 row_shl:8 row_mask:0xf bank_mask:0x3
	v_mov_b32_dpp v138, v134 row_shl:8 row_mask:0xf bank_mask:0x3
	v_mov_b32_dpp v139, v135 row_shl:8 row_mask:0xf bank_mask:0x3
	v_mov_b32_dpp v144, v140 row_shl:8 row_mask:0xf bank_mask:0x3
	v_mov_b32_dpp v145, v141 row_shl:8 row_mask:0xf bank_mask:0x3
	v_mov_b32_dpp v146, v142 row_shl:8 row_mask:0xf bank_mask:0x3
	v_mov_b32_dpp v147, v143 row_shl:8 row_mask:0xf bank_mask:0x3
	v_mfma_f32_16x16x32_bf16 v[4:7], v[236:239], v[240:243], v[4:7]
	s_nop 0
	v_mfma_f32_16x16x32_bf16 v[0:3], v[136:139], v[144:147], v[0:3]
	global_load_dwordx4 v[132:135], v[244:245], off offset:2304
	global_load_dwordx4 v[136:139], v[246:247], off offset:2304
	global_load_dwordx4 v[140:143], v[248:249], off offset:2304
	global_load_dwordx4 v[144:147], v[250:251], off offset:2304
	s_waitcnt vmcnt(32)
	v_mov_b32_e32 v236, v148
	v_mov_b32_e32 v237, v149
	v_mov_b32_e32 v238, v150
	v_mov_b32_e32 v239, v151
	v_mov_b32_e32 v240, v168
	v_mov_b32_e32 v241, v169
	v_mov_b32_e32 v242, v170
	v_mov_b32_e32 v243, v171
	v_mov_b32_dpp v236, v164 row_shr:8 row_mask:0xf bank_mask:0xc
	v_mov_b32_dpp v237, v165 row_shr:8 row_mask:0xf bank_mask:0xc
	v_mov_b32_dpp v238, v166 row_shr:8 row_mask:0xf bank_mask:0xc
	v_mov_b32_dpp v239, v167 row_shr:8 row_mask:0xf bank_mask:0xc
	v_mov_b32_dpp v240, v172 row_shr:8 row_mask:0xf bank_mask:0xc
	v_mov_b32_dpp v241, v173 row_shr:8 row_mask:0xf bank_mask:0xc
	v_mov_b32_dpp v242, v174 row_shr:8 row_mask:0xf bank_mask:0xc
	v_mov_b32_dpp v243, v175 row_shr:8 row_mask:0xf bank_mask:0xc
	v_mov_b32_dpp v164, v148 row_shl:8 row_mask:0xf bank_mask:0x3
	v_mov_b32_dpp v165, v149 row_shl:8 row_mask:0xf bank_mask:0x3
	v_mov_b32_dpp v166, v150 row_shl:8 row_mask:0xf bank_mask:0x3
	v_mov_b32_dpp v167, v151 row_shl:8 row_mask:0xf bank_mask:0x3
	v_mov_b32_dpp v172, v168 row_shl:8 row_mask:0xf bank_mask:0x3
	v_mov_b32_dpp v173, v169 row_shl:8 row_mask:0xf bank_mask:0x3
	v_mov_b32_dpp v174, v170 row_shl:8 row_mask:0xf bank_mask:0x3
	v_mov_b32_dpp v175, v171 row_shl:8 row_mask:0xf bank_mask:0x3
	v_mfma_f32_16x16x32_bf16 v[4:7], v[236:239], v[240:243], v[4:7]
	s_nop 0
	v_mfma_f32_16x16x32_bf16 v[0:3], v[164:167], v[172:175], v[0:3]
	global_load_dwordx4 v[148:151], v[244:245], off offset:2432
	global_load_dwordx4 v[164:167], v[246:247], off offset:2432
	global_load_dwordx4 v[168:171], v[248:249], off offset:2432
	global_load_dwordx4 v[172:175], v[250:251], off offset:2432
	s_waitcnt vmcnt(32)
; __device__ __forceinline__ f32x4 skinny16(const bf16_t* A, int lda, const bf16_t* Bt, int ldb, int K, int lane) {
;     ...
;     for (int k = 0; k < K / 32; k += 16) {
;         bf16x8 a[16], b[16];
; #pragma unroll
;         for (int i = 0; i < 16; ++i) { a[i] = ap[(k + i) * 4]; b[i] = bp[(k + i) * 4]; }
; #pragma unroll
;         for (int i = 0; i < 16; i += 2) { acc0 = __builtin_amdgcn_mfma_f32_16x16x32_bf16(a[i], b[i], acc0, 0, 0, 0); acc1 = __builtin_amdgcn_mfma_f32_16x16x32_bf16(a[i + 1], b[i + 1], acc1, 0, 0, 0); }
	v_mov_b32_e32 v236, v176
	v_mov_b32_e32 v237, v177
	v_mov_b32_e32 v238, v178
	v_mov_b32_e32 v239, v179
	v_mov_b32_e32 v240, v184
	v_mov_b32_e32 v241, v185
	v_mov_b32_e32 v242, v186
	v_mov_b32_e32 v243, v187
	v_mov_b32_dpp v236, v180 row_shr:8 row_mask:0xf bank_mask:0xc
	v_mov_b32_dpp v237, v181 row_shr:8 row_mask:0xf bank_mask:0xc
	v_mov_b32_dpp v238, v182 row_shr:8 row_mask:0xf bank_mask:0xc
	v_mov_b32_dpp v239, v183 row_shr:8 row_mask:0xf bank_mask:0xc
	v_mov_b32_dpp v240, v188 row_shr:8 row_mask:0xf bank_mask:0xc
	v_mov_b32_dpp v241, v189 row_shr:8 row_mask:0xf bank_mask:0xc
	v_mov_b32_dpp v242, v190 row_shr:8 row_mask:0xf bank_mask:0xc
	v_mov_b32_dpp v243, v191 row_shr:8 row_mask:0xf bank_mask:0xc
	v_mov_b32_dpp v180, v176 row_shl:8 row_mask:0xf bank_mask:0x3
	v_mov_b32_dpp v181, v177 row_shl:8 row_mask:0xf bank_mask:0x3
	v_mov_b32_dpp v182, v178 row_shl:8 row_mask:0xf bank_mask:0x3
	v_mov_b32_dpp v183, v179 row_shl:8 row_mask:0xf bank_mask:0x3
	v_mov_b32_dpp v188, v184 row_shl:8 row_mask:0xf bank_mask:0x3
	v_mov_b32_dpp v189, v185 row_shl:8 row_mask:0xf bank_mask:0x3
	v_mov_b32_dpp v190, v186 row_shl:8 row_mask:0xf bank_mask:0x3
	v_mov_b32_dpp v191, v187 row_shl:8 row_mask:0xf bank_mask:0x3
	v_mfma_f32_16x16x32_bf16 v[4:7], v[236:239], v[240:243], v[4:7]
	s_nop 0
	v_mfma_f32_16x16x32_bf16 v[0:3], v[180:183], v[188:191], v[0:3]
	global_load_dwordx4 v[176:179], v[244:245], off offset:2560
	global_load_dwordx4 v[180:183], v[246:247], off offset:2560
	global_load_dwordx4 v[184:187], v[248:249], off offset:2560
	global_load_dwordx4 v[188:191], v[250:251], off offset:2560
	s_waitcnt vmcnt(32)
	v_mov_b32_e32 v236, v204
	v_mov_b32_e32 v237, v205
	v_mov_b32_e32 v238, v206
	v_mov_b32_e32 v239, v207
	v_mov_b32_e32 v240, v212
	v_mov_b32_e32 v241, v213
	v_mov_b32_e32 v242, v214
	v_mov_b32_e32 v243, v215
	v_mov_b32_dpp v236, v208 row_shr:8 row_mask:0xf bank_mask:0xc
	v_mov_b32_dpp v237, v209 row_shr:8 row_mask:0xf bank_mask:0xc
	v_mov_b32_dpp v238, v210 row_shr:8 row_mask:0xf bank_mask:0xc
	v_mov_b32_dpp v239, v211 row_shr:8 row_mask:0xf bank_mask:0xc
	v_mov_b32_dpp v240, v216 row_shr:8 row_mask:0xf bank_mask:0xc
	v_mov_b32_dpp v241, v217 row_shr:8 row_mask:0xf bank_mask:0xc
	v_mov_b32_dpp v242, v218 row_shr:8 row_mask:0xf bank_mask:0xc
	v_mov_b32_dpp v243, v219 row_shr:8 row_mask:0xf bank_mask:0xc
	v_mov_b32_dpp v208, v204 row_shl:8 row_mask:0xf bank_mask:0x3
	v_mov_b32_dpp v209, v205 row_shl:8 row_mask:0xf bank_mask:0x3
	v_mov_b32_dpp v210, v206 row_shl:8 row_mask:0xf bank_mask:0x3
	v_mov_b32_dpp v211, v207 row_shl:8 row_mask:0xf bank_mask:0x3
	v_mov_b32_dpp v216, v212 row_shl:8 row_mask:0xf bank_mask:0x3
	v_mov_b32_dpp v217, v213 row_shl:8 row_mask:0xf bank_mask:0x3
	v_mov_b32_dpp v218, v214 row_shl:8 row_mask:0xf bank_mask:0x3
	v_mov_b32_dpp v219, v215 row_shl:8 row_mask:0xf bank_mask:0x3
	v_mfma_f32_16x16x32_bf16 v[4:7], v[236:239], v[240:243], v[4:7]
	s_nop 0
	v_mfma_f32_16x16x32_bf16 v[0:3], v[208:211], v[216:219], v[0:3]
	global_load_dwordx4 v[204:207], v[244:245], off offset:2688
	global_load_dwordx4 v[208:211], v[246:247], off offset:2688
	global_load_dwordx4 v[212:215], v[248:249], off offset:2688
	global_load_dwordx4 v[216:219], v[250:251], off offset:2688
	s_waitcnt vmcnt(32)
	v_mov_b32_e32 v236, v220
	v_mov_b32_e32 v237, v221
	v_mov_b32_e32 v238, v222
	v_mov_b32_e32 v239, v223
	v_mov_b32_e32 v240, v228
	v_mov_b32_e32 v241, v229
	v_mov_b32_e32 v242, v230
	v_mov_b32_e32 v243, v231
	v_mov_b32_dpp v236, v224 row_shr:8 row_mask:0xf bank_mask:0xc
	v_mov_b32_dpp v237, v225 row_shr:8 row_mask:0xf bank_mask:0xc
	v_mov_b32_dpp v238, v226 row_shr:8 row_mask:0xf bank_mask:0xc
	v_mov_b32_dpp v239, v227 row_shr:8 row_mask:0xf bank_mask:0xc
	v_mov_b32_dpp v240, v232 row_shr:8 row_mask:0xf bank_mask:0xc
	v_mov_b32_dpp v241, v233 row_shr:8 row_mask:0xf bank_mask:0xc
	v_mov_b32_dpp v242, v234 row_shr:8 row_mask:0xf bank_mask:0xc
	v_mov_b32_dpp v243, v235 row_shr:8 row_mask:0xf bank_mask:0xc
	v_mov_b32_dpp v224, v220 row_shl:8 row_mask:0xf bank_mask:0x3
	v_mov_b32_dpp v225, v221 row_shl:8 row_mask:0xf bank_mask:0x3
	v_mov_b32_dpp v226, v222 row_shl:8 row_mask:0xf bank_mask:0x3
	v_mov_b32_dpp v227, v223 row_shl:8 row_mask:0xf bank_mask:0x3
	v_mov_b32_dpp v232, v228 row_shl:8 row_mask:0xf bank_mask:0x3
	v_mov_b32_dpp v233, v229 row_shl:8 row_mask:0xf bank_mask:0x3
	v_mov_b32_dpp v234, v230 row_shl:8 row_mask:0xf bank_mask:0x3
	v_mov_b32_dpp v235, v231 row_shl:8 row_mask:0xf bank_mask:0x3
	v_mfma_f32_16x16x32_bf16 v[4:7], v[236:239], v[240:243], v[4:7]
	s_nop 0
	v_mfma_f32_16x16x32_bf16 v[0:3], v[224:227], v[232:235], v[0:3]
	global_load_dwordx4 v[220:223], v[244:245], off offset:2816
	global_load_dwordx4 v[224:227], v[246:247], off offset:2816
	global_load_dwordx4 v[228:231], v[248:249], off offset:2816
	global_load_dwordx4 v[232:235], v[250:251], off offset:2816
	s_waitcnt vmcnt(32)
; __device__ __forceinline__ f32x4 skinny16(const bf16_t* A, int lda, const bf16_t* Bt, int ldb, int K, int lane) {
;     ...
;     for (int k = 0; k < K / 32; k += 16) {
;         bf16x8 a[16], b[16];
; #pragma unroll
;         for (int i = 0; i < 16; ++i) { a[i] = ap[(k + i) * 4]; b[i] = bp[(k + i) * 4]; }
; #pragma unroll
;         for (int i = 0; i < 16; i += 2) { acc0 = __builtin_amdgcn_mfma_f32_16x16x32_bf16(a[i], b[i], acc0, 0, 0, 0); acc1 = __builtin_amdgcn_mfma_f32_16x16x32_bf16(a[i + 1], b[i + 1], acc1, 0, 0, 0); }
	v_mov_b32_e32 v236, v68
	v_mov_b32_e32 v237, v69
	v_mov_b32_e32 v238, v70
	v_mov_b32_e32 v239, v71
	v_mov_b32_e32 v240, v76
	v_mov_b32_e32 v241, v77
	v_mov_b32_e32 v242, v78
	v_mov_b32_e32 v243, v79
	v_mov_b32_dpp v236, v72 row_shr:8 row_mask:0xf bank_mask:0xc
	v_mov_b32_dpp v237, v73 row_shr:8 row_mask:0xf bank_mask:0xc
	v_mov_b32_dpp v238, v74 row_shr:8 row_mask:0xf bank_mask:0xc
	v_mov_b32_dpp v239, v75 row_shr:8 row_mask:0xf bank_mask:0xc
	v_mov_b32_dpp v240, v80 row_shr:8 row_mask:0xf bank_mask:0xc
	v_mov_b32_dpp v241, v81 row_shr:8 row_mask:0xf bank_mask:0xc
	v_mov_b32_dpp v242, v82 row_shr:8 row_mask:0xf bank_mask:0xc
	v_mov_b32_dpp v243, v83 row_shr:8 row_mask:0xf bank_mask:0xc
	v_mov_b32_dpp v72, v68 row_shl:8 row_mask:0xf bank_mask:0x3
	v_mov_b32_dpp v73, v69 row_shl:8 row_mask:0xf bank_mask:0x3
	v_mov_b32_dpp v74, v70 row_shl:8 row_mask:0xf bank_mask:0x3
	v_mov_b32_dpp v75, v71 row_shl:8 row_mask:0xf bank_mask:0x3
	v_mov_b32_dpp v80, v76 row_shl:8 row_mask:0xf bank_mask:0x3
	v_mov_b32_dpp v81, v77 row_shl:8 row_mask:0xf bank_mask:0x3
	v_mov_b32_dpp v82, v78 row_shl:8 row_mask:0xf bank_mask:0x3
	v_mov_b32_dpp v83, v79 row_shl:8 row_mask:0xf bank_mask:0x3
	v_mfma_f32_16x16x32_bf16 v[4:7], v[236:239], v[240:243], v[4:7]
	s_nop 0
	v_mfma_f32_16x16x32_bf16 v[0:3], v[72:75], v[80:83], v[0:3]
	global_load_dwordx4 v[68:71], v[244:245], off offset:2944
	global_load_dwordx4 v[72:75], v[246:247], off offset:2944
	global_load_dwordx4 v[76:79], v[248:249], off offset:2944
	global_load_dwordx4 v[80:83], v[250:251], off offset:2944
	s_waitcnt vmcnt(32)
	v_mov_b32_e32 v236, v84
	v_mov_b32_e32 v237, v85
	v_mov_b32_e32 v238, v86
	v_mov_b32_e32 v239, v87
	v_mov_b32_e32 v240, v92
	v_mov_b32_e32 v241, v93
	v_mov_b32_e32 v242, v94
	v_mov_b32_e32 v243, v95
	v_mov_b32_dpp v236, v88 row_shr:8 row_mask:0xf bank_mask:0xc
	v_mov_b32_dpp v237, v89 row_shr:8 row_mask:0xf bank_mask:0xc
	v_mov_b32_dpp v238, v90 row_shr:8 row_mask:0xf bank_mask:0xc
	v_mov_b32_dpp v239, v91 row_shr:8 row_mask:0xf bank_mask:0xc
	v_mov_b32_dpp v240, v96 row_shr:8 row_mask:0xf bank_mask:0xc
	v_mov_b32_dpp v241, v97 row_shr:8 row_mask:0xf bank_mask:0xc
	v_mov_b32_dpp v242, v98 row_shr:8 row_mask:0xf bank_mask:0xc
	v_mov_b32_dpp v243, v99 row_shr:8 row_mask:0xf bank_mask:0xc
	v_mov_b32_dpp v88, v84 row_shl:8 row_mask:0xf bank_mask:0x3
	v_mov_b32_dpp v89, v85 row_shl:8 row_mask:0xf bank_mask:0x3
	v_mov_b32_dpp v90, v86 row_shl:8 row_mask:0xf bank_mask:0x3
	v_mov_b32_dpp v91, v87 row_shl:8 row_mask:0xf bank_mask:0x3
	v_mov_b32_dpp v96, v92 row_shl:8 row_mask:0xf bank_mask:0x3
	v_mov_b32_dpp v97, v93 row_shl:8 row_mask:0xf bank_mask:0x3
	v_mov_b32_dpp v98, v94 row_shl:8 row_mask:0xf bank_mask:0x3
	v_mov_b32_dpp v99, v95 row_shl:8 row_mask:0xf bank_mask:0x3
	v_mfma_f32_16x16x32_bf16 v[4:7], v[236:239], v[240:243], v[4:7]
	s_nop 0
	v_mfma_f32_16x16x32_bf16 v[0:3], v[88:91], v[96:99], v[0:3]
	global_load_dwordx4 v[84:87], v[244:245], off offset:3072
	global_load_dwordx4 v[88:91], v[246:247], off offset:3072
	global_load_dwordx4 v[92:95], v[248:249], off offset:3072
	global_load_dwordx4 v[96:99], v[250:251], off offset:3072
	s_waitcnt vmcnt(32)
	v_mov_b32_e32 v236, v100
	v_mov_b32_e32 v237, v101
	v_mov_b32_e32 v238, v102
	v_mov_b32_e32 v239, v103
	v_mov_b32_e32 v240, v108
	v_mov_b32_e32 v241, v109
	v_mov_b32_e32 v242, v110
	v_mov_b32_e32 v243, v111
	v_mov_b32_dpp v236, v104 row_shr:8 row_mask:0xf bank_mask:0xc
	v_mov_b32_dpp v237, v105 row_shr:8 row_mask:0xf bank_mask:0xc
	v_mov_b32_dpp v238, v106 row_shr:8 row_mask:0xf bank_mask:0xc
	v_mov_b32_dpp v239, v107 row_shr:8 row_mask:0xf bank_mask:0xc
	v_mov_b32_dpp v240, v112 row_shr:8 row_mask:0xf bank_mask:0xc
	v_mov_b32_dpp v241, v113 row_shr:8 row_mask:0xf bank_mask:0xc
	v_mov_b32_dpp v242, v114 row_shr:8 row_mask:0xf bank_mask:0xc
	v_mov_b32_dpp v243, v115 row_shr:8 row_mask:0xf bank_mask:0xc
	v_mov_b32_dpp v104, v100 row_shl:8 row_mask:0xf bank_mask:0x3
	v_mov_b32_dpp v105, v101 row_shl:8 row_mask:0xf bank_mask:0x3
	v_mov_b32_dpp v106, v102 row_shl:8 row_mask:0xf bank_mask:0x3
	v_mov_b32_dpp v107, v103 row_shl:8 row_mask:0xf bank_mask:0x3
	v_mov_b32_dpp v112, v108 row_shl:8 row_mask:0xf bank_mask:0x3
	v_mov_b32_dpp v113, v109 row_shl:8 row_mask:0xf bank_mask:0x3
	v_mov_b32_dpp v114, v110 row_shl:8 row_mask:0xf bank_mask:0x3
	v_mov_b32_dpp v115, v111 row_shl:8 row_mask:0xf bank_mask:0x3
	v_mfma_f32_16x16x32_bf16 v[4:7], v[236:239], v[240:243], v[4:7]
	s_nop 0
	v_mfma_f32_16x16x32_bf16 v[0:3], v[104:107], v[112:115], v[0:3]
	global_load_dwordx4 v[100:103], v[244:245], off offset:3200
	global_load_dwordx4 v[104:107], v[246:247], off offset:3200
	global_load_dwordx4 v[108:111], v[248:249], off offset:3200
	global_load_dwordx4 v[112:115], v[250:251], off offset:3200
	s_waitcnt vmcnt(32)
	v_mov_b32_e32 v236, v116
	v_mov_b32_e32 v237, v117
	v_mov_b32_e32 v238, v118
	v_mov_b32_e32 v239, v119
	v_mov_b32_e32 v240, v124
	v_mov_b32_e32 v241, v125
	v_mov_b32_e32 v242, v126
	v_mov_b32_e32 v243, v127
	v_mov_b32_dpp v236, v120 row_shr:8 row_mask:0xf bank_mask:0xc
	v_mov_b32_dpp v237, v121 row_shr:8 row_mask:0xf bank_mask:0xc
	v_mov_b32_dpp v238, v122 row_shr:8 row_mask:0xf bank_mask:0xc
	v_mov_b32_dpp v239, v123 row_shr:8 row_mask:0xf bank_mask:0xc
	v_mov_b32_dpp v240, v128 row_shr:8 row_mask:0xf bank_mask:0xc
	v_mov_b32_dpp v241, v129 row_shr:8 row_mask:0xf bank_mask:0xc
	v_mov_b32_dpp v242, v130 row_shr:8 row_mask:0xf bank_mask:0xc
	v_mov_b32_dpp v243, v131 row_shr:8 row_mask:0xf bank_mask:0xc
	v_mov_b32_dpp v120, v116 row_shl:8 row_mask:0xf bank_mask:0x3
	v_mov_b32_dpp v121, v117 row_shl:8 row_mask:0xf bank_mask:0x3
	v_mov_b32_dpp v122, v118 row_shl:8 row_mask:0xf bank_mask:0x3
	v_mov_b32_dpp v123, v119 row_shl:8 row_mask:0xf bank_mask:0x3
	v_mov_b32_dpp v128, v124 row_shl:8 row_mask:0xf bank_mask:0x3
	v_mov_b32_dpp v129, v125 row_shl:8 row_mask:0xf bank_mask:0x3
	v_mov_b32_dpp v130, v126 row_shl:8 row_mask:0xf bank_mask:0x3
	v_mov_b32_dpp v131, v127 row_shl:8 row_mask:0xf bank_mask:0x3
	v_mfma_f32_16x16x32_bf16 v[4:7], v[236:239], v[240:243], v[4:7]
	s_nop 0
	v_mfma_f32_16x16x32_bf16 v[0:3], v[120:123], v[128:131], v[0:3]
	global_load_dwordx4 v[116:119], v[244:245], off offset:3328
	global_load_dwordx4 v[120:123], v[246:247], off offset:3328
	global_load_dwordx4 v[124:127], v[248:249], off offset:3328
	global_load_dwordx4 v[128:131], v[250:251], off offset:3328
	s_waitcnt vmcnt(32)
; __device__ __forceinline__ f32x4 skinny16(const bf16_t* A, int lda, const bf16_t* Bt, int ldb, int K, int lane) {
;     ...
;     for (int k = 0; k < K / 32; k += 16) {
;         bf16x8 a[16], b[16];
; #pragma unroll
;         for (int i = 0; i < 16; ++i) { a[i] = ap[(k + i) * 4]; b[i] = bp[(k + i) * 4]; }
; #pragma unroll
;         for (int i = 0; i < 16; i += 2) { acc0 = __builtin_amdgcn_mfma_f32_16x16x32_bf16(a[i], b[i], acc0, 0, 0, 0); acc1 = __builtin_amdgcn_mfma_f32_16x16x32_bf16(a[i + 1], b[i + 1], acc1, 0, 0, 0); }
	v_mov_b32_e32 v236, v132
	v_mov_b32_e32 v237, v133
	v_mov_b32_e32 v238, v134
	v_mov_b32_e32 v239, v135
	v_mov_b32_e32 v240, v140
	v_mov_b32_e32 v241, v141
	v_mov_b32_e32 v242, v142
	v_mov_b32_e32 v243, v143
	v_mov_b32_dpp v236, v136 row_shr:8 row_mask:0xf bank_mask:0xc
	v_mov_b32_dpp v237, v137 row_shr:8 row_mask:0xf bank_mask:0xc
	v_mov_b32_dpp v238, v138 row_shr:8 row_mask:0xf bank_mask:0xc
	v_mov_b32_dpp v239, v139 row_shr:8 row_mask:0xf bank_mask:0xc
	v_mov_b32_dpp v240, v144 row_shr:8 row_mask:0xf bank_mask:0xc
	v_mov_b32_dpp v241, v145 row_shr:8 row_mask:0xf bank_mask:0xc
	v_mov_b32_dpp v242, v146 row_shr:8 row_mask:0xf bank_mask:0xc
	v_mov_b32_dpp v243, v147 row_shr:8 row_mask:0xf bank_mask:0xc
	v_mov_b32_dpp v136, v132 row_shl:8 row_mask:0xf bank_mask:0x3
	v_mov_b32_dpp v137, v133 row_shl:8 row_mask:0xf bank_mask:0x3
	v_mov_b32_dpp v138, v134 row_shl:8 row_mask:0xf bank_mask:0x3
	v_mov_b32_dpp v139, v135 row_shl:8 row_mask:0xf bank_mask:0x3
	v_mov_b32_dpp v144, v140 row_shl:8 row_mask:0xf bank_mask:0x3
	v_mov_b32_dpp v145, v141 row_shl:8 row_mask:0xf bank_mask:0x3
	v_mov_b32_dpp v146, v142 row_shl:8 row_mask:0xf bank_mask:0x3
	v_mov_b32_dpp v147, v143 row_shl:8 row_mask:0xf bank_mask:0x3
	v_mfma_f32_16x16x32_bf16 v[4:7], v[236:239], v[240:243], v[4:7]
	s_nop 0
	v_mfma_f32_16x16x32_bf16 v[0:3], v[136:139], v[144:147], v[0:3]
	global_load_dwordx4 v[132:135], v[244:245], off offset:3456
	global_load_dwordx4 v[136:139], v[246:247], off offset:3456
	global_load_dwordx4 v[140:143], v[248:249], off offset:3456
	global_load_dwordx4 v[144:147], v[250:251], off offset:3456
	s_waitcnt vmcnt(32)
	v_mov_b32_e32 v236, v148
	v_mov_b32_e32 v237, v149
	v_mov_b32_e32 v238, v150
	v_mov_b32_e32 v239, v151
	v_mov_b32_e32 v240, v168
	v_mov_b32_e32 v241, v169
	v_mov_b32_e32 v242, v170
	v_mov_b32_e32 v243, v171
	v_mov_b32_dpp v236, v164 row_shr:8 row_mask:0xf bank_mask:0xc
	v_mov_b32_dpp v237, v165 row_shr:8 row_mask:0xf bank_mask:0xc
	v_mov_b32_dpp v238, v166 row_shr:8 row_mask:0xf bank_mask:0xc
	v_mov_b32_dpp v239, v167 row_shr:8 row_mask:0xf bank_mask:0xc
	v_mov_b32_dpp v240, v172 row_shr:8 row_mask:0xf bank_mask:0xc
	v_mov_b32_dpp v241, v173 row_shr:8 row_mask:0xf bank_mask:0xc
	v_mov_b32_dpp v242, v174 row_shr:8 row_mask:0xf bank_mask:0xc
	v_mov_b32_dpp v243, v175 row_shr:8 row_mask:0xf bank_mask:0xc
	v_mov_b32_dpp v164, v148 row_shl:8 row_mask:0xf bank_mask:0x3
	v_mov_b32_dpp v165, v149 row_shl:8 row_mask:0xf bank_mask:0x3
	v_mov_b32_dpp v166, v150 row_shl:8 row_mask:0xf bank_mask:0x3
	v_mov_b32_dpp v167, v151 row_shl:8 row_mask:0xf bank_mask:0x3
	v_mov_b32_dpp v172, v168 row_shl:8 row_mask:0xf bank_mask:0x3
	v_mov_b32_dpp v173, v169 row_shl:8 row_mask:0xf bank_mask:0x3
	v_mov_b32_dpp v174, v170 row_shl:8 row_mask:0xf bank_mask:0x3
	v_mov_b32_dpp v175, v171 row_shl:8 row_mask:0xf bank_mask:0x3
	v_mfma_f32_16x16x32_bf16 v[4:7], v[236:239], v[240:243], v[4:7]
	s_nop 0
	v_mfma_f32_16x16x32_bf16 v[0:3], v[164:167], v[172:175], v[0:3]
	s_waitcnt vmcnt(28)
	v_mov_b32_e32 v236, v176
	v_mov_b32_e32 v237, v177
	v_mov_b32_e32 v238, v178
	v_mov_b32_e32 v239, v179
	v_mov_b32_e32 v240, v184
	v_mov_b32_e32 v241, v185
	v_mov_b32_e32 v242, v186
	v_mov_b32_e32 v243, v187
	v_mov_b32_dpp v236, v180 row_shr:8 row_mask:0xf bank_mask:0xc
	v_mov_b32_dpp v237, v181 row_shr:8 row_mask:0xf bank_mask:0xc
	v_mov_b32_dpp v238, v182 row_shr:8 row_mask:0xf bank_mask:0xc
	v_mov_b32_dpp v239, v183 row_shr:8 row_mask:0xf bank_mask:0xc
	v_mov_b32_dpp v240, v188 row_shr:8 row_mask:0xf bank_mask:0xc
	v_mov_b32_dpp v241, v189 row_shr:8 row_mask:0xf bank_mask:0xc
	v_mov_b32_dpp v242, v190 row_shr:8 row_mask:0xf bank_mask:0xc
	v_mov_b32_dpp v243, v191 row_shr:8 row_mask:0xf bank_mask:0xc
	v_mov_b32_dpp v180, v176 row_shl:8 row_mask:0xf bank_mask:0x3
	v_mov_b32_dpp v181, v177 row_shl:8 row_mask:0xf bank_mask:0x3
	v_mov_b32_dpp v182, v178 row_shl:8 row_mask:0xf bank_mask:0x3
	v_mov_b32_dpp v183, v179 row_shl:8 row_mask:0xf bank_mask:0x3
	v_mov_b32_dpp v188, v184 row_shl:8 row_mask:0xf bank_mask:0x3
	v_mov_b32_dpp v189, v185 row_shl:8 row_mask:0xf bank_mask:0x3
	v_mov_b32_dpp v190, v186 row_shl:8 row_mask:0xf bank_mask:0x3
	v_mov_b32_dpp v191, v187 row_shl:8 row_mask:0xf bank_mask:0x3
	v_mfma_f32_16x16x32_bf16 v[4:7], v[236:239], v[240:243], v[4:7]
	s_nop 0
	v_mfma_f32_16x16x32_bf16 v[0:3], v[180:183], v[188:191], v[0:3]
	s_waitcnt vmcnt(24)
	v_mov_b32_e32 v236, v204
	v_mov_b32_e32 v237, v205
	v_mov_b32_e32 v238, v206
	v_mov_b32_e32 v239, v207
	v_mov_b32_e32 v240, v212
	v_mov_b32_e32 v241, v213
	v_mov_b32_e32 v242, v214
	v_mov_b32_e32 v243, v215
	v_mov_b32_dpp v236, v208 row_shr:8 row_mask:0xf bank_mask:0xc
	v_mov_b32_dpp v237, v209 row_shr:8 row_mask:0xf bank_mask:0xc
	v_mov_b32_dpp v238, v210 row_shr:8 row_mask:0xf bank_mask:0xc
	v_mov_b32_dpp v239, v211 row_shr:8 row_mask:0xf bank_mask:0xc
	v_mov_b32_dpp v240, v216 row_shr:8 row_mask:0xf bank_mask:0xc
	v_mov_b32_dpp v241, v217 row_shr:8 row_mask:0xf bank_mask:0xc
	v_mov_b32_dpp v242, v218 row_shr:8 row_mask:0xf bank_mask:0xc
	v_mov_b32_dpp v243, v219 row_shr:8 row_mask:0xf bank_mask:0xc
	v_mov_b32_dpp v208, v204 row_shl:8 row_mask:0xf bank_mask:0x3
	v_mov_b32_dpp v209, v205 row_shl:8 row_mask:0xf bank_mask:0x3
	v_mov_b32_dpp v210, v206 row_shl:8 row_mask:0xf bank_mask:0x3
	v_mov_b32_dpp v211, v207 row_shl:8 row_mask:0xf bank_mask:0x3
	v_mov_b32_dpp v216, v212 row_shl:8 row_mask:0xf bank_mask:0x3
	v_mov_b32_dpp v217, v213 row_shl:8 row_mask:0xf bank_mask:0x3
	v_mov_b32_dpp v218, v214 row_shl:8 row_mask:0xf bank_mask:0x3
	v_mov_b32_dpp v219, v215 row_shl:8 row_mask:0xf bank_mask:0x3
	v_mfma_f32_16x16x32_bf16 v[4:7], v[236:239], v[240:243], v[4:7]
	s_nop 0
	v_mfma_f32_16x16x32_bf16 v[0:3], v[208:211], v[216:219], v[0:3]
	s_waitcnt vmcnt(20)
; __device__ __forceinline__ f32x4 skinny16(const bf16_t* A, int lda, const bf16_t* Bt, int ldb, int K, int lane) {
;     ...
;     for (int k = 0; k < K / 32; k += 16) {
;         bf16x8 a[16], b[16];
; #pragma unroll
;         for (int i = 0; i < 16; ++i) { a[i] = ap[(k + i) * 4]; b[i] = bp[(k + i) * 4]; }
; #pragma unroll
;         for (int i = 0; i < 16; i += 2) { acc0 = __builtin_amdgcn_mfma_f32_16x16x32_bf16(a[i], b[i], acc0, 0, 0, 0); acc1 = __builtin_amdgcn_mfma_f32_16x16x32_bf16(a[i + 1], b[i + 1], acc1, 0, 0, 0); }
	v_mov_b32_e32 v236, v220
	v_mov_b32_e32 v237, v221
	v_mov_b32_e32 v238, v222
	v_mov_b32_e32 v239, v223
	v_mov_b32_e32 v240, v228
	v_mov_b32_e32 v241, v229
	v_mov_b32_e32 v242, v230
	v_mov_b32_e32 v243, v231
	v_mov_b32_dpp v236, v224 row_shr:8 row_mask:0xf bank_mask:0xc
	v_mov_b32_dpp v237, v225 row_shr:8 row_mask:0xf bank_mask:0xc
	v_mov_b32_dpp v238, v226 row_shr:8 row_mask:0xf bank_mask:0xc
	v_mov_b32_dpp v239, v227 row_shr:8 row_mask:0xf bank_mask:0xc
	v_mov_b32_dpp v240, v232 row_shr:8 row_mask:0xf bank_mask:0xc
	v_mov_b32_dpp v241, v233 row_shr:8 row_mask:0xf bank_mask:0xc
	v_mov_b32_dpp v242, v234 row_shr:8 row_mask:0xf bank_mask:0xc
	v_mov_b32_dpp v243, v235 row_shr:8 row_mask:0xf bank_mask:0xc
	v_mov_b32_dpp v224, v220 row_shl:8 row_mask:0xf bank_mask:0x3
	v_mov_b32_dpp v225, v221 row_shl:8 row_mask:0xf bank_mask:0x3
	v_mov_b32_dpp v226, v222 row_shl:8 row_mask:0xf bank_mask:0x3
	v_mov_b32_dpp v227, v223 row_shl:8 row_mask:0xf bank_mask:0x3
	v_mov_b32_dpp v232, v228 row_shl:8 row_mask:0xf bank_mask:0x3
	v_mov_b32_dpp v233, v229 row_shl:8 row_mask:0xf bank_mask:0x3
	v_mov_b32_dpp v234, v230 row_shl:8 row_mask:0xf bank_mask:0x3
	v_mov_b32_dpp v235, v231 row_shl:8 row_mask:0xf bank_mask:0x3
	v_mfma_f32_16x16x32_bf16 v[4:7], v[236:239], v[240:243], v[4:7]
	s_nop 0
	v_mfma_f32_16x16x32_bf16 v[0:3], v[224:227], v[232:235], v[0:3]
	s_waitcnt vmcnt(16)
	v_mov_b32_e32 v236, v68
	v_mov_b32_e32 v237, v69
	v_mov_b32_e32 v238, v70
	v_mov_b32_e32 v239, v71
	v_mov_b32_e32 v240, v76
	v_mov_b32_e32 v241, v77
	v_mov_b32_e32 v242, v78
	v_mov_b32_e32 v243, v79
	v_mov_b32_dpp v236, v72 row_shr:8 row_mask:0xf bank_mask:0xc
	v_mov_b32_dpp v237, v73 row_shr:8 row_mask:0xf bank_mask:0xc
	v_mov_b32_dpp v238, v74 row_shr:8 row_mask:0xf bank_mask:0xc
	v_mov_b32_dpp v239, v75 row_shr:8 row_mask:0xf bank_mask:0xc
	v_mov_b32_dpp v240, v80 row_shr:8 row_mask:0xf bank_mask:0xc
	v_mov_b32_dpp v241, v81 row_shr:8 row_mask:0xf bank_mask:0xc
	v_mov_b32_dpp v242, v82 row_shr:8 row_mask:0xf bank_mask:0xc
	v_mov_b32_dpp v243, v83 row_shr:8 row_mask:0xf bank_mask:0xc
	v_mov_b32_dpp v72, v68 row_shl:8 row_mask:0xf bank_mask:0x3
	v_mov_b32_dpp v73, v69 row_shl:8 row_mask:0xf bank_mask:0x3
	v_mov_b32_dpp v74, v70 row_shl:8 row_mask:0xf bank_mask:0x3
	v_mov_b32_dpp v75, v71 row_shl:8 row_mask:0xf bank_mask:0x3
	v_mov_b32_dpp v80, v76 row_shl:8 row_mask:0xf bank_mask:0x3
	v_mov_b32_dpp v81, v77 row_shl:8 row_mask:0xf bank_mask:0x3
	v_mov_b32_dpp v82, v78 row_shl:8 row_mask:0xf bank_mask:0x3
	v_mov_b32_dpp v83, v79 row_shl:8 row_mask:0xf bank_mask:0x3
	v_mfma_f32_16x16x32_bf16 v[4:7], v[236:239], v[240:243], v[4:7]
	s_nop 0
	v_mfma_f32_16x16x32_bf16 v[0:3], v[72:75], v[80:83], v[0:3]
	s_waitcnt vmcnt(12)
	v_mov_b32_e32 v236, v84
	v_mov_b32_e32 v237, v85
	v_mov_b32_e32 v238, v86
	v_mov_b32_e32 v239, v87
	v_mov_b32_e32 v240, v92
	v_mov_b32_e32 v241, v93
	v_mov_b32_e32 v242, v94
	v_mov_b32_e32 v243, v95
	v_mov_b32_dpp v236, v88 row_shr:8 row_mask:0xf bank_mask:0xc
	v_mov_b32_dpp v237, v89 row_shr:8 row_mask:0xf bank_mask:0xc
	v_mov_b32_dpp v238, v90 row_shr:8 row_mask:0xf bank_mask:0xc
	v_mov_b32_dpp v239, v91 row_shr:8 row_mask:0xf bank_mask:0xc
	v_mov_b32_dpp v240, v96 row_shr:8 row_mask:0xf bank_mask:0xc
	v_mov_b32_dpp v241, v97 row_shr:8 row_mask:0xf bank_mask:0xc
	v_mov_b32_dpp v242, v98 row_shr:8 row_mask:0xf bank_mask:0xc
	v_mov_b32_dpp v243, v99 row_shr:8 row_mask:0xf bank_mask:0xc
	v_mov_b32_dpp v88, v84 row_shl:8 row_mask:0xf bank_mask:0x3
	v_mov_b32_dpp v89, v85 row_shl:8 row_mask:0xf bank_mask:0x3
	v_mov_b32_dpp v90, v86 row_shl:8 row_mask:0xf bank_mask:0x3
	v_mov_b32_dpp v91, v87 row_shl:8 row_mask:0xf bank_mask:0x3
	v_mov_b32_dpp v96, v92 row_shl:8 row_mask:0xf bank_mask:0x3
	v_mov_b32_dpp v97, v93 row_shl:8 row_mask:0xf bank_mask:0x3
	v_mov_b32_dpp v98, v94 row_shl:8 row_mask:0xf bank_mask:0x3
	v_mov_b32_dpp v99, v95 row_shl:8 row_mask:0xf bank_mask:0x3
	v_mfma_f32_16x16x32_bf16 v[4:7], v[236:239], v[240:243], v[4:7]
	s_nop 0
	v_mfma_f32_16x16x32_bf16 v[0:3], v[88:91], v[96:99], v[0:3]
	s_waitcnt vmcnt(8)
; __device__ __forceinline__ f32x4 skinny16(const bf16_t* A, int lda, const bf16_t* Bt, int ldb, int K, int lane) {
;     ...
;     for (int k = 0; k < K / 32; k += 16) {
;         bf16x8 a[16], b[16];
; #pragma unroll
;         for (int i = 0; i < 16; ++i) { a[i] = ap[(k + i) * 4]; b[i] = bp[(k + i) * 4]; }
; #pragma unroll
;         for (int i = 0; i < 16; i += 2) { acc0 = __builtin_amdgcn_mfma_f32_16x16x32_bf16(a[i], b[i], acc0, 0, 0, 0); acc1 = __builtin_amdgcn_mfma_f32_16x16x32_bf16(a[i + 1], b[i + 1], acc1, 0, 0, 0); }
;     }
;     return acc0 + acc1;
; }
; __global__ void __launch_bounds__(512, 2) mega(Args a) {
;     ...
;                 } else { const int pt = task - 8;
;                     const f32x4 acc = skinny16(hb + (size_t)pt * 16 * DM, DM, Wi + (size_t)NZ * DM, DM, DM, lane);
; #pragma unroll
;                     for (int j = 0; j < 4; ++j) ba[(size_t)(pt * 16 + q8 * 4 + j) * 16 + r] = acc[j];
;                 }
	v_mov_b32_e32 v236, v100
	v_mov_b32_e32 v237, v101
	v_mov_b32_e32 v238, v102
	v_mov_b32_e32 v239, v103
	v_mov_b32_e32 v240, v108
	v_mov_b32_e32 v241, v109
	v_mov_b32_e32 v242, v110
	v_mov_b32_e32 v243, v111
	v_mov_b32_dpp v236, v104 row_shr:8 row_mask:0xf bank_mask:0xc
	v_mov_b32_dpp v237, v105 row_shr:8 row_mask:0xf bank_mask:0xc
	v_mov_b32_dpp v238, v106 row_shr:8 row_mask:0xf bank_mask:0xc
	v_mov_b32_dpp v239, v107 row_shr:8 row_mask:0xf bank_mask:0xc
	v_mov_b32_dpp v240, v112 row_shr:8 row_mask:0xf bank_mask:0xc
	v_mov_b32_dpp v241, v113 row_shr:8 row_mask:0xf bank_mask:0xc
	v_mov_b32_dpp v242, v114 row_shr:8 row_mask:0xf bank_mask:0xc
	v_mov_b32_dpp v243, v115 row_shr:8 row_mask:0xf bank_mask:0xc
	v_mov_b32_dpp v104, v100 row_shl:8 row_mask:0xf bank_mask:0x3
	v_mov_b32_dpp v105, v101 row_shl:8 row_mask:0xf bank_mask:0x3
	v_mov_b32_dpp v106, v102 row_shl:8 row_mask:0xf bank_mask:0x3
	v_mov_b32_dpp v107, v103 row_shl:8 row_mask:0xf bank_mask:0x3
	v_mov_b32_dpp v112, v108 row_shl:8 row_mask:0xf bank_mask:0x3
	v_mov_b32_dpp v113, v109 row_shl:8 row_mask:0xf bank_mask:0x3
	v_mov_b32_dpp v114, v110 row_shl:8 row_mask:0xf bank_mask:0x3
	v_mov_b32_dpp v115, v111 row_shl:8 row_mask:0xf bank_mask:0x3
	v_mfma_f32_16x16x32_bf16 v[4:7], v[236:239], v[240:243], v[4:7]
	s_nop 0
	v_mfma_f32_16x16x32_bf16 v[0:3], v[104:107], v[112:115], v[0:3]
	s_waitcnt vmcnt(4)
	v_mov_b32_e32 v236, v116
	v_mov_b32_e32 v237, v117
	v_mov_b32_e32 v238, v118
	v_mov_b32_e32 v239, v119
	v_mov_b32_e32 v240, v124
	v_mov_b32_e32 v241, v125
	v_mov_b32_e32 v242, v126
	v_mov_b32_e32 v243, v127
	v_mov_b32_dpp v236, v120 row_shr:8 row_mask:0xf bank_mask:0xc
	v_mov_b32_dpp v237, v121 row_shr:8 row_mask:0xf bank_mask:0xc
	v_mov_b32_dpp v238, v122 row_shr:8 row_mask:0xf bank_mask:0xc
	v_mov_b32_dpp v239, v123 row_shr:8 row_mask:0xf bank_mask:0xc
	v_mov_b32_dpp v240, v128 row_shr:8 row_mask:0xf bank_mask:0xc
	v_mov_b32_dpp v241, v129 row_shr:8 row_mask:0xf bank_mask:0xc
	v_mov_b32_dpp v242, v130 row_shr:8 row_mask:0xf bank_mask:0xc
	v_mov_b32_dpp v243, v131 row_shr:8 row_mask:0xf bank_mask:0xc
	v_mov_b32_dpp v120, v116 row_shl:8 row_mask:0xf bank_mask:0x3
	v_mov_b32_dpp v121, v117 row_shl:8 row_mask:0xf bank_mask:0x3
	v_mov_b32_dpp v122, v118 row_shl:8 row_mask:0xf bank_mask:0x3
	v_mov_b32_dpp v123, v119 row_shl:8 row_mask:0xf bank_mask:0x3
	v_mov_b32_dpp v128, v124 row_shl:8 row_mask:0xf bank_mask:0x3
	v_mov_b32_dpp v129, v125 row_shl:8 row_mask:0xf bank_mask:0x3
	v_mov_b32_dpp v130, v126 row_shl:8 row_mask:0xf bank_mask:0x3
	v_mov_b32_dpp v131, v127 row_shl:8 row_mask:0xf bank_mask:0x3
	v_mfma_f32_16x16x32_bf16 v[4:7], v[236:239], v[240:243], v[4:7]
	s_nop 0
	v_mfma_f32_16x16x32_bf16 v[0:3], v[120:123], v[128:131], v[0:3]
	s_waitcnt vmcnt(0)
	v_mov_b32_e32 v236, v132
	v_mov_b32_e32 v237, v133
	v_mov_b32_e32 v238, v134
	v_mov_b32_e32 v239, v135
	v_mov_b32_e32 v240, v140
	v_mov_b32_e32 v241, v141
	v_mov_b32_e32 v242, v142
	v_mov_b32_e32 v243, v143
	v_mov_b32_dpp v236, v136 row_shr:8 row_mask:0xf bank_mask:0xc
	v_mov_b32_dpp v237, v137 row_shr:8 row_mask:0xf bank_mask:0xc
	v_mov_b32_dpp v238, v138 row_shr:8 row_mask:0xf bank_mask:0xc
	v_mov_b32_dpp v239, v139 row_shr:8 row_mask:0xf bank_mask:0xc
	v_mov_b32_dpp v240, v144 row_shr:8 row_mask:0xf bank_mask:0xc
	v_mov_b32_dpp v241, v145 row_shr:8 row_mask:0xf bank_mask:0xc
	v_mov_b32_dpp v242, v146 row_shr:8 row_mask:0xf bank_mask:0xc
	v_mov_b32_dpp v243, v147 row_shr:8 row_mask:0xf bank_mask:0xc
	v_mov_b32_dpp v136, v132 row_shl:8 row_mask:0xf bank_mask:0x3
	v_mov_b32_dpp v137, v133 row_shl:8 row_mask:0xf bank_mask:0x3
	v_mov_b32_dpp v138, v134 row_shl:8 row_mask:0xf bank_mask:0x3
	v_mov_b32_dpp v139, v135 row_shl:8 row_mask:0xf bank_mask:0x3
	v_mov_b32_dpp v144, v140 row_shl:8 row_mask:0xf bank_mask:0x3
	v_mov_b32_dpp v145, v141 row_shl:8 row_mask:0xf bank_mask:0x3
	v_mov_b32_dpp v146, v142 row_shl:8 row_mask:0xf bank_mask:0x3
	v_mov_b32_dpp v147, v143 row_shl:8 row_mask:0xf bank_mask:0x3
	v_mfma_f32_16x16x32_bf16 v[4:7], v[236:239], v[240:243], v[4:7]
	s_nop 0
	v_mfma_f32_16x16x32_bf16 v[0:3], v[136:139], v[144:147], v[0:3]
	s_nop 1
	s_lshl_b32 s5, s8, 4
	s_addk_i32 s5, 0xff80
	s_nop 4
	v_pk_add_f32 v[0:1], v[4:5], v[0:1]
	v_or_b32_e32 v4, s5, v20
	v_mov_b32_e32 v5, v153
	v_pk_add_f32 v[2:3], v[6:7], v[2:3]
	v_lshlrev_b64 v[6:7], 6, v[4:5]
	v_lshl_add_u64 v[6:7], v[8:9], 0, v[6:7]
	global_store_dword v[6:7], v0, off
	v_or_b32_e32 v6, 1, v4
	v_mov_b32_e32 v7, v153
	v_lshlrev_b64 v[6:7], 6, v[6:7]
	v_lshl_add_u64 v[6:7], v[8:9], 0, v[6:7]
	global_store_dword v[6:7], v1, off
	v_or_b32_e32 v0, 2, v4
	v_mov_b32_e32 v1, v153
	v_lshlrev_b64 v[0:1], 6, v[0:1]
	v_lshl_add_u64 v[0:1], v[8:9], 0, v[0:1]
	global_store_dword v[0:1], v2, off
	v_or_b32_e32 v0, 3, v4
	v_mov_b32_e32 v1, v153
	v_lshlrev_b64 v[0:1], 6, v[0:1]
	v_lshl_add_u64 v[0:1], v[8:9], 0, v[0:1]
	s_mov_b64 s[6:7], 0
	global_store_dword v[0:1], v3, off

; __device__ __forceinline__ f32x4 skinny16(const bf16_t* A, int lda, const bf16_t* Bt, int ldb, int K, int lane) {
;     const int r = lane & 15, q = lane >> 4;
;     const bf16x8* ap = (const bf16x8*)(A + (size_t)r * lda + q * 8);
;     const bf16x8* bp = (const bf16x8*)(Bt + (size_t)r * ldb + q * 8);
;     f32x4 acc0 = {0.f, 0.f, 0.f, 0.f}, acc1 = {0.f, 0.f, 0.f, 0.f};
; #pragma unroll 1
;     for (int k = 0; k < K / 32; k += 16) {
;         bf16x8 a[16], b[16];
; #pragma unroll
;         for (int i = 0; i < 16; ++i) { a[i] = ap[(k + i) * 4]; b[i] = bp[(k + i) * 4]; }
; #pragma unroll
;         for (int i = 0; i < 16; i += 2) { acc0 = __builtin_amdgcn_mfma_f32_16x16x32_bf16(a[i], b[i], acc0, 0, 0, 0); acc1 = __builtin_amdgcn_mfma_f32_16x16x32_bf16(a[i + 1], b[i + 1], acc1, 0, 0, 0); }
; __global__ void __launch_bounds__(512, 2) mega(Args a) {
;     ...
;                     const f32x4 acc = skinny16(hb + (size_t)(MP + mt * 16) * DM, DM, Wi + (size_t)NZ * DM, DM, DM, lane);
.LBB0_367:
	v_lshl_add_u64 v[18:19], v[16:17], 0, s[6:7]
	v_lshl_add_u64 v[62:63], v[16:17], 0, s[40:41]
	v_bfe_u32 v252, v200, 3, 1
	v_mul_u32_u24_e32 v252, 0x7fc0, v252
	v_sub_u32_e32 v252, 0, v252
	v_ashrrev_i32_e32 v253, 31, v252
	v_lshl_add_u64 v[244:245], v[18:19], 0, v[252:253]
	v_lshl_add_u64 v[248:249], v[62:63], 0, v[252:253]
	v_mov_b32_e32 v252, 0x8000
	v_mov_b32_e32 v253, 0
	v_lshl_add_u64 v[246:247], v[244:245], 0, v[252:253]
	v_lshl_add_u64 v[250:251], v[248:249], 0, v[252:253]
	global_load_dwordx4 v[68:71], v[244:245], off offset:-512
	global_load_dwordx4 v[72:75], v[246:247], off offset:-512
	global_load_dwordx4 v[76:79], v[248:249], off offset:-512
	global_load_dwordx4 v[80:83], v[250:251], off offset:-512
	global_load_dwordx4 v[84:87], v[244:245], off offset:-384
	global_load_dwordx4 v[88:91], v[246:247], off offset:-384
	global_load_dwordx4 v[92:95], v[248:249], off offset:-384
	global_load_dwordx4 v[96:99], v[250:251], off offset:-384
	global_load_dwordx4 v[100:103], v[244:245], off offset:-256
	global_load_dwordx4 v[104:107], v[246:247], off offset:-256
	global_load_dwordx4 v[108:111], v[248:249], off offset:-256
	global_load_dwordx4 v[112:115], v[250:251], off offset:-256
	global_load_dwordx4 v[116:119], v[244:245], off offset:-128
	global_load_dwordx4 v[120:123], v[246:247], off offset:-128
	global_load_dwordx4 v[124:127], v[248:249], off offset:-128
	global_load_dwordx4 v[128:131], v[250:251], off offset:-128
	global_load_dwordx4 v[132:135], v[244:245], off offset:0
	global_load_dwordx4 v[136:139], v[246:247], off offset:0
	global_load_dwordx4 v[140:143], v[248:249], off offset:0
	global_load_dwordx4 v[144:147], v[250:251], off offset:0
	global_load_dwordx4 v[148:151], v[244:245], off offset:128
	global_load_dwordx4 v[164:167], v[246:247], off offset:128
	global_load_dwordx4 v[168:171], v[248:249], off offset:128
	global_load_dwordx4 v[172:175], v[250:251], off offset:128
	global_load_dwordx4 v[176:179], v[244:245], off offset:256
	global_load_dwordx4 v[180:183], v[246:247], off offset:256
	global_load_dwordx4 v[184:187], v[248:249], off offset:256
	global_load_dwordx4 v[188:191], v[250:251], off offset:256
	global_load_dwordx4 v[204:207], v[244:245], off offset:384
	global_load_dwordx4 v[208:211], v[246:247], off offset:384
	global_load_dwordx4 v[212:215], v[248:249], off offset:384
	global_load_dwordx4 v[216:219], v[250:251], off offset:384
	global_load_dwordx4 v[220:223], v[244:245], off offset:512
	global_load_dwordx4 v[224:227], v[246:247], off offset:512
	global_load_dwordx4 v[228:231], v[248:249], off offset:512
	global_load_dwordx4 v[232:235], v[250:251], off offset:512
	s_waitcnt vmcnt(32)
	v_mov_b32_e32 v236, v68
	v_mov_b32_e32 v237, v69
	v_mov_b32_e32 v238, v70
	v_mov_b32_e32 v239, v71
	v_mov_b32_e32 v240, v76
	v_mov_b32_e32 v241, v77
	v_mov_b32_e32 v242, v78
	v_mov_b32_e32 v243, v79
	v_mov_b32_dpp v236, v72 row_shr:8 row_mask:0xf bank_mask:0xc
	v_mov_b32_dpp v237, v73 row_shr:8 row_mask:0xf bank_mask:0xc
	v_mov_b32_dpp v238, v74 row_shr:8 row_mask:0xf bank_mask:0xc
	v_mov_b32_dpp v239, v75 row_shr:8 row_mask:0xf bank_mask:0xc
	v_mov_b32_dpp v240, v80 row_shr:8 row_mask:0xf bank_mask:0xc
	v_mov_b32_dpp v241, v81 row_shr:8 row_mask:0xf bank_mask:0xc
	v_mov_b32_dpp v242, v82 row_shr:8 row_mask:0xf bank_mask:0xc
	v_mov_b32_dpp v243, v83 row_shr:8 row_mask:0xf bank_mask:0xc
	v_mov_b32_dpp v72, v68 row_shl:8 row_mask:0xf bank_mask:0x3
	v_mov_b32_dpp v73, v69 row_shl:8 row_mask:0xf bank_mask:0x3
	v_mov_b32_dpp v74, v70 row_shl:8 row_mask:0xf bank_mask:0x3
	v_mov_b32_dpp v75, v71 row_shl:8 row_mask:0xf bank_mask:0x3
	v_mov_b32_dpp v80, v76 row_shl:8 row_mask:0xf bank_mask:0x3
	v_mov_b32_dpp v81, v77 row_shl:8 row_mask:0xf bank_mask:0x3
	v_mov_b32_dpp v82, v78 row_shl:8 row_mask:0xf bank_mask:0x3
	v_mov_b32_dpp v83, v79 row_shl:8 row_mask:0xf bank_mask:0x3
	v_mfma_f32_16x16x32_bf16 v[4:7], v[236:239], v[240:243], v[4:7]
	s_nop 0
	v_mfma_f32_16x16x32_bf16 v[0:3], v[72:75], v[80:83], v[0:3]
	global_load_dwordx4 v[68:71], v[244:245], off offset:640
	global_load_dwordx4 v[72:75], v[246:247], off offset:640
	global_load_dwordx4 v[76:79], v[248:249], off offset:640
	global_load_dwordx4 v[80:83], v[250:251], off offset:640
	s_waitcnt vmcnt(32)
	v_mov_b32_e32 v236, v84
	v_mov_b32_e32 v237, v85
	v_mov_b32_e32 v238, v86
	v_mov_b32_e32 v239, v87
	v_mov_b32_e32 v240, v92
	v_mov_b32_e32 v241, v93
	v_mov_b32_e32 v242, v94
	v_mov_b32_e32 v243, v95
	v_mov_b32_dpp v236, v88 row_shr:8 row_mask:0xf bank_mask:0xc
	v_mov_b32_dpp v237, v89 row_shr:8 row_mask:0xf bank_mask:0xc
	v_mov_b32_dpp v238, v90 row_shr:8 row_mask:0xf bank_mask:0xc
	v_mov_b32_dpp v239, v91 row_shr:8 row_mask:0xf bank_mask:0xc
	v_mov_b32_dpp v240, v96 row_shr:8 row_mask:0xf bank_mask:0xc
	v_mov_b32_dpp v241, v97 row_shr:8 row_mask:0xf bank_mask:0xc
	v_mov_b32_dpp v242, v98 row_shr:8 row_mask:0xf bank_mask:0xc
	v_mov_b32_dpp v243, v99 row_shr:8 row_mask:0xf bank_mask:0xc
	v_mov_b32_dpp v88, v84 row_shl:8 row_mask:0xf bank_mask:0x3
	v_mov_b32_dpp v89, v85 row_shl:8 row_mask:0xf bank_mask:0x3
	v_mov_b32_dpp v90, v86 row_shl:8 row_mask:0xf bank_mask:0x3
	v_mov_b32_dpp v91, v87 row_shl:8 row_mask:0xf bank_mask:0x3
	v_mov_b32_dpp v96, v92 row_shl:8 row_mask:0xf bank_mask:0x3
	v_mov_b32_dpp v97, v93 row_shl:8 row_mask:0xf bank_mask:0x3
	v_mov_b32_dpp v98, v94 row_shl:8 row_mask:0xf bank_mask:0x3
	v_mov_b32_dpp v99, v95 row_shl:8 row_mask:0xf bank_mask:0x3
	v_mfma_f32_16x16x32_bf16 v[4:7], v[236:239], v[240:243], v[4:7]
	s_nop 0
	v_mfma_f32_16x16x32_bf16 v[0:3], v[88:91], v[96:99], v[0:3]
	global_load_dwordx4 v[84:87], v[244:245], off offset:768
	global_load_dwordx4 v[88:91], v[246:247], off offset:768
	global_load_dwordx4 v[92:95], v[248:249], off offset:768
	global_load_dwordx4 v[96:99], v[250:251], off offset:768
	s_waitcnt vmcnt(32)
; __device__ __forceinline__ f32x4 skinny16(const bf16_t* A, int lda, const bf16_t* Bt, int ldb, int K, int lane) {
;     ...
;     for (int k = 0; k < K / 32; k += 16) {
;         bf16x8 a[16], b[16];
; #pragma unroll
;         for (int i = 0; i < 16; ++i) { a[i] = ap[(k + i) * 4]; b[i] = bp[(k + i) * 4]; }
; #pragma unroll
;         for (int i = 0; i < 16; i += 2) { acc0 = __builtin_amdgcn_mfma_f32_16x16x32_bf16(a[i], b[i], acc0, 0, 0, 0); acc1 = __builtin_amdgcn_mfma_f32_16x16x32_bf16(a[i + 1], b[i + 1], acc1, 0, 0, 0); }
	v_mov_b32_e32 v236, v100
	v_mov_b32_e32 v237, v101
	v_mov_b32_e32 v238, v102
	v_mov_b32_e32 v239, v103
	v_mov_b32_e32 v240, v108
	v_mov_b32_e32 v241, v109
	v_mov_b32_e32 v242, v110
	v_mov_b32_e32 v243, v111
	v_mov_b32_dpp v236, v104 row_shr:8 row_mask:0xf bank_mask:0xc
	v_mov_b32_dpp v237, v105 row_shr:8 row_mask:0xf bank_mask:0xc
	v_mov_b32_dpp v238, v106 row_shr:8 row_mask:0xf bank_mask:0xc
	v_mov_b32_dpp v239, v107 row_shr:8 row_mask:0xf bank_mask:0xc
	v_mov_b32_dpp v240, v112 row_shr:8 row_mask:0xf bank_mask:0xc
	v_mov_b32_dpp v241, v113 row_shr:8 row_mask:0xf bank_mask:0xc
	v_mov_b32_dpp v242, v114 row_shr:8 row_mask:0xf bank_mask:0xc
	v_mov_b32_dpp v243, v115 row_shr:8 row_mask:0xf bank_mask:0xc
	v_mov_b32_dpp v104, v100 row_shl:8 row_mask:0xf bank_mask:0x3
	v_mov_b32_dpp v105, v101 row_shl:8 row_mask:0xf bank_mask:0x3
	v_mov_b32_dpp v106, v102 row_shl:8 row_mask:0xf bank_mask:0x3
	v_mov_b32_dpp v107, v103 row_shl:8 row_mask:0xf bank_mask:0x3
	v_mov_b32_dpp v112, v108 row_shl:8 row_mask:0xf bank_mask:0x3
	v_mov_b32_dpp v113, v109 row_shl:8 row_mask:0xf bank_mask:0x3
	v_mov_b32_dpp v114, v110 row_shl:8 row_mask:0xf bank_mask:0x3
	v_mov_b32_dpp v115, v111 row_shl:8 row_mask:0xf bank_mask:0x3
	v_mfma_f32_16x16x32_bf16 v[4:7], v[236:239], v[240:243], v[4:7]
	s_nop 0
	v_mfma_f32_16x16x32_bf16 v[0:3], v[104:107], v[112:115], v[0:3]
	global_load_dwordx4 v[100:103], v[244:245], off offset:896
	global_load_dwordx4 v[104:107], v[246:247], off offset:896
	global_load_dwordx4 v[108:111], v[248:249], off offset:896
	global_load_dwordx4 v[112:115], v[250:251], off offset:896
	s_waitcnt vmcnt(32)
	v_mov_b32_e32 v236, v116
	v_mov_b32_e32 v237, v117
	v_mov_b32_e32 v238, v118
	v_mov_b32_e32 v239, v119
	v_mov_b32_e32 v240, v124
	v_mov_b32_e32 v241, v125
	v_mov_b32_e32 v242, v126
	v_mov_b32_e32 v243, v127
	v_mov_b32_dpp v236, v120 row_shr:8 row_mask:0xf bank_mask:0xc
	v_mov_b32_dpp v237, v121 row_shr:8 row_mask:0xf bank_mask:0xc
	v_mov_b32_dpp v238, v122 row_shr:8 row_mask:0xf bank_mask:0xc
	v_mov_b32_dpp v239, v123 row_shr:8 row_mask:0xf bank_mask:0xc
	v_mov_b32_dpp v240, v128 row_shr:8 row_mask:0xf bank_mask:0xc
	v_mov_b32_dpp v241, v129 row_shr:8 row_mask:0xf bank_mask:0xc
	v_mov_b32_dpp v242, v130 row_shr:8 row_mask:0xf bank_mask:0xc
	v_mov_b32_dpp v243, v131 row_shr:8 row_mask:0xf bank_mask:0xc
	v_mov_b32_dpp v120, v116 row_shl:8 row_mask:0xf bank_mask:0x3
	v_mov_b32_dpp v121, v117 row_shl:8 row_mask:0xf bank_mask:0x3
	v_mov_b32_dpp v122, v118 row_shl:8 row_mask:0xf bank_mask:0x3
	v_mov_b32_dpp v123, v119 row_shl:8 row_mask:0xf bank_mask:0x3
	v_mov_b32_dpp v128, v124 row_shl:8 row_mask:0xf bank_mask:0x3
	v_mov_b32_dpp v129, v125 row_shl:8 row_mask:0xf bank_mask:0x3
	v_mov_b32_dpp v130, v126 row_shl:8 row_mask:0xf bank_mask:0x3
	v_mov_b32_dpp v131, v127 row_shl:8 row_mask:0xf bank_mask:0x3
	v_mfma_f32_16x16x32_bf16 v[4:7], v[236:239], v[240:243], v[4:7]
	s_nop 0
	v_mfma_f32_16x16x32_bf16 v[0:3], v[120:123], v[128:131], v[0:3]
	global_load_dwordx4 v[116:119], v[244:245], off offset:1024
	global_load_dwordx4 v[120:123], v[246:247], off offset:1024
	global_load_dwordx4 v[124:127], v[248:249], off offset:1024
	global_load_dwordx4 v[128:131], v[250:251], off offset:1024
	s_waitcnt vmcnt(32)
	v_mov_b32_e32 v236, v132
	v_mov_b32_e32 v237, v133
	v_mov_b32_e32 v238, v134
	v_mov_b32_e32 v239, v135
	v_mov_b32_e32 v240, v140
	v_mov_b32_e32 v241, v141
	v_mov_b32_e32 v242, v142
	v_mov_b32_e32 v243, v143
	v_mov_b32_dpp v236, v136 row_shr:8 row_mask:0xf bank_mask:0xc
	v_mov_b32_dpp v237, v137 row_shr:8 row_mask:0xf bank_mask:0xc
	v_mov_b32_dpp v238, v138 row_shr:8 row_mask:0xf bank_mask:0xc
	v_mov_b32_dpp v239, v139 row_shr:8 row_mask:0xf bank_mask:0xc
	v_mov_b32_dpp v240, v144 row_shr:8 row_mask:0xf bank_mask:0xc
	v_mov_b32_dpp v241, v145 row_shr:8 row_mask:0xf bank_mask:0xc
	v_mov_b32_dpp v242, v146 row_shr:8 row_mask:0xf bank_mask:0xc
	v_mov_b32_dpp v243, v147 row_shr:8 row_mask:0xf bank_mask:0xc
	v_mov_b32_dpp v136, v132 row_shl:8 row_mask:0xf bank_mask:0x3
	v_mov_b32_dpp v137, v133 row_shl:8 row_mask:0xf bank_mask:0x3
	v_mov_b32_dpp v138, v134 row_shl:8 row_mask:0xf bank_mask:0x3
	v_mov_b32_dpp v139, v135 row_shl:8 row_mask:0xf bank_mask:0x3
	v_mov_b32_dpp v144, v140 row_shl:8 row_mask:0xf bank_mask:0x3
	v_mov_b32_dpp v145, v141 row_shl:8 row_mask:0xf bank_mask:0x3
	v_mov_b32_dpp v146, v142 row_shl:8 row_mask:0xf bank_mask:0x3
	v_mov_b32_dpp v147, v143 row_shl:8 row_mask:0xf bank_mask:0x3
	v_mfma_f32_16x16x32_bf16 v[4:7], v[236:239], v[240:243], v[4:7]
	s_nop 0
	v_mfma_f32_16x16x32_bf16 v[0:3], v[136:139], v[144:147], v[0:3]
	global_load_dwordx4 v[132:135], v[244:245], off offset:1152
	global_load_dwordx4 v[136:139], v[246:247], off offset:1152
	global_load_dwordx4 v[140:143], v[248:249], off offset:1152
	global_load_dwordx4 v[144:147], v[250:251], off offset:1152
	s_waitcnt vmcnt(32)
; __device__ __forceinline__ f32x4 skinny16(const bf16_t* A, int lda, const bf16_t* Bt, int ldb, int K, int lane) {
;     ...
;     for (int k = 0; k < K / 32; k += 16) {
;         bf16x8 a[16], b[16];
; #pragma unroll
;         for (int i = 0; i < 16; ++i) { a[i] = ap[(k + i) * 4]; b[i] = bp[(k + i) * 4]; }
; #pragma unroll
;         for (int i = 0; i < 16; i += 2) { acc0 = __builtin_amdgcn_mfma_f32_16x16x32_bf16(a[i], b[i], acc0, 0, 0, 0); acc1 = __builtin_amdgcn_mfma_f32_16x16x32_bf16(a[i + 1], b[i + 1], acc1, 0, 0, 0); }
	v_mov_b32_e32 v236, v148
	v_mov_b32_e32 v237, v149
	v_mov_b32_e32 v238, v150
	v_mov_b32_e32 v239, v151
	v_mov_b32_e32 v240, v168
	v_mov_b32_e32 v241, v169
	v_mov_b32_e32 v242, v170
	v_mov_b32_e32 v243, v171
	v_mov_b32_dpp v236, v164 row_shr:8 row_mask:0xf bank_mask:0xc
	v_mov_b32_dpp v237, v165 row_shr:8 row_mask:0xf bank_mask:0xc
	v_mov_b32_dpp v238, v166 row_shr:8 row_mask:0xf bank_mask:0xc
	v_mov_b32_dpp v239, v167 row_shr:8 row_mask:0xf bank_mask:0xc
	v_mov_b32_dpp v240, v172 row_shr:8 row_mask:0xf bank_mask:0xc
	v_mov_b32_dpp v241, v173 row_shr:8 row_mask:0xf bank_mask:0xc
	v_mov_b32_dpp v242, v174 row_shr:8 row_mask:0xf bank_mask:0xc
	v_mov_b32_dpp v243, v175 row_shr:8 row_mask:0xf bank_mask:0xc
	v_mov_b32_dpp v164, v148 row_shl:8 row_mask:0xf bank_mask:0x3
	v_mov_b32_dpp v165, v149 row_shl:8 row_mask:0xf bank_mask:0x3
	v_mov_b32_dpp v166, v150 row_shl:8 row_mask:0xf bank_mask:0x3
	v_mov_b32_dpp v167, v151 row_shl:8 row_mask:0xf bank_mask:0x3
	v_mov_b32_dpp v172, v168 row_shl:8 row_mask:0xf bank_mask:0x3
	v_mov_b32_dpp v173, v169 row_shl:8 row_mask:0xf bank_mask:0x3
	v_mov_b32_dpp v174, v170 row_shl:8 row_mask:0xf bank_mask:0x3
	v_mov_b32_dpp v175, v171 row_shl:8 row_mask:0xf bank_mask:0x3
	v_mfma_f32_16x16x32_bf16 v[4:7], v[236:239], v[240:243], v[4:7]
	s_nop 0
	v_mfma_f32_16x16x32_bf16 v[0:3], v[164:167], v[172:175], v[0:3]
	global_load_dwordx4 v[148:151], v[244:245], off offset:1280
	global_load_dwordx4 v[164:167], v[246:247], off offset:1280
	global_load_dwordx4 v[168:171], v[248:249], off offset:1280
	global_load_dwordx4 v[172:175], v[250:251], off offset:1280
	s_waitcnt vmcnt(32)
	v_mov_b32_e32 v236, v176
	v_mov_b32_e32 v237, v177
	v_mov_b32_e32 v238, v178
	v_mov_b32_e32 v239, v179
	v_mov_b32_e32 v240, v184
	v_mov_b32_e32 v241, v185
	v_mov_b32_e32 v242, v186
	v_mov_b32_e32 v243, v187
	v_mov_b32_dpp v236, v180 row_shr:8 row_mask:0xf bank_mask:0xc
	v_mov_b32_dpp v237, v181 row_shr:8 row_mask:0xf bank_mask:0xc
	v_mov_b32_dpp v238, v182 row_shr:8 row_mask:0xf bank_mask:0xc
	v_mov_b32_dpp v239, v183 row_shr:8 row_mask:0xf bank_mask:0xc
	v_mov_b32_dpp v240, v188 row_shr:8 row_mask:0xf bank_mask:0xc
	v_mov_b32_dpp v241, v189 row_shr:8 row_mask:0xf bank_mask:0xc
	v_mov_b32_dpp v242, v190 row_shr:8 row_mask:0xf bank_mask:0xc
	v_mov_b32_dpp v243, v191 row_shr:8 row_mask:0xf bank_mask:0xc
	v_mov_b32_dpp v180, v176 row_shl:8 row_mask:0xf bank_mask:0x3
	v_mov_b32_dpp v181, v177 row_shl:8 row_mask:0xf bank_mask:0x3
	v_mov_b32_dpp v182, v178 row_shl:8 row_mask:0xf bank_mask:0x3
	v_mov_b32_dpp v183, v179 row_shl:8 row_mask:0xf bank_mask:0x3
	v_mov_b32_dpp v188, v184 row_shl:8 row_mask:0xf bank_mask:0x3
	v_mov_b32_dpp v189, v185 row_shl:8 row_mask:0xf bank_mask:0x3
	v_mov_b32_dpp v190, v186 row_shl:8 row_mask:0xf bank_mask:0x3
	v_mov_b32_dpp v191, v187 row_shl:8 row_mask:0xf bank_mask:0x3
	v_mfma_f32_16x16x32_bf16 v[4:7], v[236:239], v[240:243], v[4:7]
	s_nop 0
	v_mfma_f32_16x16x32_bf16 v[0:3], v[180:183], v[188:191], v[0:3]
	global_load_dwordx4 v[176:179], v[244:245], off offset:1408
	global_load_dwordx4 v[180:183], v[246:247], off offset:1408
	global_load_dwordx4 v[184:187], v[248:249], off offset:1408
	global_load_dwordx4 v[188:191], v[250:251], off offset:1408
	s_waitcnt vmcnt(32)
	v_mov_b32_e32 v236, v204
	v_mov_b32_e32 v237, v205
	v_mov_b32_e32 v238, v206
	v_mov_b32_e32 v239, v207
	v_mov_b32_e32 v240, v212
	v_mov_b32_e32 v241, v213
	v_mov_b32_e32 v242, v214
	v_mov_b32_e32 v243, v215
	v_mov_b32_dpp v236, v208 row_shr:8 row_mask:0xf bank_mask:0xc
	v_mov_b32_dpp v237, v209 row_shr:8 row_mask:0xf bank_mask:0xc
	v_mov_b32_dpp v238, v210 row_shr:8 row_mask:0xf bank_mask:0xc
	v_mov_b32_dpp v239, v211 row_shr:8 row_mask:0xf bank_mask:0xc
	v_mov_b32_dpp v240, v216 row_shr:8 row_mask:0xf bank_mask:0xc
	v_mov_b32_dpp v241, v217 row_shr:8 row_mask:0xf bank_mask:0xc
	v_mov_b32_dpp v242, v218 row_shr:8 row_mask:0xf bank_mask:0xc
	v_mov_b32_dpp v243, v219 row_shr:8 row_mask:0xf bank_mask:0xc
	v_mov_b32_dpp v208, v204 row_shl:8 row_mask:0xf bank_mask:0x3
	v_mov_b32_dpp v209, v205 row_shl:8 row_mask:0xf bank_mask:0x3
	v_mov_b32_dpp v210, v206 row_shl:8 row_mask:0xf bank_mask:0x3
	v_mov_b32_dpp v211, v207 row_shl:8 row_mask:0xf bank_mask:0x3
	v_mov_b32_dpp v216, v212 row_shl:8 row_mask:0xf bank_mask:0x3
	v_mov_b32_dpp v217, v213 row_shl:8 row_mask:0xf bank_mask:0x3
	v_mov_b32_dpp v218, v214 row_shl:8 row_mask:0xf bank_mask:0x3
	v_mov_b32_dpp v219, v215 row_shl:8 row_mask:0xf bank_mask:0x3
	v_mfma_f32_16x16x32_bf16 v[4:7], v[236:239], v[240:243], v[4:7]
	s_nop 0
	v_mfma_f32_16x16x32_bf16 v[0:3], v[208:211], v[216:219], v[0:3]
	global_load_dwordx4 v[204:207], v[244:245], off offset:1536
	global_load_dwordx4 v[208:211], v[246:247], off offset:1536
	global_load_dwordx4 v[212:215], v[248:249], off offset:1536
	global_load_dwordx4 v[216:219], v[250:251], off offset:1536
	s_waitcnt vmcnt(32)
; __device__ __forceinline__ f32x4 skinny16(const bf16_t* A, int lda, const bf16_t* Bt, int ldb, int K, int lane) {
;     ...
;     for (int k = 0; k < K / 32; k += 16) {
;         bf16x8 a[16], b[16];
; #pragma unroll
;         for (int i = 0; i < 16; ++i) { a[i] = ap[(k + i) * 4]; b[i] = bp[(k + i) * 4]; }
; #pragma unroll
;         for (int i = 0; i < 16; i += 2) { acc0 = __builtin_amdgcn_mfma_f32_16x16x32_bf16(a[i], b[i], acc0, 0, 0, 0); acc1 = __builtin_amdgcn_mfma_f32_16x16x32_bf16(a[i + 1], b[i + 1], acc1, 0, 0, 0); }
	v_mov_b32_e32 v236, v220
	v_mov_b32_e32 v237, v221
	v_mov_b32_e32 v238, v222
	v_mov_b32_e32 v239, v223
	v_mov_b32_e32 v240, v228
	v_mov_b32_e32 v241, v229
	v_mov_b32_e32 v242, v230
	v_mov_b32_e32 v243, v231
	v_mov_b32_dpp v236, v224 row_shr:8 row_mask:0xf bank_mask:0xc
	v_mov_b32_dpp v237, v225 row_shr:8 row_mask:0xf bank_mask:0xc
	v_mov_b32_dpp v238, v226 row_shr:8 row_mask:0xf bank_mask:0xc
	v_mov_b32_dpp v239, v227 row_shr:8 row_mask:0xf bank_mask:0xc
	v_mov_b32_dpp v240, v232 row_shr:8 row_mask:0xf bank_mask:0xc
	v_mov_b32_dpp v241, v233 row_shr:8 row_mask:0xf bank_mask:0xc
	v_mov_b32_dpp v242, v234 row_shr:8 row_mask:0xf bank_mask:0xc
	v_mov_b32_dpp v243, v235 row_shr:8 row_mask:0xf bank_mask:0xc
	v_mov_b32_dpp v224, v220 row_shl:8 row_mask:0xf bank_mask:0x3
	v_mov_b32_dpp v225, v221 row_shl:8 row_mask:0xf bank_mask:0x3
	v_mov_b32_dpp v226, v222 row_shl:8 row_mask:0xf bank_mask:0x3
	v_mov_b32_dpp v227, v223 row_shl:8 row_mask:0xf bank_mask:0x3
	v_mov_b32_dpp v232, v228 row_shl:8 row_mask:0xf bank_mask:0x3
	v_mov_b32_dpp v233, v229 row_shl:8 row_mask:0xf bank_mask:0x3
	v_mov_b32_dpp v234, v230 row_shl:8 row_mask:0xf bank_mask:0x3
	v_mov_b32_dpp v235, v231 row_shl:8 row_mask:0xf bank_mask:0x3
	v_mfma_f32_16x16x32_bf16 v[4:7], v[236:239], v[240:243], v[4:7]
	s_nop 0
	v_mfma_f32_16x16x32_bf16 v[0:3], v[224:227], v[232:235], v[0:3]
	global_load_dwordx4 v[220:223], v[244:245], off offset:1664
	global_load_dwordx4 v[224:227], v[246:247], off offset:1664
	global_load_dwordx4 v[228:231], v[248:249], off offset:1664
	global_load_dwordx4 v[232:235], v[250:251], off offset:1664
	s_waitcnt vmcnt(32)
	v_mov_b32_e32 v236, v68
	v_mov_b32_e32 v237, v69
	v_mov_b32_e32 v238, v70
	v_mov_b32_e32 v239, v71
	v_mov_b32_e32 v240, v76
	v_mov_b32_e32 v241, v77
	v_mov_b32_e32 v242, v78
	v_mov_b32_e32 v243, v79
	v_mov_b32_dpp v236, v72 row_shr:8 row_mask:0xf bank_mask:0xc
	v_mov_b32_dpp v237, v73 row_shr:8 row_mask:0xf bank_mask:0xc
	v_mov_b32_dpp v238, v74 row_shr:8 row_mask:0xf bank_mask:0xc
	v_mov_b32_dpp v239, v75 row_shr:8 row_mask:0xf bank_mask:0xc
	v_mov_b32_dpp v240, v80 row_shr:8 row_mask:0xf bank_mask:0xc
	v_mov_b32_dpp v241, v81 row_shr:8 row_mask:0xf bank_mask:0xc
	v_mov_b32_dpp v242, v82 row_shr:8 row_mask:0xf bank_mask:0xc
	v_mov_b32_dpp v243, v83 row_shr:8 row_mask:0xf bank_mask:0xc
	v_mov_b32_dpp v72, v68 row_shl:8 row_mask:0xf bank_mask:0x3
	v_mov_b32_dpp v73, v69 row_shl:8 row_mask:0xf bank_mask:0x3
	v_mov_b32_dpp v74, v70 row_shl:8 row_mask:0xf bank_mask:0x3
	v_mov_b32_dpp v75, v71 row_shl:8 row_mask:0xf bank_mask:0x3
	v_mov_b32_dpp v80, v76 row_shl:8 row_mask:0xf bank_mask:0x3
	v_mov_b32_dpp v81, v77 row_shl:8 row_mask:0xf bank_mask:0x3
	v_mov_b32_dpp v82, v78 row_shl:8 row_mask:0xf bank_mask:0x3
	v_mov_b32_dpp v83, v79 row_shl:8 row_mask:0xf bank_mask:0x3
	v_mfma_f32_16x16x32_bf16 v[4:7], v[236:239], v[240:243], v[4:7]
	s_nop 0
	v_mfma_f32_16x16x32_bf16 v[0:3], v[72:75], v[80:83], v[0:3]
	global_load_dwordx4 v[68:71], v[244:245], off offset:1792
	global_load_dwordx4 v[72:75], v[246:247], off offset:1792
	global_load_dwordx4 v[76:79], v[248:249], off offset:1792
	global_load_dwordx4 v[80:83], v[250:251], off offset:1792
	s_waitcnt vmcnt(32)
	v_mov_b32_e32 v236, v84
	v_mov_b32_e32 v237, v85
	v_mov_b32_e32 v238, v86
	v_mov_b32_e32 v239, v87
	v_mov_b32_e32 v240, v92
	v_mov_b32_e32 v241, v93
	v_mov_b32_e32 v242, v94
	v_mov_b32_e32 v243, v95
	v_mov_b32_dpp v236, v88 row_shr:8 row_mask:0xf bank_mask:0xc
	v_mov_b32_dpp v237, v89 row_shr:8 row_mask:0xf bank_mask:0xc
	v_mov_b32_dpp v238, v90 row_shr:8 row_mask:0xf bank_mask:0xc
	v_mov_b32_dpp v239, v91 row_shr:8 row_mask:0xf bank_mask:0xc
	v_mov_b32_dpp v240, v96 row_shr:8 row_mask:0xf bank_mask:0xc
	v_mov_b32_dpp v241, v97 row_shr:8 row_mask:0xf bank_mask:0xc
	v_mov_b32_dpp v242, v98 row_shr:8 row_mask:0xf bank_mask:0xc
	v_mov_b32_dpp v243, v99 row_shr:8 row_mask:0xf bank_mask:0xc
	v_mov_b32_dpp v88, v84 row_shl:8 row_mask:0xf bank_mask:0x3
	v_mov_b32_dpp v89, v85 row_shl:8 row_mask:0xf bank_mask:0x3
	v_mov_b32_dpp v90, v86 row_shl:8 row_mask:0xf bank_mask:0x3
	v_mov_b32_dpp v91, v87 row_shl:8 row_mask:0xf bank_mask:0x3
	v_mov_b32_dpp v96, v92 row_shl:8 row_mask:0xf bank_mask:0x3
	v_mov_b32_dpp v97, v93 row_shl:8 row_mask:0xf bank_mask:0x3
	v_mov_b32_dpp v98, v94 row_shl:8 row_mask:0xf bank_mask:0x3
	v_mov_b32_dpp v99, v95 row_shl:8 row_mask:0xf bank_mask:0x3
	v_mfma_f32_16x16x32_bf16 v[4:7], v[236:239], v[240:243], v[4:7]
	s_nop 0
	v_mfma_f32_16x16x32_bf16 v[0:3], v[88:91], v[96:99], v[0:3]
	global_load_dwordx4 v[84:87], v[244:245], off offset:1920
	global_load_dwordx4 v[88:91], v[246:247], off offset:1920
	global_load_dwordx4 v[92:95], v[248:249], off offset:1920
	global_load_dwordx4 v[96:99], v[250:251], off offset:1920
	s_waitcnt vmcnt(32)
	v_mov_b32_e32 v236, v100
	v_mov_b32_e32 v237, v101
	v_mov_b32_e32 v238, v102
	v_mov_b32_e32 v239, v103
	v_mov_b32_e32 v240, v108
	v_mov_b32_e32 v241, v109
	v_mov_b32_e32 v242, v110
	v_mov_b32_e32 v243, v111
	v_mov_b32_dpp v236, v104 row_shr:8 row_mask:0xf bank_mask:0xc
	v_mov_b32_dpp v237, v105 row_shr:8 row_mask:0xf bank_mask:0xc
	v_mov_b32_dpp v238, v106 row_shr:8 row_mask:0xf bank_mask:0xc
	v_mov_b32_dpp v239, v107 row_shr:8 row_mask:0xf bank_mask:0xc
	v_mov_b32_dpp v240, v112 row_shr:8 row_mask:0xf bank_mask:0xc
	v_mov_b32_dpp v241, v113 row_shr:8 row_mask:0xf bank_mask:0xc
	v_mov_b32_dpp v242, v114 row_shr:8 row_mask:0xf bank_mask:0xc
	v_mov_b32_dpp v243, v115 row_shr:8 row_mask:0xf bank_mask:0xc
	v_mov_b32_dpp v104, v100 row_shl:8 row_mask:0xf bank_mask:0x3
	v_mov_b32_dpp v105, v101 row_shl:8 row_mask:0xf bank_mask:0x3
	v_mov_b32_dpp v106, v102 row_shl:8 row_mask:0xf bank_mask:0x3
	v_mov_b32_dpp v107, v103 row_shl:8 row_mask:0xf bank_mask:0x3
	v_mov_b32_dpp v112, v108 row_shl:8 row_mask:0xf bank_mask:0x3
	v_mov_b32_dpp v113, v109 row_shl:8 row_mask:0xf bank_mask:0x3
	v_mov_b32_dpp v114, v110 row_shl:8 row_mask:0xf bank_mask:0x3
	v_mov_b32_dpp v115, v111 row_shl:8 row_mask:0xf bank_mask:0x3
	v_mfma_f32_16x16x32_bf16 v[4:7], v[236:239], v[240:243], v[4:7]
	s_nop 0
	v_mfma_f32_16x16x32_bf16 v[0:3], v[104:107], v[112:115], v[0:3]
	global_load_dwordx4 v[100:103], v[244:245], off offset:2048
	global_load_dwordx4 v[104:107], v[246:247], off offset:2048
	global_load_dwordx4 v[108:111], v[248:249], off offset:2048
	global_load_dwordx4 v[112:115], v[250:251], off offset:2048
	s_waitcnt vmcnt(32)
; __device__ __forceinline__ f32x4 skinny16(const bf16_t* A, int lda, const bf16_t* Bt, int ldb, int K, int lane) {
;     ...
;     for (int k = 0; k < K / 32; k += 16) {
;         bf16x8 a[16], b[16];
; #pragma unroll
;         for (int i = 0; i < 16; ++i) { a[i] = ap[(k + i) * 4]; b[i] = bp[(k + i) * 4]; }
; #pragma unroll
;         for (int i = 0; i < 16; i += 2) { acc0 = __builtin_amdgcn_mfma_f32_16x16x32_bf16(a[i], b[i], acc0, 0, 0, 0); acc1 = __builtin_amdgcn_mfma_f32_16x16x32_bf16(a[i + 1], b[i + 1], acc1, 0, 0, 0); }
	v_mov_b32_e32 v236, v116
	v_mov_b32_e32 v237, v117
	v_mov_b32_e32 v238, v118
	v_mov_b32_e32 v239, v119
	v_mov_b32_e32 v240, v124
	v_mov_b32_e32 v241, v125
	v_mov_b32_e32 v242, v126
	v_mov_b32_e32 v243, v127
	v_mov_b32_dpp v236, v120 row_shr:8 row_mask:0xf bank_mask:0xc
	v_mov_b32_dpp v237, v121 row_shr:8 row_mask:0xf bank_mask:0xc
	v_mov_b32_dpp v238, v122 row_shr:8 row_mask:0xf bank_mask:0xc
	v_mov_b32_dpp v239, v123 row_shr:8 row_mask:0xf bank_mask:0xc
	v_mov_b32_dpp v240, v128 row_shr:8 row_mask:0xf bank_mask:0xc
	v_mov_b32_dpp v241, v129 row_shr:8 row_mask:0xf bank_mask:0xc
	v_mov_b32_dpp v242, v130 row_shr:8 row_mask:0xf bank_mask:0xc
	v_mov_b32_dpp v243, v131 row_shr:8 row_mask:0xf bank_mask:0xc
	v_mov_b32_dpp v120, v116 row_shl:8 row_mask:0xf bank_mask:0x3
	v_mov_b32_dpp v121, v117 row_shl:8 row_mask:0xf bank_mask:0x3
	v_mov_b32_dpp v122, v118 row_shl:8 row_mask:0xf bank_mask:0x3
	v_mov_b32_dpp v123, v119 row_shl:8 row_mask:0xf bank_mask:0x3
	v_mov_b32_dpp v128, v124 row_shl:8 row_mask:0xf bank_mask:0x3
	v_mov_b32_dpp v129, v125 row_shl:8 row_mask:0xf bank_mask:0x3
	v_mov_b32_dpp v130, v126 row_shl:8 row_mask:0xf bank_mask:0x3
	v_mov_b32_dpp v131, v127 row_shl:8 row_mask:0xf bank_mask:0x3
	v_mfma_f32_16x16x32_bf16 v[4:7], v[236:239], v[240:243], v[4:7]
	s_nop 0
	v_mfma_f32_16x16x32_bf16 v[0:3], v[120:123], v[128:131], v[0:3]
	global_load_dwordx4 v[116:119], v[244:245], off offset:2176
	global_load_dwordx4 v[120:123], v[246:247], off offset:2176
	global_load_dwordx4 v[124:127], v[248:249], off offset:2176
	global_load_dwordx4 v[128:131], v[250:251], off offset:2176
	s_waitcnt vmcnt(32)
	v_mov_b32_e32 v236, v132
	v_mov_b32_e32 v237, v133
	v_mov_b32_e32 v238, v134
	v_mov_b32_e32 v239, v135
	v_mov_b32_e32 v240, v140
	v_mov_b32_e32 v241, v141
	v_mov_b32_e32 v242, v142
	v_mov_b32_e32 v243, v143
	v_mov_b32_dpp v236, v136 row_shr:8 row_mask:0xf bank_mask:0xc
	v_mov_b32_dpp v237, v137 row_shr:8 row_mask:0xf bank_mask:0xc
	v_mov_b32_dpp v238, v138 row_shr:8 row_mask:0xf bank_mask:0xc
	v_mov_b32_dpp v239, v139 row_shr:8 row_mask:0xf bank_mask:0xc
	v_mov_b32_dpp v240, v144 row_shr:8 row_mask:0xf bank_mask:0xc
	v_mov_b32_dpp v241, v145 row_shr:8 row_mask:0xf bank_mask:0xc
	v_mov_b32_dpp v242, v146 row_shr:8 row_mask:0xf bank_mask:0xc
	v_mov_b32_dpp v243, v147 row_shr:8 row_mask:0xf bank_mask:0xc
	v_mov_b32_dpp v136, v132 row_shl:8 row_mask:0xf bank_mask:0x3
	v_mov_b32_dpp v137, v133 row_shl:8 row_mask:0xf bank_mask:0x3
	v_mov_b32_dpp v138, v134 row_shl:8 row_mask:0xf bank_mask:0x3
	v_mov_b32_dpp v139, v135 row_shl:8 row_mask:0xf bank_mask:0x3
	v_mov_b32_dpp v144, v140 row_shl:8 row_mask:0xf bank_mask:0x3
	v_mov_b32_dpp v145, v141 row_shl:8 row_mask:0xf bank_mask:0x3
	v_mov_b32_dpp v146, v142 row_shl:8 row_mask:0xf bank_mask:0x3
	v_mov_b32_dpp v147, v143 row_shl:8 row_mask:0xf bank_mask:0x3
	v_mfma_f32_16x16x32_bf16 v[4:7], v[236:239], v[240:243], v[4:7]
	s_nop 0
	v_mfma_f32_16x16x32_bf16 v[0:3], v[136:139], v[144:147], v[0:3]
	global_load_dwordx4 v[132:135], v[244:245], off offset:2304
	global_load_dwordx4 v[136:139], v[246:247], off offset:2304
	global_load_dwordx4 v[140:143], v[248:249], off offset:2304
	global_load_dwordx4 v[144:147], v[250:251], off offset:2304
	s_waitcnt vmcnt(32)
	v_mov_b32_e32 v236, v148
	v_mov_b32_e32 v237, v149
	v_mov_b32_e32 v238, v150
	v_mov_b32_e32 v239, v151
	v_mov_b32_e32 v240, v168
	v_mov_b32_e32 v241, v169
	v_mov_b32_e32 v242, v170
	v_mov_b32_e32 v243, v171
	v_mov_b32_dpp v236, v164 row_shr:8 row_mask:0xf bank_mask:0xc
	v_mov_b32_dpp v237, v165 row_shr:8 row_mask:0xf bank_mask:0xc
	v_mov_b32_dpp v238, v166 row_shr:8 row_mask:0xf bank_mask:0xc
	v_mov_b32_dpp v239, v167 row_shr:8 row_mask:0xf bank_mask:0xc
	v_mov_b32_dpp v240, v172 row_shr:8 row_mask:0xf bank_mask:0xc
	v_mov_b32_dpp v241, v173 row_shr:8 row_mask:0xf bank_mask:0xc
	v_mov_b32_dpp v242, v174 row_shr:8 row_mask:0xf bank_mask:0xc
	v_mov_b32_dpp v243, v175 row_shr:8 row_mask:0xf bank_mask:0xc
	v_mov_b32_dpp v164, v148 row_shl:8 row_mask:0xf bank_mask:0x3
	v_mov_b32_dpp v165, v149 row_shl:8 row_mask:0xf bank_mask:0x3
	v_mov_b32_dpp v166, v150 row_shl:8 row_mask:0xf bank_mask:0x3
	v_mov_b32_dpp v167, v151 row_shl:8 row_mask:0xf bank_mask:0x3
	v_mov_b32_dpp v172, v168 row_shl:8 row_mask:0xf bank_mask:0x3
	v_mov_b32_dpp v173, v169 row_shl:8 row_mask:0xf bank_mask:0x3
	v_mov_b32_dpp v174, v170 row_shl:8 row_mask:0xf bank_mask:0x3
	v_mov_b32_dpp v175, v171 row_shl:8 row_mask:0xf bank_mask:0x3
	v_mfma_f32_16x16x32_bf16 v[4:7], v[236:239], v[240:243], v[4:7]
	s_nop 0
	v_mfma_f32_16x16x32_bf16 v[0:3], v[164:167], v[172:175], v[0:3]
	global_load_dwordx4 v[148:151], v[244:245], off offset:2432
	global_load_dwordx4 v[164:167], v[246:247], off offset:2432
	global_load_dwordx4 v[168:171], v[248:249], off offset:2432
	global_load_dwordx4 v[172:175], v[250:251], off offset:2432
	s_waitcnt vmcnt(32)
; __device__ __forceinline__ f32x4 skinny16(const bf16_t* A, int lda, const bf16_t* Bt, int ldb, int K, int lane) {
;     ...
;     for (int k = 0; k < K / 32; k += 16) {
;         bf16x8 a[16], b[16];
; #pragma unroll
;         for (int i = 0; i < 16; ++i) { a[i] = ap[(k + i) * 4]; b[i] = bp[(k + i) * 4]; }
; #pragma unroll
;         for (int i = 0; i < 16; i += 2) { acc0 = __builtin_amdgcn_mfma_f32_16x16x32_bf16(a[i], b[i], acc0, 0, 0, 0); acc1 = __builtin_amdgcn_mfma_f32_16x16x32_bf16(a[i + 1], b[i + 1], acc1, 0, 0, 0); }
	v_mov_b32_e32 v236, v176
	v_mov_b32_e32 v237, v177
	v_mov_b32_e32 v238, v178
	v_mov_b32_e32 v239, v179
	v_mov_b32_e32 v240, v184
	v_mov_b32_e32 v241, v185
	v_mov_b32_e32 v242, v186
	v_mov_b32_e32 v243, v187
	v_mov_b32_dpp v236, v180 row_shr:8 row_mask:0xf bank_mask:0xc
	v_mov_b32_dpp v237, v181 row_shr:8 row_mask:0xf bank_mask:0xc
	v_mov_b32_dpp v238, v182 row_shr:8 row_mask:0xf bank_mask:0xc
	v_mov_b32_dpp v239, v183 row_shr:8 row_mask:0xf bank_mask:0xc
	v_mov_b32_dpp v240, v188 row_shr:8 row_mask:0xf bank_mask:0xc
	v_mov_b32_dpp v241, v189 row_shr:8 row_mask:0xf bank_mask:0xc
	v_mov_b32_dpp v242, v190 row_shr:8 row_mask:0xf bank_mask:0xc
	v_mov_b32_dpp v243, v191 row_shr:8 row_mask:0xf bank_mask:0xc
	v_mov_b32_dpp v180, v176 row_shl:8 row_mask:0xf bank_mask:0x3
	v_mov_b32_dpp v181, v177 row_shl:8 row_mask:0xf bank_mask:0x3
	v_mov_b32_dpp v182, v178 row_shl:8 row_mask:0xf bank_mask:0x3
	v_mov_b32_dpp v183, v179 row_shl:8 row_mask:0xf bank_mask:0x3
	v_mov_b32_dpp v188, v184 row_shl:8 row_mask:0xf bank_mask:0x3
	v_mov_b32_dpp v189, v185 row_shl:8 row_mask:0xf bank_mask:0x3
	v_mov_b32_dpp v190, v186 row_shl:8 row_mask:0xf bank_mask:0x3
	v_mov_b32_dpp v191, v187 row_shl:8 row_mask:0xf bank_mask:0x3
	v_mfma_f32_16x16x32_bf16 v[4:7], v[236:239], v[240:243], v[4:7]
	s_nop 0
	v_mfma_f32_16x16x32_bf16 v[0:3], v[180:183], v[188:191], v[0:3]
	global_load_dwordx4 v[176:179], v[244:245], off offset:2560
	global_load_dwordx4 v[180:183], v[246:247], off offset:2560
	global_load_dwordx4 v[184:187], v[248:249], off offset:2560
	global_load_dwordx4 v[188:191], v[250:251], off offset:2560
	s_waitcnt vmcnt(32)
	v_mov_b32_e32 v236, v204
	v_mov_b32_e32 v237, v205
	v_mov_b32_e32 v238, v206
	v_mov_b32_e32 v239, v207
	v_mov_b32_e32 v240, v212
	v_mov_b32_e32 v241, v213
	v_mov_b32_e32 v242, v214
	v_mov_b32_e32 v243, v215
	v_mov_b32_dpp v236, v208 row_shr:8 row_mask:0xf bank_mask:0xc
	v_mov_b32_dpp v237, v209 row_shr:8 row_mask:0xf bank_mask:0xc
	v_mov_b32_dpp v238, v210 row_shr:8 row_mask:0xf bank_mask:0xc
	v_mov_b32_dpp v239, v211 row_shr:8 row_mask:0xf bank_mask:0xc
	v_mov_b32_dpp v240, v216 row_shr:8 row_mask:0xf bank_mask:0xc
	v_mov_b32_dpp v241, v217 row_shr:8 row_mask:0xf bank_mask:0xc
	v_mov_b32_dpp v242, v218 row_shr:8 row_mask:0xf bank_mask:0xc
	v_mov_b32_dpp v243, v219 row_shr:8 row_mask:0xf bank_mask:0xc
	v_mov_b32_dpp v208, v204 row_shl:8 row_mask:0xf bank_mask:0x3
	v_mov_b32_dpp v209, v205 row_shl:8 row_mask:0xf bank_mask:0x3
	v_mov_b32_dpp v210, v206 row_shl:8 row_mask:0xf bank_mask:0x3
	v_mov_b32_dpp v211, v207 row_shl:8 row_mask:0xf bank_mask:0x3
	v_mov_b32_dpp v216, v212 row_shl:8 row_mask:0xf bank_mask:0x3
	v_mov_b32_dpp v217, v213 row_shl:8 row_mask:0xf bank_mask:0x3
	v_mov_b32_dpp v218, v214 row_shl:8 row_mask:0xf bank_mask:0x3
	v_mov_b32_dpp v219, v215 row_shl:8 row_mask:0xf bank_mask:0x3
	v_mfma_f32_16x16x32_bf16 v[4:7], v[236:239], v[240:243], v[4:7]
	s_nop 0
	v_mfma_f32_16x16x32_bf16 v[0:3], v[208:211], v[216:219], v[0:3]
	global_load_dwordx4 v[204:207], v[244:245], off offset:2688
	global_load_dwordx4 v[208:211], v[246:247], off offset:2688
	global_load_dwordx4 v[212:215], v[248:249], off offset:2688
	global_load_dwordx4 v[216:219], v[250:251], off offset:2688
	s_waitcnt vmcnt(32)
	v_mov_b32_e32 v236, v220
	v_mov_b32_e32 v237, v221
	v_mov_b32_e32 v238, v222
	v_mov_b32_e32 v239, v223
	v_mov_b32_e32 v240, v228
	v_mov_b32_e32 v241, v229
	v_mov_b32_e32 v242, v230
	v_mov_b32_e32 v243, v231
	v_mov_b32_dpp v236, v224 row_shr:8 row_mask:0xf bank_mask:0xc
	v_mov_b32_dpp v237, v225 row_shr:8 row_mask:0xf bank_mask:0xc
	v_mov_b32_dpp v238, v226 row_shr:8 row_mask:0xf bank_mask:0xc
	v_mov_b32_dpp v239, v227 row_shr:8 row_mask:0xf bank_mask:0xc
	v_mov_b32_dpp v240, v232 row_shr:8 row_mask:0xf bank_mask:0xc
	v_mov_b32_dpp v241, v233 row_shr:8 row_mask:0xf bank_mask:0xc
	v_mov_b32_dpp v242, v234 row_shr:8 row_mask:0xf bank_mask:0xc
	v_mov_b32_dpp v243, v235 row_shr:8 row_mask:0xf bank_mask:0xc
	v_mov_b32_dpp v224, v220 row_shl:8 row_mask:0xf bank_mask:0x3
	v_mov_b32_dpp v225, v221 row_shl:8 row_mask:0xf bank_mask:0x3
	v_mov_b32_dpp v226, v222 row_shl:8 row_mask:0xf bank_mask:0x3
	v_mov_b32_dpp v227, v223 row_shl:8 row_mask:0xf bank_mask:0x3
	v_mov_b32_dpp v232, v228 row_shl:8 row_mask:0xf bank_mask:0x3
	v_mov_b32_dpp v233, v229 row_shl:8 row_mask:0xf bank_mask:0x3
	v_mov_b32_dpp v234, v230 row_shl:8 row_mask:0xf bank_mask:0x3
	v_mov_b32_dpp v235, v231 row_shl:8 row_mask:0xf bank_mask:0x3
	v_mfma_f32_16x16x32_bf16 v[4:7], v[236:239], v[240:243], v[4:7]
	s_nop 0
	v_mfma_f32_16x16x32_bf16 v[0:3], v[224:227], v[232:235], v[0:3]
	global_load_dwordx4 v[220:223], v[244:245], off offset:2816
	global_load_dwordx4 v[224:227], v[246:247], off offset:2816
	global_load_dwordx4 v[228:231], v[248:249], off offset:2816
	global_load_dwordx4 v[232:235], v[250:251], off offset:2816
	s_waitcnt vmcnt(32)
; __device__ __forceinline__ f32x4 skinny16(const bf16_t* A, int lda, const bf16_t* Bt, int ldb, int K, int lane) {
;     ...
;     for (int k = 0; k < K / 32; k += 16) {
;         bf16x8 a[16], b[16];
; #pragma unroll
;         for (int i = 0; i < 16; ++i) { a[i] = ap[(k + i) * 4]; b[i] = bp[(k + i) * 4]; }
; #pragma unroll
;         for (int i = 0; i < 16; i += 2) { acc0 = __builtin_amdgcn_mfma_f32_16x16x32_bf16(a[i], b[i], acc0, 0, 0, 0); acc1 = __builtin_amdgcn_mfma_f32_16x16x32_bf16(a[i + 1], b[i + 1], acc1, 0, 0, 0); }
	v_mov_b32_e32 v236, v68
	v_mov_b32_e32 v237, v69
	v_mov_b32_e32 v238, v70
	v_mov_b32_e32 v239, v71
	v_mov_b32_e32 v240, v76
	v_mov_b32_e32 v241, v77
	v_mov_b32_e32 v242, v78
	v_mov_b32_e32 v243, v79
	v_mov_b32_dpp v236, v72 row_shr:8 row_mask:0xf bank_mask:0xc
	v_mov_b32_dpp v237, v73 row_shr:8 row_mask:0xf bank_mask:0xc
	v_mov_b32_dpp v238, v74 row_shr:8 row_mask:0xf bank_mask:0xc
	v_mov_b32_dpp v239, v75 row_shr:8 row_mask:0xf bank_mask:0xc
	v_mov_b32_dpp v240, v80 row_shr:8 row_mask:0xf bank_mask:0xc
	v_mov_b32_dpp v241, v81 row_shr:8 row_mask:0xf bank_mask:0xc
	v_mov_b32_dpp v242, v82 row_shr:8 row_mask:0xf bank_mask:0xc
	v_mov_b32_dpp v243, v83 row_shr:8 row_mask:0xf bank_mask:0xc
	v_mov_b32_dpp v72, v68 row_shl:8 row_mask:0xf bank_mask:0x3
	v_mov_b32_dpp v73, v69 row_shl:8 row_mask:0xf bank_mask:0x3
	v_mov_b32_dpp v74, v70 row_shl:8 row_mask:0xf bank_mask:0x3
	v_mov_b32_dpp v75, v71 row_shl:8 row_mask:0xf bank_mask:0x3
	v_mov_b32_dpp v80, v76 row_shl:8 row_mask:0xf bank_mask:0x3
	v_mov_b32_dpp v81, v77 row_shl:8 row_mask:0xf bank_mask:0x3
	v_mov_b32_dpp v82, v78 row_shl:8 row_mask:0xf bank_mask:0x3
	v_mov_b32_dpp v83, v79 row_shl:8 row_mask:0xf bank_mask:0x3
	v_mfma_f32_16x16x32_bf16 v[4:7], v[236:239], v[240:243], v[4:7]
	s_nop 0
	v_mfma_f32_16x16x32_bf16 v[0:3], v[72:75], v[80:83], v[0:3]
	global_load_dwordx4 v[68:71], v[244:245], off offset:2944
	global_load_dwordx4 v[72:75], v[246:247], off offset:2944
	global_load_dwordx4 v[76:79], v[248:249], off offset:2944
	global_load_dwordx4 v[80:83], v[250:251], off offset:2944
	s_waitcnt vmcnt(32)
	v_mov_b32_e32 v236, v84
	v_mov_b32_e32 v237, v85
	v_mov_b32_e32 v238, v86
	v_mov_b32_e32 v239, v87
	v_mov_b32_e32 v240, v92
	v_mov_b32_e32 v241, v93
	v_mov_b32_e32 v242, v94
	v_mov_b32_e32 v243, v95
	v_mov_b32_dpp v236, v88 row_shr:8 row_mask:0xf bank_mask:0xc
	v_mov_b32_dpp v237, v89 row_shr:8 row_mask:0xf bank_mask:0xc
	v_mov_b32_dpp v238, v90 row_shr:8 row_mask:0xf bank_mask:0xc
	v_mov_b32_dpp v239, v91 row_shr:8 row_mask:0xf bank_mask:0xc
	v_mov_b32_dpp v240, v96 row_shr:8 row_mask:0xf bank_mask:0xc
	v_mov_b32_dpp v241, v97 row_shr:8 row_mask:0xf bank_mask:0xc
	v_mov_b32_dpp v242, v98 row_shr:8 row_mask:0xf bank_mask:0xc
	v_mov_b32_dpp v243, v99 row_shr:8 row_mask:0xf bank_mask:0xc
	v_mov_b32_dpp v88, v84 row_shl:8 row_mask:0xf bank_mask:0x3
	v_mov_b32_dpp v89, v85 row_shl:8 row_mask:0xf bank_mask:0x3
	v_mov_b32_dpp v90, v86 row_shl:8 row_mask:0xf bank_mask:0x3
	v_mov_b32_dpp v91, v87 row_shl:8 row_mask:0xf bank_mask:0x3
	v_mov_b32_dpp v96, v92 row_shl:8 row_mask:0xf bank_mask:0x3
	v_mov_b32_dpp v97, v93 row_shl:8 row_mask:0xf bank_mask:0x3
	v_mov_b32_dpp v98, v94 row_shl:8 row_mask:0xf bank_mask:0x3
	v_mov_b32_dpp v99, v95 row_shl:8 row_mask:0xf bank_mask:0x3
	v_mfma_f32_16x16x32_bf16 v[4:7], v[236:239], v[240:243], v[4:7]
	s_nop 0
	v_mfma_f32_16x16x32_bf16 v[0:3], v[88:91], v[96:99], v[0:3]
	global_load_dwordx4 v[84:87], v[244:245], off offset:3072
	global_load_dwordx4 v[88:91], v[246:247], off offset:3072
	global_load_dwordx4 v[92:95], v[248:249], off offset:3072
	global_load_dwordx4 v[96:99], v[250:251], off offset:3072
	s_waitcnt vmcnt(32)
	v_mov_b32_e32 v236, v100
	v_mov_b32_e32 v237, v101
	v_mov_b32_e32 v238, v102
	v_mov_b32_e32 v239, v103
	v_mov_b32_e32 v240, v108
	v_mov_b32_e32 v241, v109
	v_mov_b32_e32 v242, v110
	v_mov_b32_e32 v243, v111
	v_mov_b32_dpp v236, v104 row_shr:8 row_mask:0xf bank_mask:0xc
	v_mov_b32_dpp v237, v105 row_shr:8 row_mask:0xf bank_mask:0xc
	v_mov_b32_dpp v238, v106 row_shr:8 row_mask:0xf bank_mask:0xc
	v_mov_b32_dpp v239, v107 row_shr:8 row_mask:0xf bank_mask:0xc
	v_mov_b32_dpp v240, v112 row_shr:8 row_mask:0xf bank_mask:0xc
	v_mov_b32_dpp v241, v113 row_shr:8 row_mask:0xf bank_mask:0xc
	v_mov_b32_dpp v242, v114 row_shr:8 row_mask:0xf bank_mask:0xc
	v_mov_b32_dpp v243, v115 row_shr:8 row_mask:0xf bank_mask:0xc
	v_mov_b32_dpp v104, v100 row_shl:8 row_mask:0xf bank_mask:0x3
	v_mov_b32_dpp v105, v101 row_shl:8 row_mask:0xf bank_mask:0x3
	v_mov_b32_dpp v106, v102 row_shl:8 row_mask:0xf bank_mask:0x3
	v_mov_b32_dpp v107, v103 row_shl:8 row_mask:0xf bank_mask:0x3
	v_mov_b32_dpp v112, v108 row_shl:8 row_mask:0xf bank_mask:0x3
	v_mov_b32_dpp v113, v109 row_shl:8 row_mask:0xf bank_mask:0x3
	v_mov_b32_dpp v114, v110 row_shl:8 row_mask:0xf bank_mask:0x3
	v_mov_b32_dpp v115, v111 row_shl:8 row_mask:0xf bank_mask:0x3
	v_mfma_f32_16x16x32_bf16 v[4:7], v[236:239], v[240:243], v[4:7]
	s_nop 0
	v_mfma_f32_16x16x32_bf16 v[0:3], v[104:107], v[112:115], v[0:3]
	global_load_dwordx4 v[100:103], v[244:245], off offset:3200
	global_load_dwordx4 v[104:107], v[246:247], off offset:3200
	global_load_dwordx4 v[108:111], v[248:249], off offset:3200
	global_load_dwordx4 v[112:115], v[250:251], off offset:3200
	s_waitcnt vmcnt(32)
	v_mov_b32_e32 v236, v116
	v_mov_b32_e32 v237, v117
	v_mov_b32_e32 v238, v118
	v_mov_b32_e32 v239, v119
	v_mov_b32_e32 v240, v124
	v_mov_b32_e32 v241, v125
	v_mov_b32_e32 v242, v126
	v_mov_b32_e32 v243, v127
	v_mov_b32_dpp v236, v120 row_shr:8 row_mask:0xf bank_mask:0xc
	v_mov_b32_dpp v237, v121 row_shr:8 row_mask:0xf bank_mask:0xc
	v_mov_b32_dpp v238, v122 row_shr:8 row_mask:0xf bank_mask:0xc
	v_mov_b32_dpp v239, v123 row_shr:8 row_mask:0xf bank_mask:0xc
	v_mov_b32_dpp v240, v128 row_shr:8 row_mask:0xf bank_mask:0xc
	v_mov_b32_dpp v241, v129 row_shr:8 row_mask:0xf bank_mask:0xc
	v_mov_b32_dpp v242, v130 row_shr:8 row_mask:0xf bank_mask:0xc
	v_mov_b32_dpp v243, v131 row_shr:8 row_mask:0xf bank_mask:0xc
	v_mov_b32_dpp v120, v116 row_shl:8 row_mask:0xf bank_mask:0x3
	v_mov_b32_dpp v121, v117 row_shl:8 row_mask:0xf bank_mask:0x3
	v_mov_b32_dpp v122, v118 row_shl:8 row_mask:0xf bank_mask:0x3
	v_mov_b32_dpp v123, v119 row_shl:8 row_mask:0xf bank_mask:0x3
	v_mov_b32_dpp v128, v124 row_shl:8 row_mask:0xf bank_mask:0x3
	v_mov_b32_dpp v129, v125 row_shl:8 row_mask:0xf bank_mask:0x3
	v_mov_b32_dpp v130, v126 row_shl:8 row_mask:0xf bank_mask:0x3
	v_mov_b32_dpp v131, v127 row_shl:8 row_mask:0xf bank_mask:0x3
	v_mfma_f32_16x16x32_bf16 v[4:7], v[236:239], v[240:243], v[4:7]
	s_nop 0
	v_mfma_f32_16x16x32_bf16 v[0:3], v[120:123], v[128:131], v[0:3]
	global_load_dwordx4 v[116:119], v[244:245], off offset:3328
	global_load_dwordx4 v[120:123], v[246:247], off offset:3328
	global_load_dwordx4 v[124:127], v[248:249], off offset:3328
	global_load_dwordx4 v[128:131], v[250:251], off offset:3328
	s_waitcnt vmcnt(32)
; __device__ __forceinline__ f32x4 skinny16(const bf16_t* A, int lda, const bf16_t* Bt, int ldb, int K, int lane) {
;     ...
;     for (int k = 0; k < K / 32; k += 16) {
;         bf16x8 a[16], b[16];
; #pragma unroll
;         for (int i = 0; i < 16; ++i) { a[i] = ap[(k + i) * 4]; b[i] = bp[(k + i) * 4]; }
; #pragma unroll
;         for (int i = 0; i < 16; i += 2) { acc0 = __builtin_amdgcn_mfma_f32_16x16x32_bf16(a[i], b[i], acc0, 0, 0, 0); acc1 = __builtin_amdgcn_mfma_f32_16x16x32_bf16(a[i + 1], b[i + 1], acc1, 0, 0, 0); }
	v_mov_b32_e32 v236, v132
	v_mov_b32_e32 v237, v133
	v_mov_b32_e32 v238, v134
	v_mov_b32_e32 v239, v135
	v_mov_b32_e32 v240, v140
	v_mov_b32_e32 v241, v141
	v_mov_b32_e32 v242, v142
	v_mov_b32_e32 v243, v143
	v_mov_b32_dpp v236, v136 row_shr:8 row_mask:0xf bank_mask:0xc
	v_mov_b32_dpp v237, v137 row_shr:8 row_mask:0xf bank_mask:0xc
	v_mov_b32_dpp v238, v138 row_shr:8 row_mask:0xf bank_mask:0xc
	v_mov_b32_dpp v239, v139 row_shr:8 row_mask:0xf bank_mask:0xc
	v_mov_b32_dpp v240, v144 row_shr:8 row_mask:0xf bank_mask:0xc
	v_mov_b32_dpp v241, v145 row_shr:8 row_mask:0xf bank_mask:0xc
	v_mov_b32_dpp v242, v146 row_shr:8 row_mask:0xf bank_mask:0xc
	v_mov_b32_dpp v243, v147 row_shr:8 row_mask:0xf bank_mask:0xc
	v_mov_b32_dpp v136, v132 row_shl:8 row_mask:0xf bank_mask:0x3
	v_mov_b32_dpp v137, v133 row_shl:8 row_mask:0xf bank_mask:0x3
	v_mov_b32_dpp v138, v134 row_shl:8 row_mask:0xf bank_mask:0x3
	v_mov_b32_dpp v139, v135 row_shl:8 row_mask:0xf bank_mask:0x3
	v_mov_b32_dpp v144, v140 row_shl:8 row_mask:0xf bank_mask:0x3
	v_mov_b32_dpp v145, v141 row_shl:8 row_mask:0xf bank_mask:0x3
	v_mov_b32_dpp v146, v142 row_shl:8 row_mask:0xf bank_mask:0x3
	v_mov_b32_dpp v147, v143 row_shl:8 row_mask:0xf bank_mask:0x3
	v_mfma_f32_16x16x32_bf16 v[4:7], v[236:239], v[240:243], v[4:7]
	s_nop 0
	v_mfma_f32_16x16x32_bf16 v[0:3], v[136:139], v[144:147], v[0:3]
	global_load_dwordx4 v[132:135], v[244:245], off offset:3456
	global_load_dwordx4 v[136:139], v[246:247], off offset:3456
	global_load_dwordx4 v[140:143], v[248:249], off offset:3456
	global_load_dwordx4 v[144:147], v[250:251], off offset:3456
	s_waitcnt vmcnt(32)
	v_mov_b32_e32 v236, v148
	v_mov_b32_e32 v237, v149
	v_mov_b32_e32 v238, v150
	v_mov_b32_e32 v239, v151
	v_mov_b32_e32 v240, v168
	v_mov_b32_e32 v241, v169
	v_mov_b32_e32 v242, v170
	v_mov_b32_e32 v243, v171
	v_mov_b32_dpp v236, v164 row_shr:8 row_mask:0xf bank_mask:0xc
	v_mov_b32_dpp v237, v165 row_shr:8 row_mask:0xf bank_mask:0xc
	v_mov_b32_dpp v238, v166 row_shr:8 row_mask:0xf bank_mask:0xc
	v_mov_b32_dpp v239, v167 row_shr:8 row_mask:0xf bank_mask:0xc
	v_mov_b32_dpp v240, v172 row_shr:8 row_mask:0xf bank_mask:0xc
	v_mov_b32_dpp v241, v173 row_shr:8 row_mask:0xf bank_mask:0xc
	v_mov_b32_dpp v242, v174 row_shr:8 row_mask:0xf bank_mask:0xc
	v_mov_b32_dpp v243, v175 row_shr:8 row_mask:0xf bank_mask:0xc
	v_mov_b32_dpp v164, v148 row_shl:8 row_mask:0xf bank_mask:0x3
	v_mov_b32_dpp v165, v149 row_shl:8 row_mask:0xf bank_mask:0x3
	v_mov_b32_dpp v166, v150 row_shl:8 row_mask:0xf bank_mask:0x3
	v_mov_b32_dpp v167, v151 row_shl:8 row_mask:0xf bank_mask:0x3
	v_mov_b32_dpp v172, v168 row_shl:8 row_mask:0xf bank_mask:0x3
	v_mov_b32_dpp v173, v169 row_shl:8 row_mask:0xf bank_mask:0x3
	v_mov_b32_dpp v174, v170 row_shl:8 row_mask:0xf bank_mask:0x3
	v_mov_b32_dpp v175, v171 row_shl:8 row_mask:0xf bank_mask:0x3
	v_mfma_f32_16x16x32_bf16 v[4:7], v[236:239], v[240:243], v[4:7]
	s_nop 0
	v_mfma_f32_16x16x32_bf16 v[0:3], v[164:167], v[172:175], v[0:3]
	s_waitcnt vmcnt(28)
	v_mov_b32_e32 v236, v176
	v_mov_b32_e32 v237, v177
	v_mov_b32_e32 v238, v178
	v_mov_b32_e32 v239, v179
	v_mov_b32_e32 v240, v184
	v_mov_b32_e32 v241, v185
	v_mov_b32_e32 v242, v186
	v_mov_b32_e32 v243, v187
	v_mov_b32_dpp v236, v180 row_shr:8 row_mask:0xf bank_mask:0xc
	v_mov_b32_dpp v237, v181 row_shr:8 row_mask:0xf bank_mask:0xc
	v_mov_b32_dpp v238, v182 row_shr:8 row_mask:0xf bank_mask:0xc
	v_mov_b32_dpp v239, v183 row_shr:8 row_mask:0xf bank_mask:0xc
	v_mov_b32_dpp v240, v188 row_shr:8 row_mask:0xf bank_mask:0xc
	v_mov_b32_dpp v241, v189 row_shr:8 row_mask:0xf bank_mask:0xc
	v_mov_b32_dpp v242, v190 row_shr:8 row_mask:0xf bank_mask:0xc
	v_mov_b32_dpp v243, v191 row_shr:8 row_mask:0xf bank_mask:0xc
	v_mov_b32_dpp v180, v176 row_shl:8 row_mask:0xf bank_mask:0x3
	v_mov_b32_dpp v181, v177 row_shl:8 row_mask:0xf bank_mask:0x3
	v_mov_b32_dpp v182, v178 row_shl:8 row_mask:0xf bank_mask:0x3
	v_mov_b32_dpp v183, v179 row_shl:8 row_mask:0xf bank_mask:0x3
	v_mov_b32_dpp v188, v184 row_shl:8 row_mask:0xf bank_mask:0x3
	v_mov_b32_dpp v189, v185 row_shl:8 row_mask:0xf bank_mask:0x3
	v_mov_b32_dpp v190, v186 row_shl:8 row_mask:0xf bank_mask:0x3
	v_mov_b32_dpp v191, v187 row_shl:8 row_mask:0xf bank_mask:0x3
	v_mfma_f32_16x16x32_bf16 v[4:7], v[236:239], v[240:243], v[4:7]
	s_nop 0
	v_mfma_f32_16x16x32_bf16 v[0:3], v[180:183], v[188:191], v[0:3]
	s_waitcnt vmcnt(24)
	v_mov_b32_e32 v236, v204
	v_mov_b32_e32 v237, v205
	v_mov_b32_e32 v238, v206
	v_mov_b32_e32 v239, v207
	v_mov_b32_e32 v240, v212
	v_mov_b32_e32 v241, v213
	v_mov_b32_e32 v242, v214
	v_mov_b32_e32 v243, v215
	v_mov_b32_dpp v236, v208 row_shr:8 row_mask:0xf bank_mask:0xc
	v_mov_b32_dpp v237, v209 row_shr:8 row_mask:0xf bank_mask:0xc
	v_mov_b32_dpp v238, v210 row_shr:8 row_mask:0xf bank_mask:0xc
	v_mov_b32_dpp v239, v211 row_shr:8 row_mask:0xf bank_mask:0xc
	v_mov_b32_dpp v240, v216 row_shr:8 row_mask:0xf bank_mask:0xc
	v_mov_b32_dpp v241, v217 row_shr:8 row_mask:0xf bank_mask:0xc
	v_mov_b32_dpp v242, v218 row_shr:8 row_mask:0xf bank_mask:0xc
	v_mov_b32_dpp v243, v219 row_shr:8 row_mask:0xf bank_mask:0xc
	v_mov_b32_dpp v208, v204 row_shl:8 row_mask:0xf bank_mask:0x3
	v_mov_b32_dpp v209, v205 row_shl:8 row_mask:0xf bank_mask:0x3
	v_mov_b32_dpp v210, v206 row_shl:8 row_mask:0xf bank_mask:0x3
	v_mov_b32_dpp v211, v207 row_shl:8 row_mask:0xf bank_mask:0x3
	v_mov_b32_dpp v216, v212 row_shl:8 row_mask:0xf bank_mask:0x3
	v_mov_b32_dpp v217, v213 row_shl:8 row_mask:0xf bank_mask:0x3
	v_mov_b32_dpp v218, v214 row_shl:8 row_mask:0xf bank_mask:0x3
	v_mov_b32_dpp v219, v215 row_shl:8 row_mask:0xf bank_mask:0x3
	v_mfma_f32_16x16x32_bf16 v[4:7], v[236:239], v[240:243], v[4:7]
	s_nop 0
	v_mfma_f32_16x16x32_bf16 v[0:3], v[208:211], v[216:219], v[0:3]
	s_waitcnt vmcnt(20)
; __device__ __forceinline__ f32x4 skinny16(const bf16_t* A, int lda, const bf16_t* Bt, int ldb, int K, int lane) {
;     ...
;     for (int k = 0; k < K / 32; k += 16) {
;         bf16x8 a[16], b[16];
; #pragma unroll
;         for (int i = 0; i < 16; ++i) { a[i] = ap[(k + i) * 4]; b[i] = bp[(k + i) * 4]; }
; #pragma unroll
;         for (int i = 0; i < 16; i += 2) { acc0 = __builtin_amdgcn_mfma_f32_16x16x32_bf16(a[i], b[i], acc0, 0, 0, 0); acc1 = __builtin_amdgcn_mfma_f32_16x16x32_bf16(a[i + 1], b[i + 1], acc1, 0, 0, 0); }
	v_mov_b32_e32 v236, v220
	v_mov_b32_e32 v237, v221
	v_mov_b32_e32 v238, v222
	v_mov_b32_e32 v239, v223
	v_mov_b32_e32 v240, v228
	v_mov_b32_e32 v241, v229
	v_mov_b32_e32 v242, v230
	v_mov_b32_e32 v243, v231
	v_mov_b32_dpp v236, v224 row_shr:8 row_mask:0xf bank_mask:0xc
	v_mov_b32_dpp v237, v225 row_shr:8 row_mask:0xf bank_mask:0xc
	v_mov_b32_dpp v238, v226 row_shr:8 row_mask:0xf bank_mask:0xc
	v_mov_b32_dpp v239, v227 row_shr:8 row_mask:0xf bank_mask:0xc
	v_mov_b32_dpp v240, v232 row_shr:8 row_mask:0xf bank_mask:0xc
	v_mov_b32_dpp v241, v233 row_shr:8 row_mask:0xf bank_mask:0xc
	v_mov_b32_dpp v242, v234 row_shr:8 row_mask:0xf bank_mask:0xc
	v_mov_b32_dpp v243, v235 row_shr:8 row_mask:0xf bank_mask:0xc
	v_mov_b32_dpp v224, v220 row_shl:8 row_mask:0xf bank_mask:0x3
	v_mov_b32_dpp v225, v221 row_shl:8 row_mask:0xf bank_mask:0x3
	v_mov_b32_dpp v226, v222 row_shl:8 row_mask:0xf bank_mask:0x3
	v_mov_b32_dpp v227, v223 row_shl:8 row_mask:0xf bank_mask:0x3
	v_mov_b32_dpp v232, v228 row_shl:8 row_mask:0xf bank_mask:0x3
	v_mov_b32_dpp v233, v229 row_shl:8 row_mask:0xf bank_mask:0x3
	v_mov_b32_dpp v234, v230 row_shl:8 row_mask:0xf bank_mask:0x3
	v_mov_b32_dpp v235, v231 row_shl:8 row_mask:0xf bank_mask:0x3
	v_mfma_f32_16x16x32_bf16 v[4:7], v[236:239], v[240:243], v[4:7]
	s_nop 0
	v_mfma_f32_16x16x32_bf16 v[0:3], v[224:227], v[232:235], v[0:3]
	s_waitcnt vmcnt(16)
	v_mov_b32_e32 v236, v68
	v_mov_b32_e32 v237, v69
	v_mov_b32_e32 v238, v70
	v_mov_b32_e32 v239, v71
	v_mov_b32_e32 v240, v76
	v_mov_b32_e32 v241, v77
	v_mov_b32_e32 v242, v78
	v_mov_b32_e32 v243, v79
	v_mov_b32_dpp v236, v72 row_shr:8 row_mask:0xf bank_mask:0xc
	v_mov_b32_dpp v237, v73 row_shr:8 row_mask:0xf bank_mask:0xc
	v_mov_b32_dpp v238, v74 row_shr:8 row_mask:0xf bank_mask:0xc
	v_mov_b32_dpp v239, v75 row_shr:8 row_mask:0xf bank_mask:0xc
	v_mov_b32_dpp v240, v80 row_shr:8 row_mask:0xf bank_mask:0xc
	v_mov_b32_dpp v241, v81 row_shr:8 row_mask:0xf bank_mask:0xc
	v_mov_b32_dpp v242, v82 row_shr:8 row_mask:0xf bank_mask:0xc
	v_mov_b32_dpp v243, v83 row_shr:8 row_mask:0xf bank_mask:0xc
	v_mov_b32_dpp v72, v68 row_shl:8 row_mask:0xf bank_mask:0x3
	v_mov_b32_dpp v73, v69 row_shl:8 row_mask:0xf bank_mask:0x3
	v_mov_b32_dpp v74, v70 row_shl:8 row_mask:0xf bank_mask:0x3
	v_mov_b32_dpp v75, v71 row_shl:8 row_mask:0xf bank_mask:0x3
	v_mov_b32_dpp v80, v76 row_shl:8 row_mask:0xf bank_mask:0x3
	v_mov_b32_dpp v81, v77 row_shl:8 row_mask:0xf bank_mask:0x3
	v_mov_b32_dpp v82, v78 row_shl:8 row_mask:0xf bank_mask:0x3
	v_mov_b32_dpp v83, v79 row_shl:8 row_mask:0xf bank_mask:0x3
	v_mfma_f32_16x16x32_bf16 v[4:7], v[236:239], v[240:243], v[4:7]
	s_nop 0
	v_mfma_f32_16x16x32_bf16 v[0:3], v[72:75], v[80:83], v[0:3]
	s_waitcnt vmcnt(12)
	v_mov_b32_e32 v236, v84
	v_mov_b32_e32 v237, v85
	v_mov_b32_e32 v238, v86
	v_mov_b32_e32 v239, v87
	v_mov_b32_e32 v240, v92
	v_mov_b32_e32 v241, v93
	v_mov_b32_e32 v242, v94
	v_mov_b32_e32 v243, v95
	v_mov_b32_dpp v236, v88 row_shr:8 row_mask:0xf bank_mask:0xc
	v_mov_b32_dpp v237, v89 row_shr:8 row_mask:0xf bank_mask:0xc
	v_mov_b32_dpp v238, v90 row_shr:8 row_mask:0xf bank_mask:0xc
	v_mov_b32_dpp v239, v91 row_shr:8 row_mask:0xf bank_mask:0xc
	v_mov_b32_dpp v240, v96 row_shr:8 row_mask:0xf bank_mask:0xc
	v_mov_b32_dpp v241, v97 row_shr:8 row_mask:0xf bank_mask:0xc
	v_mov_b32_dpp v242, v98 row_shr:8 row_mask:0xf bank_mask:0xc
	v_mov_b32_dpp v243, v99 row_shr:8 row_mask:0xf bank_mask:0xc
	v_mov_b32_dpp v88, v84 row_shl:8 row_mask:0xf bank_mask:0x3
	v_mov_b32_dpp v89, v85 row_shl:8 row_mask:0xf bank_mask:0x3
	v_mov_b32_dpp v90, v86 row_shl:8 row_mask:0xf bank_mask:0x3
	v_mov_b32_dpp v91, v87 row_shl:8 row_mask:0xf bank_mask:0x3
	v_mov_b32_dpp v96, v92 row_shl:8 row_mask:0xf bank_mask:0x3
	v_mov_b32_dpp v97, v93 row_shl:8 row_mask:0xf bank_mask:0x3
	v_mov_b32_dpp v98, v94 row_shl:8 row_mask:0xf bank_mask:0x3
	v_mov_b32_dpp v99, v95 row_shl:8 row_mask:0xf bank_mask:0x3
	v_mfma_f32_16x16x32_bf16 v[4:7], v[236:239], v[240:243], v[4:7]
	s_nop 0
	v_mfma_f32_16x16x32_bf16 v[0:3], v[88:91], v[96:99], v[0:3]
	s_waitcnt vmcnt(8)
; __device__ __forceinline__ f32x4 skinny16(const bf16_t* A, int lda, const bf16_t* Bt, int ldb, int K, int lane) {
;     ...
;     for (int k = 0; k < K / 32; k += 16) {
;         bf16x8 a[16], b[16];
; #pragma unroll
;         for (int i = 0; i < 16; ++i) { a[i] = ap[(k + i) * 4]; b[i] = bp[(k + i) * 4]; }
; #pragma unroll
;         for (int i = 0; i < 16; i += 2) { acc0 = __builtin_amdgcn_mfma_f32_16x16x32_bf16(a[i], b[i], acc0, 0, 0, 0); acc1 = __builtin_amdgcn_mfma_f32_16x16x32_bf16(a[i + 1], b[i + 1], acc1, 0, 0, 0); }
;     }
;     return acc0 + acc1;
; }
; __global__ void __launch_bounds__(512, 2) mega(Args a) {
;     ...
;                 if (task < 8) { const int mt = task;
;                     const f32x4 acc = skinny16(hb + (size_t)(MP + mt * 16) * DM, DM, Wi + (size_t)NZ * DM, DM, DM, lane);
; #pragma unroll
;                     for (int j = 0; j < 4; ++j) zs[(size_t)(mt * 16 + q8 * 4 + j) * DINP + NZ + r] = acc[j];
	v_mov_b32_e32 v236, v100
	v_mov_b32_e32 v237, v101
	v_mov_b32_e32 v238, v102
	v_mov_b32_e32 v239, v103
	v_mov_b32_e32 v240, v108
	v_mov_b32_e32 v241, v109
	v_mov_b32_e32 v242, v110
	v_mov_b32_e32 v243, v111
	v_mov_b32_dpp v236, v104 row_shr:8 row_mask:0xf bank_mask:0xc
	v_mov_b32_dpp v237, v105 row_shr:8 row_mask:0xf bank_mask:0xc
	v_mov_b32_dpp v238, v106 row_shr:8 row_mask:0xf bank_mask:0xc
	v_mov_b32_dpp v239, v107 row_shr:8 row_mask:0xf bank_mask:0xc
	v_mov_b32_dpp v240, v112 row_shr:8 row_mask:0xf bank_mask:0xc
	v_mov_b32_dpp v241, v113 row_shr:8 row_mask:0xf bank_mask:0xc
	v_mov_b32_dpp v242, v114 row_shr:8 row_mask:0xf bank_mask:0xc
	v_mov_b32_dpp v243, v115 row_shr:8 row_mask:0xf bank_mask:0xc
	v_mov_b32_dpp v104, v100 row_shl:8 row_mask:0xf bank_mask:0x3
	v_mov_b32_dpp v105, v101 row_shl:8 row_mask:0xf bank_mask:0x3
	v_mov_b32_dpp v106, v102 row_shl:8 row_mask:0xf bank_mask:0x3
	v_mov_b32_dpp v107, v103 row_shl:8 row_mask:0xf bank_mask:0x3
	v_mov_b32_dpp v112, v108 row_shl:8 row_mask:0xf bank_mask:0x3
	v_mov_b32_dpp v113, v109 row_shl:8 row_mask:0xf bank_mask:0x3
	v_mov_b32_dpp v114, v110 row_shl:8 row_mask:0xf bank_mask:0x3
	v_mov_b32_dpp v115, v111 row_shl:8 row_mask:0xf bank_mask:0x3
	v_mfma_f32_16x16x32_bf16 v[4:7], v[236:239], v[240:243], v[4:7]
	s_nop 0
	v_mfma_f32_16x16x32_bf16 v[0:3], v[104:107], v[112:115], v[0:3]
	s_waitcnt vmcnt(4)
	v_mov_b32_e32 v236, v116
	v_mov_b32_e32 v237, v117
	v_mov_b32_e32 v238, v118
	v_mov_b32_e32 v239, v119
	v_mov_b32_e32 v240, v124
	v_mov_b32_e32 v241, v125
	v_mov_b32_e32 v242, v126
	v_mov_b32_e32 v243, v127
	v_mov_b32_dpp v236, v120 row_shr:8 row_mask:0xf bank_mask:0xc
	v_mov_b32_dpp v237, v121 row_shr:8 row_mask:0xf bank_mask:0xc
	v_mov_b32_dpp v238, v122 row_shr:8 row_mask:0xf bank_mask:0xc
	v_mov_b32_dpp v239, v123 row_shr:8 row_mask:0xf bank_mask:0xc
	v_mov_b32_dpp v240, v128 row_shr:8 row_mask:0xf bank_mask:0xc
	v_mov_b32_dpp v241, v129 row_shr:8 row_mask:0xf bank_mask:0xc
	v_mov_b32_dpp v242, v130 row_shr:8 row_mask:0xf bank_mask:0xc
	v_mov_b32_dpp v243, v131 row_shr:8 row_mask:0xf bank_mask:0xc
	v_mov_b32_dpp v120, v116 row_shl:8 row_mask:0xf bank_mask:0x3
	v_mov_b32_dpp v121, v117 row_shl:8 row_mask:0xf bank_mask:0x3
	v_mov_b32_dpp v122, v118 row_shl:8 row_mask:0xf bank_mask:0x3
	v_mov_b32_dpp v123, v119 row_shl:8 row_mask:0xf bank_mask:0x3
	v_mov_b32_dpp v128, v124 row_shl:8 row_mask:0xf bank_mask:0x3
	v_mov_b32_dpp v129, v125 row_shl:8 row_mask:0xf bank_mask:0x3
	v_mov_b32_dpp v130, v126 row_shl:8 row_mask:0xf bank_mask:0x3
	v_mov_b32_dpp v131, v127 row_shl:8 row_mask:0xf bank_mask:0x3
	v_mfma_f32_16x16x32_bf16 v[4:7], v[236:239], v[240:243], v[4:7]
	s_nop 0
	v_mfma_f32_16x16x32_bf16 v[0:3], v[120:123], v[128:131], v[0:3]
	s_waitcnt vmcnt(0)
	v_mov_b32_e32 v236, v132
	v_mov_b32_e32 v237, v133
	v_mov_b32_e32 v238, v134
	v_mov_b32_e32 v239, v135
	v_mov_b32_e32 v240, v140
	v_mov_b32_e32 v241, v141
	v_mov_b32_e32 v242, v142
	v_mov_b32_e32 v243, v143
	v_mov_b32_dpp v236, v136 row_shr:8 row_mask:0xf bank_mask:0xc
	v_mov_b32_dpp v237, v137 row_shr:8 row_mask:0xf bank_mask:0xc
	v_mov_b32_dpp v238, v138 row_shr:8 row_mask:0xf bank_mask:0xc
	v_mov_b32_dpp v239, v139 row_shr:8 row_mask:0xf bank_mask:0xc
	v_mov_b32_dpp v240, v144 row_shr:8 row_mask:0xf bank_mask:0xc
	v_mov_b32_dpp v241, v145 row_shr:8 row_mask:0xf bank_mask:0xc
	v_mov_b32_dpp v242, v146 row_shr:8 row_mask:0xf bank_mask:0xc
	v_mov_b32_dpp v243, v147 row_shr:8 row_mask:0xf bank_mask:0xc
	v_mov_b32_dpp v136, v132 row_shl:8 row_mask:0xf bank_mask:0x3
	v_mov_b32_dpp v137, v133 row_shl:8 row_mask:0xf bank_mask:0x3
	v_mov_b32_dpp v138, v134 row_shl:8 row_mask:0xf bank_mask:0x3
	v_mov_b32_dpp v139, v135 row_shl:8 row_mask:0xf bank_mask:0x3
	v_mov_b32_dpp v144, v140 row_shl:8 row_mask:0xf bank_mask:0x3
	v_mov_b32_dpp v145, v141 row_shl:8 row_mask:0xf bank_mask:0x3
	v_mov_b32_dpp v146, v142 row_shl:8 row_mask:0xf bank_mask:0x3
	v_mov_b32_dpp v147, v143 row_shl:8 row_mask:0xf bank_mask:0x3
	v_mfma_f32_16x16x32_bf16 v[4:7], v[236:239], v[240:243], v[4:7]
	s_nop 0
	v_mfma_f32_16x16x32_bf16 v[0:3], v[136:139], v[144:147], v[0:3]
	s_nop 1
	s_nop 6
	v_pk_add_f32 v[2:3], v[6:7], v[2:3]
	v_lshl_or_b32 v6, s8, 4, v20
	v_pk_add_f32 v[0:1], v[4:5], v[0:1]
	v_mad_i64_i32 v[4:5], s[6:7], v6, s80, v[158:159]
	v_lshl_add_u64 v[4:5], v[4:5], 0, v[152:153]
	v_add_co_u32_e32 v4, vcc, 0x8000, v4
	s_nop 1
	v_addc_co_u32_e32 v5, vcc, 0, v5, vcc
	global_store_dword v[4:5], v0, off
	v_or_b32_e32 v0, 1, v6
	v_mad_i64_i32 v[4:5], s[6:7], v0, s80, v[158:159]
	v_lshl_add_u64 v[4:5], v[4:5], 0, v[152:153]
	v_add_co_u32_e32 v4, vcc, 0x8000, v4
	v_or_b32_e32 v0, 2, v6
	s_nop 0
	v_addc_co_u32_e32 v5, vcc, 0, v5, vcc
	global_store_dword v[4:5], v1, off
	v_mad_i64_i32 v[0:1], s[6:7], v0, s80, v[158:159]
	v_lshl_add_u64 v[0:1], v[0:1], 0, v[152:153]
	v_add_co_u32_e32 v0, vcc, 0x8000, v0
	s_nop 1
	v_addc_co_u32_e32 v1, vcc, 0, v1, vcc
	global_store_dword v[0:1], v2, off
	v_or_b32_e32 v0, 3, v6
	v_mad_i64_i32 v[0:1], s[6:7], v0, s80, v[158:159]
	v_lshl_add_u64 v[0:1], v[0:1], 0, v[152:153]
	v_add_co_u32_e32 v0, vcc, 0x8000, v0
	s_nop 1
	v_addc_co_u32_e32 v1, vcc, 0, v1, vcc
	global_store_dword v[0:1], v3, off
	s_branch .LBB0_360

; __device__ __forceinline__ f32x4 skinny16(const bf16_t* A, int lda, const bf16_t* Bt, int ldb, int K, int lane) {
;     ...
;     for (int k = 0; k < K / 32; k += 16) {
;         bf16x8 a[16], b[16];
; #pragma unroll
;         for (int i = 0; i < 16; ++i) { a[i] = ap[(k + i) * 4]; b[i] = bp[(k + i) * 4]; }
; #pragma unroll
;         for (int i = 0; i < 16; i += 2) { acc0 = __builtin_amdgcn_mfma_f32_16x16x32_bf16(a[i], b[i], acc0, 0, 0, 0); acc1 = __builtin_amdgcn_mfma_f32_16x16x32_bf16(a[i + 1], b[i + 1], acc1, 0, 0, 0); }
;     }
.LBB0_584:
	v_bfe_u32 v252, v14, 3, 1
	v_mul_u32_u24_e32 v252, 0x7fc0, v252
	v_sub_u32_e32 v252, 0, v252
	v_ashrrev_i32_e32 v253, 31, v252
	v_lshl_add_u64 v[244:245], v[12:13], 0, v[252:253]
	v_lshl_add_u64 v[248:249], v[10:11], 0, v[252:253]
	v_mov_b32_e32 v252, 0x8000
	v_mov_b32_e32 v253, 0
	v_lshl_add_u64 v[246:247], v[244:245], 0, v[252:253]
	v_lshl_add_u64 v[250:251], v[248:249], 0, v[252:253]
	global_load_dwordx4 v[68:71], v[244:245], off offset:-512
	global_load_dwordx4 v[72:75], v[246:247], off offset:-512
	global_load_dwordx4 v[76:79], v[248:249], off offset:-960
	global_load_dwordx4 v[80:83], v[250:251], off offset:-960
	global_load_dwordx4 v[84:87], v[244:245], off offset:-384
	global_load_dwordx4 v[88:91], v[246:247], off offset:-384
	global_load_dwordx4 v[92:95], v[248:249], off offset:-832
	global_load_dwordx4 v[96:99], v[250:251], off offset:-832
	global_load_dwordx4 v[100:103], v[244:245], off offset:-256
	global_load_dwordx4 v[104:107], v[246:247], off offset:-256
	global_load_dwordx4 v[108:111], v[248:249], off offset:-704
	global_load_dwordx4 v[112:115], v[250:251], off offset:-704
	global_load_dwordx4 v[116:119], v[244:245], off offset:-128
	global_load_dwordx4 v[120:123], v[246:247], off offset:-128
	global_load_dwordx4 v[124:127], v[248:249], off offset:-576
	global_load_dwordx4 v[128:131], v[250:251], off offset:-576
	global_load_dwordx4 v[132:135], v[244:245], off offset:0
	global_load_dwordx4 v[136:139], v[246:247], off offset:0
	global_load_dwordx4 v[140:143], v[248:249], off offset:-448
	global_load_dwordx4 v[144:147], v[250:251], off offset:-448
	global_load_dwordx4 v[148:151], v[244:245], off offset:128
	global_load_dwordx4 v[164:167], v[246:247], off offset:128
	global_load_dwordx4 v[168:171], v[248:249], off offset:-320
	global_load_dwordx4 v[172:175], v[250:251], off offset:-320
	global_load_dwordx4 v[176:179], v[244:245], off offset:256
	global_load_dwordx4 v[180:183], v[246:247], off offset:256
	global_load_dwordx4 v[184:187], v[248:249], off offset:-192
	global_load_dwordx4 v[188:191], v[250:251], off offset:-192
	global_load_dwordx4 v[204:207], v[244:245], off offset:384
	global_load_dwordx4 v[208:211], v[246:247], off offset:384
	global_load_dwordx4 v[212:215], v[248:249], off offset:-64
	global_load_dwordx4 v[216:219], v[250:251], off offset:-64
	global_load_dwordx4 v[220:223], v[244:245], off offset:512
	global_load_dwordx4 v[224:227], v[246:247], off offset:512
	global_load_dwordx4 v[228:231], v[248:249], off offset:64
	global_load_dwordx4 v[232:235], v[250:251], off offset:64
	s_waitcnt vmcnt(32)
	v_mov_b32_e32 v236, v68
	v_mov_b32_e32 v237, v69
	v_mov_b32_e32 v238, v70
	v_mov_b32_e32 v239, v71
	v_mov_b32_e32 v240, v76
	v_mov_b32_e32 v241, v77
	v_mov_b32_e32 v242, v78
	v_mov_b32_e32 v243, v79
	v_mov_b32_dpp v236, v72 row_shr:8 row_mask:0xf bank_mask:0xc
	v_mov_b32_dpp v237, v73 row_shr:8 row_mask:0xf bank_mask:0xc
	v_mov_b32_dpp v238, v74 row_shr:8 row_mask:0xf bank_mask:0xc
	v_mov_b32_dpp v239, v75 row_shr:8 row_mask:0xf bank_mask:0xc
	v_mov_b32_dpp v240, v80 row_shr:8 row_mask:0xf bank_mask:0xc
	v_mov_b32_dpp v241, v81 row_shr:8 row_mask:0xf bank_mask:0xc
	v_mov_b32_dpp v242, v82 row_shr:8 row_mask:0xf bank_mask:0xc
	v_mov_b32_dpp v243, v83 row_shr:8 row_mask:0xf bank_mask:0xc
	v_mov_b32_dpp v72, v68 row_shl:8 row_mask:0xf bank_mask:0x3
	v_mov_b32_dpp v73, v69 row_shl:8 row_mask:0xf bank_mask:0x3
	v_mov_b32_dpp v74, v70 row_shl:8 row_mask:0xf bank_mask:0x3
	v_mov_b32_dpp v75, v71 row_shl:8 row_mask:0xf bank_mask:0x3
	v_mov_b32_dpp v80, v76 row_shl:8 row_mask:0xf bank_mask:0x3
	v_mov_b32_dpp v81, v77 row_shl:8 row_mask:0xf bank_mask:0x3
	v_mov_b32_dpp v82, v78 row_shl:8 row_mask:0xf bank_mask:0x3
	v_mov_b32_dpp v83, v79 row_shl:8 row_mask:0xf bank_mask:0x3
	v_mfma_f32_16x16x32_bf16 v[4:7], v[236:239], v[240:243], v[4:7]
	s_nop 0
	v_mfma_f32_16x16x32_bf16 v[0:3], v[72:75], v[80:83], v[0:3]
	global_load_dwordx4 v[68:71], v[244:245], off offset:640
	global_load_dwordx4 v[72:75], v[246:247], off offset:640
	global_load_dwordx4 v[76:79], v[248:249], off offset:192
	global_load_dwordx4 v[80:83], v[250:251], off offset:192
	s_waitcnt vmcnt(32)
	v_mov_b32_e32 v236, v84
	v_mov_b32_e32 v237, v85
	v_mov_b32_e32 v238, v86
	v_mov_b32_e32 v239, v87
	v_mov_b32_e32 v240, v92
	v_mov_b32_e32 v241, v93
	v_mov_b32_e32 v242, v94
	v_mov_b32_e32 v243, v95
	v_mov_b32_dpp v236, v88 row_shr:8 row_mask:0xf bank_mask:0xc
	v_mov_b32_dpp v237, v89 row_shr:8 row_mask:0xf bank_mask:0xc
	v_mov_b32_dpp v238, v90 row_shr:8 row_mask:0xf bank_mask:0xc
	v_mov_b32_dpp v239, v91 row_shr:8 row_mask:0xf bank_mask:0xc
	v_mov_b32_dpp v240, v96 row_shr:8 row_mask:0xf bank_mask:0xc
	v_mov_b32_dpp v241, v97 row_shr:8 row_mask:0xf bank_mask:0xc
	v_mov_b32_dpp v242, v98 row_shr:8 row_mask:0xf bank_mask:0xc
	v_mov_b32_dpp v243, v99 row_shr:8 row_mask:0xf bank_mask:0xc
	v_mov_b32_dpp v88, v84 row_shl:8 row_mask:0xf bank_mask:0x3
	v_mov_b32_dpp v89, v85 row_shl:8 row_mask:0xf bank_mask:0x3
	v_mov_b32_dpp v90, v86 row_shl:8 row_mask:0xf bank_mask:0x3
	v_mov_b32_dpp v91, v87 row_shl:8 row_mask:0xf bank_mask:0x3
	v_mov_b32_dpp v96, v92 row_shl:8 row_mask:0xf bank_mask:0x3
	v_mov_b32_dpp v97, v93 row_shl:8 row_mask:0xf bank_mask:0x3
	v_mov_b32_dpp v98, v94 row_shl:8 row_mask:0xf bank_mask:0x3
	v_mov_b32_dpp v99, v95 row_shl:8 row_mask:0xf bank_mask:0x3
	v_mfma_f32_16x16x32_bf16 v[4:7], v[236:239], v[240:243], v[4:7]
	s_nop 0
	v_mfma_f32_16x16x32_bf16 v[0:3], v[88:91], v[96:99], v[0:3]
	global_load_dwordx4 v[84:87], v[244:245], off offset:768
	global_load_dwordx4 v[88:91], v[246:247], off offset:768
	global_load_dwordx4 v[92:95], v[248:249], off offset:320
	global_load_dwordx4 v[96:99], v[250:251], off offset:320
	s_waitcnt vmcnt(32)
; __device__ __forceinline__ f32x4 skinny16(const bf16_t* A, int lda, const bf16_t* Bt, int ldb, int K, int lane) {
;     ...
;     for (int k = 0; k < K / 32; k += 16) {
;         bf16x8 a[16], b[16];
; #pragma unroll
;         for (int i = 0; i < 16; ++i) { a[i] = ap[(k + i) * 4]; b[i] = bp[(k + i) * 4]; }
; #pragma unroll
;         for (int i = 0; i < 16; i += 2) { acc0 = __builtin_amdgcn_mfma_f32_16x16x32_bf16(a[i], b[i], acc0, 0, 0, 0); acc1 = __builtin_amdgcn_mfma_f32_16x16x32_bf16(a[i + 1], b[i + 1], acc1, 0, 0, 0); }
;     }
	v_mov_b32_e32 v236, v100
	v_mov_b32_e32 v237, v101
	v_mov_b32_e32 v238, v102
	v_mov_b32_e32 v239, v103
	v_mov_b32_e32 v240, v108
	v_mov_b32_e32 v241, v109
	v_mov_b32_e32 v242, v110
	v_mov_b32_e32 v243, v111
	v_mov_b32_dpp v236, v104 row_shr:8 row_mask:0xf bank_mask:0xc
	v_mov_b32_dpp v237, v105 row_shr:8 row_mask:0xf bank_mask:0xc
	v_mov_b32_dpp v238, v106 row_shr:8 row_mask:0xf bank_mask:0xc
	v_mov_b32_dpp v239, v107 row_shr:8 row_mask:0xf bank_mask:0xc
	v_mov_b32_dpp v240, v112 row_shr:8 row_mask:0xf bank_mask:0xc
	v_mov_b32_dpp v241, v113 row_shr:8 row_mask:0xf bank_mask:0xc
	v_mov_b32_dpp v242, v114 row_shr:8 row_mask:0xf bank_mask:0xc
	v_mov_b32_dpp v243, v115 row_shr:8 row_mask:0xf bank_mask:0xc
	v_mov_b32_dpp v104, v100 row_shl:8 row_mask:0xf bank_mask:0x3
	v_mov_b32_dpp v105, v101 row_shl:8 row_mask:0xf bank_mask:0x3
	v_mov_b32_dpp v106, v102 row_shl:8 row_mask:0xf bank_mask:0x3
	v_mov_b32_dpp v107, v103 row_shl:8 row_mask:0xf bank_mask:0x3
	v_mov_b32_dpp v112, v108 row_shl:8 row_mask:0xf bank_mask:0x3
	v_mov_b32_dpp v113, v109 row_shl:8 row_mask:0xf bank_mask:0x3
	v_mov_b32_dpp v114, v110 row_shl:8 row_mask:0xf bank_mask:0x3
	v_mov_b32_dpp v115, v111 row_shl:8 row_mask:0xf bank_mask:0x3
	v_mfma_f32_16x16x32_bf16 v[4:7], v[236:239], v[240:243], v[4:7]
	s_nop 0
	v_mfma_f32_16x16x32_bf16 v[0:3], v[104:107], v[112:115], v[0:3]
	global_load_dwordx4 v[100:103], v[244:245], off offset:896
	global_load_dwordx4 v[104:107], v[246:247], off offset:896
	global_load_dwordx4 v[108:111], v[248:249], off offset:448
	global_load_dwordx4 v[112:115], v[250:251], off offset:448
	s_waitcnt vmcnt(32)
	v_mov_b32_e32 v236, v116
	v_mov_b32_e32 v237, v117
	v_mov_b32_e32 v238, v118
	v_mov_b32_e32 v239, v119
	v_mov_b32_e32 v240, v124
	v_mov_b32_e32 v241, v125
	v_mov_b32_e32 v242, v126
	v_mov_b32_e32 v243, v127
	v_mov_b32_dpp v236, v120 row_shr:8 row_mask:0xf bank_mask:0xc
	v_mov_b32_dpp v237, v121 row_shr:8 row_mask:0xf bank_mask:0xc
	v_mov_b32_dpp v238, v122 row_shr:8 row_mask:0xf bank_mask:0xc
	v_mov_b32_dpp v239, v123 row_shr:8 row_mask:0xf bank_mask:0xc
	v_mov_b32_dpp v240, v128 row_shr:8 row_mask:0xf bank_mask:0xc
	v_mov_b32_dpp v241, v129 row_shr:8 row_mask:0xf bank_mask:0xc
	v_mov_b32_dpp v242, v130 row_shr:8 row_mask:0xf bank_mask:0xc
	v_mov_b32_dpp v243, v131 row_shr:8 row_mask:0xf bank_mask:0xc
	v_mov_b32_dpp v120, v116 row_shl:8 row_mask:0xf bank_mask:0x3
	v_mov_b32_dpp v121, v117 row_shl:8 row_mask:0xf bank_mask:0x3
	v_mov_b32_dpp v122, v118 row_shl:8 row_mask:0xf bank_mask:0x3
	v_mov_b32_dpp v123, v119 row_shl:8 row_mask:0xf bank_mask:0x3
	v_mov_b32_dpp v128, v124 row_shl:8 row_mask:0xf bank_mask:0x3
	v_mov_b32_dpp v129, v125 row_shl:8 row_mask:0xf bank_mask:0x3
	v_mov_b32_dpp v130, v126 row_shl:8 row_mask:0xf bank_mask:0x3
	v_mov_b32_dpp v131, v127 row_shl:8 row_mask:0xf bank_mask:0x3
	v_mfma_f32_16x16x32_bf16 v[4:7], v[236:239], v[240:243], v[4:7]
	s_nop 0
	v_mfma_f32_16x16x32_bf16 v[0:3], v[120:123], v[128:131], v[0:3]
	global_load_dwordx4 v[116:119], v[244:245], off offset:1024
	global_load_dwordx4 v[120:123], v[246:247], off offset:1024
	global_load_dwordx4 v[124:127], v[248:249], off offset:576
	global_load_dwordx4 v[128:131], v[250:251], off offset:576
	s_waitcnt vmcnt(32)
	v_mov_b32_e32 v236, v132
	v_mov_b32_e32 v237, v133
	v_mov_b32_e32 v238, v134
	v_mov_b32_e32 v239, v135
	v_mov_b32_e32 v240, v140
	v_mov_b32_e32 v241, v141
	v_mov_b32_e32 v242, v142
	v_mov_b32_e32 v243, v143
	v_mov_b32_dpp v236, v136 row_shr:8 row_mask:0xf bank_mask:0xc
	v_mov_b32_dpp v237, v137 row_shr:8 row_mask:0xf bank_mask:0xc
	v_mov_b32_dpp v238, v138 row_shr:8 row_mask:0xf bank_mask:0xc
	v_mov_b32_dpp v239, v139 row_shr:8 row_mask:0xf bank_mask:0xc
	v_mov_b32_dpp v240, v144 row_shr:8 row_mask:0xf bank_mask:0xc
	v_mov_b32_dpp v241, v145 row_shr:8 row_mask:0xf bank_mask:0xc
	v_mov_b32_dpp v242, v146 row_shr:8 row_mask:0xf bank_mask:0xc
	v_mov_b32_dpp v243, v147 row_shr:8 row_mask:0xf bank_mask:0xc
	v_mov_b32_dpp v136, v132 row_shl:8 row_mask:0xf bank_mask:0x3
	v_mov_b32_dpp v137, v133 row_shl:8 row_mask:0xf bank_mask:0x3
	v_mov_b32_dpp v138, v134 row_shl:8 row_mask:0xf bank_mask:0x3
	v_mov_b32_dpp v139, v135 row_shl:8 row_mask:0xf bank_mask:0x3
	v_mov_b32_dpp v144, v140 row_shl:8 row_mask:0xf bank_mask:0x3
	v_mov_b32_dpp v145, v141 row_shl:8 row_mask:0xf bank_mask:0x3
	v_mov_b32_dpp v146, v142 row_shl:8 row_mask:0xf bank_mask:0x3
	v_mov_b32_dpp v147, v143 row_shl:8 row_mask:0xf bank_mask:0x3
	v_mfma_f32_16x16x32_bf16 v[4:7], v[236:239], v[240:243], v[4:7]
	s_nop 0
	v_mfma_f32_16x16x32_bf16 v[0:3], v[136:139], v[144:147], v[0:3]
	global_load_dwordx4 v[132:135], v[244:245], off offset:1152
	global_load_dwordx4 v[136:139], v[246:247], off offset:1152
	global_load_dwordx4 v[140:143], v[248:249], off offset:704
	global_load_dwordx4 v[144:147], v[250:251], off offset:704
	s_waitcnt vmcnt(32)
; __device__ __forceinline__ f32x4 skinny16(const bf16_t* A, int lda, const bf16_t* Bt, int ldb, int K, int lane) {
;     ...
;     for (int k = 0; k < K / 32; k += 16) {
;         bf16x8 a[16], b[16];
; #pragma unroll
;         for (int i = 0; i < 16; ++i) { a[i] = ap[(k + i) * 4]; b[i] = bp[(k + i) * 4]; }
; #pragma unroll
;         for (int i = 0; i < 16; i += 2) { acc0 = __builtin_amdgcn_mfma_f32_16x16x32_bf16(a[i], b[i], acc0, 0, 0, 0); acc1 = __builtin_amdgcn_mfma_f32_16x16x32_bf16(a[i + 1], b[i + 1], acc1, 0, 0, 0); }
;     }
	v_mov_b32_e32 v236, v148
	v_mov_b32_e32 v237, v149
	v_mov_b32_e32 v238, v150
	v_mov_b32_e32 v239, v151
	v_mov_b32_e32 v240, v168
	v_mov_b32_e32 v241, v169
	v_mov_b32_e32 v242, v170
	v_mov_b32_e32 v243, v171
	v_mov_b32_dpp v236, v164 row_shr:8 row_mask:0xf bank_mask:0xc
	v_mov_b32_dpp v237, v165 row_shr:8 row_mask:0xf bank_mask:0xc
	v_mov_b32_dpp v238, v166 row_shr:8 row_mask:0xf bank_mask:0xc
	v_mov_b32_dpp v239, v167 row_shr:8 row_mask:0xf bank_mask:0xc
	v_mov_b32_dpp v240, v172 row_shr:8 row_mask:0xf bank_mask:0xc
	v_mov_b32_dpp v241, v173 row_shr:8 row_mask:0xf bank_mask:0xc
	v_mov_b32_dpp v242, v174 row_shr:8 row_mask:0xf bank_mask:0xc
	v_mov_b32_dpp v243, v175 row_shr:8 row_mask:0xf bank_mask:0xc
	v_mov_b32_dpp v164, v148 row_shl:8 row_mask:0xf bank_mask:0x3
	v_mov_b32_dpp v165, v149 row_shl:8 row_mask:0xf bank_mask:0x3
	v_mov_b32_dpp v166, v150 row_shl:8 row_mask:0xf bank_mask:0x3
	v_mov_b32_dpp v167, v151 row_shl:8 row_mask:0xf bank_mask:0x3
	v_mov_b32_dpp v172, v168 row_shl:8 row_mask:0xf bank_mask:0x3
	v_mov_b32_dpp v173, v169 row_shl:8 row_mask:0xf bank_mask:0x3
	v_mov_b32_dpp v174, v170 row_shl:8 row_mask:0xf bank_mask:0x3
	v_mov_b32_dpp v175, v171 row_shl:8 row_mask:0xf bank_mask:0x3
	v_mfma_f32_16x16x32_bf16 v[4:7], v[236:239], v[240:243], v[4:7]
	s_nop 0
	v_mfma_f32_16x16x32_bf16 v[0:3], v[164:167], v[172:175], v[0:3]
	global_load_dwordx4 v[148:151], v[244:245], off offset:1280
	global_load_dwordx4 v[164:167], v[246:247], off offset:1280
	global_load_dwordx4 v[168:171], v[248:249], off offset:832
	global_load_dwordx4 v[172:175], v[250:251], off offset:832
	s_waitcnt vmcnt(32)
	v_mov_b32_e32 v236, v176
	v_mov_b32_e32 v237, v177
	v_mov_b32_e32 v238, v178
	v_mov_b32_e32 v239, v179
	v_mov_b32_e32 v240, v184
	v_mov_b32_e32 v241, v185
	v_mov_b32_e32 v242, v186
	v_mov_b32_e32 v243, v187
	v_mov_b32_dpp v236, v180 row_shr:8 row_mask:0xf bank_mask:0xc
	v_mov_b32_dpp v237, v181 row_shr:8 row_mask:0xf bank_mask:0xc
	v_mov_b32_dpp v238, v182 row_shr:8 row_mask:0xf bank_mask:0xc
	v_mov_b32_dpp v239, v183 row_shr:8 row_mask:0xf bank_mask:0xc
	v_mov_b32_dpp v240, v188 row_shr:8 row_mask:0xf bank_mask:0xc
	v_mov_b32_dpp v241, v189 row_shr:8 row_mask:0xf bank_mask:0xc
	v_mov_b32_dpp v242, v190 row_shr:8 row_mask:0xf bank_mask:0xc
	v_mov_b32_dpp v243, v191 row_shr:8 row_mask:0xf bank_mask:0xc
	v_mov_b32_dpp v180, v176 row_shl:8 row_mask:0xf bank_mask:0x3
	v_mov_b32_dpp v181, v177 row_shl:8 row_mask:0xf bank_mask:0x3
	v_mov_b32_dpp v182, v178 row_shl:8 row_mask:0xf bank_mask:0x3
	v_mov_b32_dpp v183, v179 row_shl:8 row_mask:0xf bank_mask:0x3
	v_mov_b32_dpp v188, v184 row_shl:8 row_mask:0xf bank_mask:0x3
	v_mov_b32_dpp v189, v185 row_shl:8 row_mask:0xf bank_mask:0x3
	v_mov_b32_dpp v190, v186 row_shl:8 row_mask:0xf bank_mask:0x3
	v_mov_b32_dpp v191, v187 row_shl:8 row_mask:0xf bank_mask:0x3
	v_mfma_f32_16x16x32_bf16 v[4:7], v[236:239], v[240:243], v[4:7]
	s_nop 0
	v_mfma_f32_16x16x32_bf16 v[0:3], v[180:183], v[188:191], v[0:3]
	global_load_dwordx4 v[176:179], v[244:245], off offset:1408
	global_load_dwordx4 v[180:183], v[246:247], off offset:1408
	global_load_dwordx4 v[184:187], v[248:249], off offset:960
	global_load_dwordx4 v[188:191], v[250:251], off offset:960
	s_waitcnt vmcnt(32)
	v_mov_b32_e32 v236, v204
	v_mov_b32_e32 v237, v205
	v_mov_b32_e32 v238, v206
	v_mov_b32_e32 v239, v207
	v_mov_b32_e32 v240, v212
	v_mov_b32_e32 v241, v213
	v_mov_b32_e32 v242, v214
	v_mov_b32_e32 v243, v215
	v_mov_b32_dpp v236, v208 row_shr:8 row_mask:0xf bank_mask:0xc
	v_mov_b32_dpp v237, v209 row_shr:8 row_mask:0xf bank_mask:0xc
	v_mov_b32_dpp v238, v210 row_shr:8 row_mask:0xf bank_mask:0xc
	v_mov_b32_dpp v239, v211 row_shr:8 row_mask:0xf bank_mask:0xc
	v_mov_b32_dpp v240, v216 row_shr:8 row_mask:0xf bank_mask:0xc
	v_mov_b32_dpp v241, v217 row_shr:8 row_mask:0xf bank_mask:0xc
	v_mov_b32_dpp v242, v218 row_shr:8 row_mask:0xf bank_mask:0xc
	v_mov_b32_dpp v243, v219 row_shr:8 row_mask:0xf bank_mask:0xc
	v_mov_b32_dpp v208, v204 row_shl:8 row_mask:0xf bank_mask:0x3
	v_mov_b32_dpp v209, v205 row_shl:8 row_mask:0xf bank_mask:0x3
	v_mov_b32_dpp v210, v206 row_shl:8 row_mask:0xf bank_mask:0x3
	v_mov_b32_dpp v211, v207 row_shl:8 row_mask:0xf bank_mask:0x3
	v_mov_b32_dpp v216, v212 row_shl:8 row_mask:0xf bank_mask:0x3
	v_mov_b32_dpp v217, v213 row_shl:8 row_mask:0xf bank_mask:0x3
	v_mov_b32_dpp v218, v214 row_shl:8 row_mask:0xf bank_mask:0x3
	v_mov_b32_dpp v219, v215 row_shl:8 row_mask:0xf bank_mask:0x3
	v_mfma_f32_16x16x32_bf16 v[4:7], v[236:239], v[240:243], v[4:7]
	s_nop 0
	v_mfma_f32_16x16x32_bf16 v[0:3], v[208:211], v[216:219], v[0:3]
	global_load_dwordx4 v[204:207], v[244:245], off offset:1536
	global_load_dwordx4 v[208:211], v[246:247], off offset:1536
	global_load_dwordx4 v[212:215], v[248:249], off offset:1088
	global_load_dwordx4 v[216:219], v[250:251], off offset:1088
	s_waitcnt vmcnt(32)
; __device__ __forceinline__ f32x4 skinny16(const bf16_t* A, int lda, const bf16_t* Bt, int ldb, int K, int lane) {
;     ...
;     for (int k = 0; k < K / 32; k += 16) {
;         bf16x8 a[16], b[16];
; #pragma unroll
;         for (int i = 0; i < 16; ++i) { a[i] = ap[(k + i) * 4]; b[i] = bp[(k + i) * 4]; }
; #pragma unroll
;         for (int i = 0; i < 16; i += 2) { acc0 = __builtin_amdgcn_mfma_f32_16x16x32_bf16(a[i], b[i], acc0, 0, 0, 0); acc1 = __builtin_amdgcn_mfma_f32_16x16x32_bf16(a[i + 1], b[i + 1], acc1, 0, 0, 0); }
;     }
	v_mov_b32_e32 v236, v220
	v_mov_b32_e32 v237, v221
	v_mov_b32_e32 v238, v222
	v_mov_b32_e32 v239, v223
	v_mov_b32_e32 v240, v228
	v_mov_b32_e32 v241, v229
	v_mov_b32_e32 v242, v230
	v_mov_b32_e32 v243, v231
	v_mov_b32_dpp v236, v224 row_shr:8 row_mask:0xf bank_mask:0xc
	v_mov_b32_dpp v237, v225 row_shr:8 row_mask:0xf bank_mask:0xc
	v_mov_b32_dpp v238, v226 row_shr:8 row_mask:0xf bank_mask:0xc
	v_mov_b32_dpp v239, v227 row_shr:8 row_mask:0xf bank_mask:0xc
	v_mov_b32_dpp v240, v232 row_shr:8 row_mask:0xf bank_mask:0xc
	v_mov_b32_dpp v241, v233 row_shr:8 row_mask:0xf bank_mask:0xc
	v_mov_b32_dpp v242, v234 row_shr:8 row_mask:0xf bank_mask:0xc
	v_mov_b32_dpp v243, v235 row_shr:8 row_mask:0xf bank_mask:0xc
	v_mov_b32_dpp v224, v220 row_shl:8 row_mask:0xf bank_mask:0x3
	v_mov_b32_dpp v225, v221 row_shl:8 row_mask:0xf bank_mask:0x3
	v_mov_b32_dpp v226, v222 row_shl:8 row_mask:0xf bank_mask:0x3
	v_mov_b32_dpp v227, v223 row_shl:8 row_mask:0xf bank_mask:0x3
	v_mov_b32_dpp v232, v228 row_shl:8 row_mask:0xf bank_mask:0x3
	v_mov_b32_dpp v233, v229 row_shl:8 row_mask:0xf bank_mask:0x3
	v_mov_b32_dpp v234, v230 row_shl:8 row_mask:0xf bank_mask:0x3
	v_mov_b32_dpp v235, v231 row_shl:8 row_mask:0xf bank_mask:0x3
	v_mfma_f32_16x16x32_bf16 v[4:7], v[236:239], v[240:243], v[4:7]
	s_nop 0
	v_mfma_f32_16x16x32_bf16 v[0:3], v[224:227], v[232:235], v[0:3]
	global_load_dwordx4 v[220:223], v[244:245], off offset:1664
	global_load_dwordx4 v[224:227], v[246:247], off offset:1664
	global_load_dwordx4 v[228:231], v[248:249], off offset:1216
	global_load_dwordx4 v[232:235], v[250:251], off offset:1216
	s_waitcnt vmcnt(32)
	v_mov_b32_e32 v236, v68
	v_mov_b32_e32 v237, v69
	v_mov_b32_e32 v238, v70
	v_mov_b32_e32 v239, v71
	v_mov_b32_e32 v240, v76
	v_mov_b32_e32 v241, v77
	v_mov_b32_e32 v242, v78
	v_mov_b32_e32 v243, v79
	v_mov_b32_dpp v236, v72 row_shr:8 row_mask:0xf bank_mask:0xc
	v_mov_b32_dpp v237, v73 row_shr:8 row_mask:0xf bank_mask:0xc
	v_mov_b32_dpp v238, v74 row_shr:8 row_mask:0xf bank_mask:0xc
	v_mov_b32_dpp v239, v75 row_shr:8 row_mask:0xf bank_mask:0xc
	v_mov_b32_dpp v240, v80 row_shr:8 row_mask:0xf bank_mask:0xc
	v_mov_b32_dpp v241, v81 row_shr:8 row_mask:0xf bank_mask:0xc
	v_mov_b32_dpp v242, v82 row_shr:8 row_mask:0xf bank_mask:0xc
	v_mov_b32_dpp v243, v83 row_shr:8 row_mask:0xf bank_mask:0xc
	v_mov_b32_dpp v72, v68 row_shl:8 row_mask:0xf bank_mask:0x3
	v_mov_b32_dpp v73, v69 row_shl:8 row_mask:0xf bank_mask:0x3
	v_mov_b32_dpp v74, v70 row_shl:8 row_mask:0xf bank_mask:0x3
	v_mov_b32_dpp v75, v71 row_shl:8 row_mask:0xf bank_mask:0x3
	v_mov_b32_dpp v80, v76 row_shl:8 row_mask:0xf bank_mask:0x3
	v_mov_b32_dpp v81, v77 row_shl:8 row_mask:0xf bank_mask:0x3
	v_mov_b32_dpp v82, v78 row_shl:8 row_mask:0xf bank_mask:0x3
	v_mov_b32_dpp v83, v79 row_shl:8 row_mask:0xf bank_mask:0x3
	v_mfma_f32_16x16x32_bf16 v[4:7], v[236:239], v[240:243], v[4:7]
	s_nop 0
	v_mfma_f32_16x16x32_bf16 v[0:3], v[72:75], v[80:83], v[0:3]
	global_load_dwordx4 v[68:71], v[244:245], off offset:1792
	global_load_dwordx4 v[72:75], v[246:247], off offset:1792
	global_load_dwordx4 v[76:79], v[248:249], off offset:1344
	global_load_dwordx4 v[80:83], v[250:251], off offset:1344
	s_waitcnt vmcnt(32)
	v_mov_b32_e32 v236, v84
	v_mov_b32_e32 v237, v85
	v_mov_b32_e32 v238, v86
	v_mov_b32_e32 v239, v87
	v_mov_b32_e32 v240, v92
	v_mov_b32_e32 v241, v93
	v_mov_b32_e32 v242, v94
	v_mov_b32_e32 v243, v95
	v_mov_b32_dpp v236, v88 row_shr:8 row_mask:0xf bank_mask:0xc
	v_mov_b32_dpp v237, v89 row_shr:8 row_mask:0xf bank_mask:0xc
	v_mov_b32_dpp v238, v90 row_shr:8 row_mask:0xf bank_mask:0xc
	v_mov_b32_dpp v239, v91 row_shr:8 row_mask:0xf bank_mask:0xc
	v_mov_b32_dpp v240, v96 row_shr:8 row_mask:0xf bank_mask:0xc
	v_mov_b32_dpp v241, v97 row_shr:8 row_mask:0xf bank_mask:0xc
	v_mov_b32_dpp v242, v98 row_shr:8 row_mask:0xf bank_mask:0xc
	v_mov_b32_dpp v243, v99 row_shr:8 row_mask:0xf bank_mask:0xc
	v_mov_b32_dpp v88, v84 row_shl:8 row_mask:0xf bank_mask:0x3
	v_mov_b32_dpp v89, v85 row_shl:8 row_mask:0xf bank_mask:0x3
	v_mov_b32_dpp v90, v86 row_shl:8 row_mask:0xf bank_mask:0x3
	v_mov_b32_dpp v91, v87 row_shl:8 row_mask:0xf bank_mask:0x3
	v_mov_b32_dpp v96, v92 row_shl:8 row_mask:0xf bank_mask:0x3
	v_mov_b32_dpp v97, v93 row_shl:8 row_mask:0xf bank_mask:0x3
	v_mov_b32_dpp v98, v94 row_shl:8 row_mask:0xf bank_mask:0x3
	v_mov_b32_dpp v99, v95 row_shl:8 row_mask:0xf bank_mask:0x3
	v_mfma_f32_16x16x32_bf16 v[4:7], v[236:239], v[240:243], v[4:7]
	s_nop 0
	v_mfma_f32_16x16x32_bf16 v[0:3], v[88:91], v[96:99], v[0:3]
	global_load_dwordx4 v[84:87], v[244:245], off offset:1920
	global_load_dwordx4 v[88:91], v[246:247], off offset:1920
	global_load_dwordx4 v[92:95], v[248:249], off offset:1472
	global_load_dwordx4 v[96:99], v[250:251], off offset:1472
	s_waitcnt vmcnt(32)
	v_mov_b32_e32 v236, v100
	v_mov_b32_e32 v237, v101
	v_mov_b32_e32 v238, v102
	v_mov_b32_e32 v239, v103
	v_mov_b32_e32 v240, v108
	v_mov_b32_e32 v241, v109
	v_mov_b32_e32 v242, v110
	v_mov_b32_e32 v243, v111
	v_mov_b32_dpp v236, v104 row_shr:8 row_mask:0xf bank_mask:0xc
	v_mov_b32_dpp v237, v105 row_shr:8 row_mask:0xf bank_mask:0xc
	v_mov_b32_dpp v238, v106 row_shr:8 row_mask:0xf bank_mask:0xc
	v_mov_b32_dpp v239, v107 row_shr:8 row_mask:0xf bank_mask:0xc
	v_mov_b32_dpp v240, v112 row_shr:8 row_mask:0xf bank_mask:0xc
	v_mov_b32_dpp v241, v113 row_shr:8 row_mask:0xf bank_mask:0xc
	v_mov_b32_dpp v242, v114 row_shr:8 row_mask:0xf bank_mask:0xc
	v_mov_b32_dpp v243, v115 row_shr:8 row_mask:0xf bank_mask:0xc
	v_mov_b32_dpp v104, v100 row_shl:8 row_mask:0xf bank_mask:0x3
	v_mov_b32_dpp v105, v101 row_shl:8 row_mask:0xf bank_mask:0x3
	v_mov_b32_dpp v106, v102 row_shl:8 row_mask:0xf bank_mask:0x3
	v_mov_b32_dpp v107, v103 row_shl:8 row_mask:0xf bank_mask:0x3
	v_mov_b32_dpp v112, v108 row_shl:8 row_mask:0xf bank_mask:0x3
	v_mov_b32_dpp v113, v109 row_shl:8 row_mask:0xf bank_mask:0x3
	v_mov_b32_dpp v114, v110 row_shl:8 row_mask:0xf bank_mask:0x3
	v_mov_b32_dpp v115, v111 row_shl:8 row_mask:0xf bank_mask:0x3
	v_mfma_f32_16x16x32_bf16 v[4:7], v[236:239], v[240:243], v[4:7]
	s_nop 0
	v_mfma_f32_16x16x32_bf16 v[0:3], v[104:107], v[112:115], v[0:3]
	global_load_dwordx4 v[100:103], v[244:245], off offset:2048
	global_load_dwordx4 v[104:107], v[246:247], off offset:2048
	global_load_dwordx4 v[108:111], v[248:249], off offset:1600
	global_load_dwordx4 v[112:115], v[250:251], off offset:1600
	s_waitcnt vmcnt(32)
; __device__ __forceinline__ f32x4 skinny16(const bf16_t* A, int lda, const bf16_t* Bt, int ldb, int K, int lane) {
;     ...
;     for (int k = 0; k < K / 32; k += 16) {
;         bf16x8 a[16], b[16];
; #pragma unroll
;         for (int i = 0; i < 16; ++i) { a[i] = ap[(k + i) * 4]; b[i] = bp[(k + i) * 4]; }
; #pragma unroll
;         for (int i = 0; i < 16; i += 2) { acc0 = __builtin_amdgcn_mfma_f32_16x16x32_bf16(a[i], b[i], acc0, 0, 0, 0); acc1 = __builtin_amdgcn_mfma_f32_16x16x32_bf16(a[i + 1], b[i + 1], acc1, 0, 0, 0); }
;     }
	v_mov_b32_e32 v236, v116
	v_mov_b32_e32 v237, v117
	v_mov_b32_e32 v238, v118
	v_mov_b32_e32 v239, v119
	v_mov_b32_e32 v240, v124
	v_mov_b32_e32 v241, v125
	v_mov_b32_e32 v242, v126
	v_mov_b32_e32 v243, v127
	v_mov_b32_dpp v236, v120 row_shr:8 row_mask:0xf bank_mask:0xc
	v_mov_b32_dpp v237, v121 row_shr:8 row_mask:0xf bank_mask:0xc
	v_mov_b32_dpp v238, v122 row_shr:8 row_mask:0xf bank_mask:0xc
	v_mov_b32_dpp v239, v123 row_shr:8 row_mask:0xf bank_mask:0xc
	v_mov_b32_dpp v240, v128 row_shr:8 row_mask:0xf bank_mask:0xc
	v_mov_b32_dpp v241, v129 row_shr:8 row_mask:0xf bank_mask:0xc
	v_mov_b32_dpp v242, v130 row_shr:8 row_mask:0xf bank_mask:0xc
	v_mov_b32_dpp v243, v131 row_shr:8 row_mask:0xf bank_mask:0xc
	v_mov_b32_dpp v120, v116 row_shl:8 row_mask:0xf bank_mask:0x3
	v_mov_b32_dpp v121, v117 row_shl:8 row_mask:0xf bank_mask:0x3
	v_mov_b32_dpp v122, v118 row_shl:8 row_mask:0xf bank_mask:0x3
	v_mov_b32_dpp v123, v119 row_shl:8 row_mask:0xf bank_mask:0x3
	v_mov_b32_dpp v128, v124 row_shl:8 row_mask:0xf bank_mask:0x3
	v_mov_b32_dpp v129, v125 row_shl:8 row_mask:0xf bank_mask:0x3
	v_mov_b32_dpp v130, v126 row_shl:8 row_mask:0xf bank_mask:0x3
	v_mov_b32_dpp v131, v127 row_shl:8 row_mask:0xf bank_mask:0x3
	v_mfma_f32_16x16x32_bf16 v[4:7], v[236:239], v[240:243], v[4:7]
	s_nop 0
	v_mfma_f32_16x16x32_bf16 v[0:3], v[120:123], v[128:131], v[0:3]
	global_load_dwordx4 v[116:119], v[244:245], off offset:2176
	global_load_dwordx4 v[120:123], v[246:247], off offset:2176
	global_load_dwordx4 v[124:127], v[248:249], off offset:1728
	global_load_dwordx4 v[128:131], v[250:251], off offset:1728
	s_waitcnt vmcnt(32)
	v_mov_b32_e32 v236, v132
	v_mov_b32_e32 v237, v133
	v_mov_b32_e32 v238, v134
	v_mov_b32_e32 v239, v135
	v_mov_b32_e32 v240, v140
	v_mov_b32_e32 v241, v141
	v_mov_b32_e32 v242, v142
	v_mov_b32_e32 v243, v143
	v_mov_b32_dpp v236, v136 row_shr:8 row_mask:0xf bank_mask:0xc
	v_mov_b32_dpp v237, v137 row_shr:8 row_mask:0xf bank_mask:0xc
	v_mov_b32_dpp v238, v138 row_shr:8 row_mask:0xf bank_mask:0xc
	v_mov_b32_dpp v239, v139 row_shr:8 row_mask:0xf bank_mask:0xc
	v_mov_b32_dpp v240, v144 row_shr:8 row_mask:0xf bank_mask:0xc
	v_mov_b32_dpp v241, v145 row_shr:8 row_mask:0xf bank_mask:0xc
	v_mov_b32_dpp v242, v146 row_shr:8 row_mask:0xf bank_mask:0xc
	v_mov_b32_dpp v243, v147 row_shr:8 row_mask:0xf bank_mask:0xc
	v_mov_b32_dpp v136, v132 row_shl:8 row_mask:0xf bank_mask:0x3
	v_mov_b32_dpp v137, v133 row_shl:8 row_mask:0xf bank_mask:0x3
	v_mov_b32_dpp v138, v134 row_shl:8 row_mask:0xf bank_mask:0x3
	v_mov_b32_dpp v139, v135 row_shl:8 row_mask:0xf bank_mask:0x3
	v_mov_b32_dpp v144, v140 row_shl:8 row_mask:0xf bank_mask:0x3
	v_mov_b32_dpp v145, v141 row_shl:8 row_mask:0xf bank_mask:0x3
	v_mov_b32_dpp v146, v142 row_shl:8 row_mask:0xf bank_mask:0x3
	v_mov_b32_dpp v147, v143 row_shl:8 row_mask:0xf bank_mask:0x3
	v_mfma_f32_16x16x32_bf16 v[4:7], v[236:239], v[240:243], v[4:7]
	s_nop 0
	v_mfma_f32_16x16x32_bf16 v[0:3], v[136:139], v[144:147], v[0:3]
	global_load_dwordx4 v[132:135], v[244:245], off offset:2304
	global_load_dwordx4 v[136:139], v[246:247], off offset:2304
	global_load_dwordx4 v[140:143], v[248:249], off offset:1856
	global_load_dwordx4 v[144:147], v[250:251], off offset:1856
	s_waitcnt vmcnt(32)
	v_mov_b32_e32 v236, v148
	v_mov_b32_e32 v237, v149
	v_mov_b32_e32 v238, v150
	v_mov_b32_e32 v239, v151
	v_mov_b32_e32 v240, v168
	v_mov_b32_e32 v241, v169
	v_mov_b32_e32 v242, v170
	v_mov_b32_e32 v243, v171
	v_mov_b32_dpp v236, v164 row_shr:8 row_mask:0xf bank_mask:0xc
	v_mov_b32_dpp v237, v165 row_shr:8 row_mask:0xf bank_mask:0xc
	v_mov_b32_dpp v238, v166 row_shr:8 row_mask:0xf bank_mask:0xc
	v_mov_b32_dpp v239, v167 row_shr:8 row_mask:0xf bank_mask:0xc
	v_mov_b32_dpp v240, v172 row_shr:8 row_mask:0xf bank_mask:0xc
	v_mov_b32_dpp v241, v173 row_shr:8 row_mask:0xf bank_mask:0xc
	v_mov_b32_dpp v242, v174 row_shr:8 row_mask:0xf bank_mask:0xc
	v_mov_b32_dpp v243, v175 row_shr:8 row_mask:0xf bank_mask:0xc
	v_mov_b32_dpp v164, v148 row_shl:8 row_mask:0xf bank_mask:0x3
	v_mov_b32_dpp v165, v149 row_shl:8 row_mask:0xf bank_mask:0x3
	v_mov_b32_dpp v166, v150 row_shl:8 row_mask:0xf bank_mask:0x3
	v_mov_b32_dpp v167, v151 row_shl:8 row_mask:0xf bank_mask:0x3
	v_mov_b32_dpp v172, v168 row_shl:8 row_mask:0xf bank_mask:0x3
	v_mov_b32_dpp v173, v169 row_shl:8 row_mask:0xf bank_mask:0x3
	v_mov_b32_dpp v174, v170 row_shl:8 row_mask:0xf bank_mask:0x3
	v_mov_b32_dpp v175, v171 row_shl:8 row_mask:0xf bank_mask:0x3
	v_mfma_f32_16x16x32_bf16 v[4:7], v[236:239], v[240:243], v[4:7]
	s_nop 0
	v_mfma_f32_16x16x32_bf16 v[0:3], v[164:167], v[172:175], v[0:3]
	global_load_dwordx4 v[148:151], v[244:245], off offset:2432
	global_load_dwordx4 v[164:167], v[246:247], off offset:2432
	global_load_dwordx4 v[168:171], v[248:249], off offset:1984
	global_load_dwordx4 v[172:175], v[250:251], off offset:1984
	s_waitcnt vmcnt(32)
; __device__ __forceinline__ f32x4 skinny16(const bf16_t* A, int lda, const bf16_t* Bt, int ldb, int K, int lane) {
;     ...
;     for (int k = 0; k < K / 32; k += 16) {
;         bf16x8 a[16], b[16];
; #pragma unroll
;         for (int i = 0; i < 16; ++i) { a[i] = ap[(k + i) * 4]; b[i] = bp[(k + i) * 4]; }
; #pragma unroll
;         for (int i = 0; i < 16; i += 2) { acc0 = __builtin_amdgcn_mfma_f32_16x16x32_bf16(a[i], b[i], acc0, 0, 0, 0); acc1 = __builtin_amdgcn_mfma_f32_16x16x32_bf16(a[i + 1], b[i + 1], acc1, 0, 0, 0); }
;     }
	v_mov_b32_e32 v236, v176
	v_mov_b32_e32 v237, v177
	v_mov_b32_e32 v238, v178
	v_mov_b32_e32 v239, v179
	v_mov_b32_e32 v240, v184
	v_mov_b32_e32 v241, v185
	v_mov_b32_e32 v242, v186
	v_mov_b32_e32 v243, v187
	v_mov_b32_dpp v236, v180 row_shr:8 row_mask:0xf bank_mask:0xc
	v_mov_b32_dpp v237, v181 row_shr:8 row_mask:0xf bank_mask:0xc
	v_mov_b32_dpp v238, v182 row_shr:8 row_mask:0xf bank_mask:0xc
	v_mov_b32_dpp v239, v183 row_shr:8 row_mask:0xf bank_mask:0xc
	v_mov_b32_dpp v240, v188 row_shr:8 row_mask:0xf bank_mask:0xc
	v_mov_b32_dpp v241, v189 row_shr:8 row_mask:0xf bank_mask:0xc
	v_mov_b32_dpp v242, v190 row_shr:8 row_mask:0xf bank_mask:0xc
	v_mov_b32_dpp v243, v191 row_shr:8 row_mask:0xf bank_mask:0xc
	v_mov_b32_dpp v180, v176 row_shl:8 row_mask:0xf bank_mask:0x3
	v_mov_b32_dpp v181, v177 row_shl:8 row_mask:0xf bank_mask:0x3
	v_mov_b32_dpp v182, v178 row_shl:8 row_mask:0xf bank_mask:0x3
	v_mov_b32_dpp v183, v179 row_shl:8 row_mask:0xf bank_mask:0x3
	v_mov_b32_dpp v188, v184 row_shl:8 row_mask:0xf bank_mask:0x3
	v_mov_b32_dpp v189, v185 row_shl:8 row_mask:0xf bank_mask:0x3
	v_mov_b32_dpp v190, v186 row_shl:8 row_mask:0xf bank_mask:0x3
	v_mov_b32_dpp v191, v187 row_shl:8 row_mask:0xf bank_mask:0x3
	v_mfma_f32_16x16x32_bf16 v[4:7], v[236:239], v[240:243], v[4:7]
	s_nop 0
	v_mfma_f32_16x16x32_bf16 v[0:3], v[180:183], v[188:191], v[0:3]
	global_load_dwordx4 v[176:179], v[244:245], off offset:2560
	global_load_dwordx4 v[180:183], v[246:247], off offset:2560
	global_load_dwordx4 v[184:187], v[248:249], off offset:2112
	global_load_dwordx4 v[188:191], v[250:251], off offset:2112
	s_waitcnt vmcnt(32)
	v_mov_b32_e32 v236, v204
	v_mov_b32_e32 v237, v205
	v_mov_b32_e32 v238, v206
	v_mov_b32_e32 v239, v207
	v_mov_b32_e32 v240, v212
	v_mov_b32_e32 v241, v213
	v_mov_b32_e32 v242, v214
	v_mov_b32_e32 v243, v215
	v_mov_b32_dpp v236, v208 row_shr:8 row_mask:0xf bank_mask:0xc
	v_mov_b32_dpp v237, v209 row_shr:8 row_mask:0xf bank_mask:0xc
	v_mov_b32_dpp v238, v210 row_shr:8 row_mask:0xf bank_mask:0xc
	v_mov_b32_dpp v239, v211 row_shr:8 row_mask:0xf bank_mask:0xc
	v_mov_b32_dpp v240, v216 row_shr:8 row_mask:0xf bank_mask:0xc
	v_mov_b32_dpp v241, v217 row_shr:8 row_mask:0xf bank_mask:0xc
	v_mov_b32_dpp v242, v218 row_shr:8 row_mask:0xf bank_mask:0xc
	v_mov_b32_dpp v243, v219 row_shr:8 row_mask:0xf bank_mask:0xc
	v_mov_b32_dpp v208, v204 row_shl:8 row_mask:0xf bank_mask:0x3
	v_mov_b32_dpp v209, v205 row_shl:8 row_mask:0xf bank_mask:0x3
	v_mov_b32_dpp v210, v206 row_shl:8 row_mask:0xf bank_mask:0x3
	v_mov_b32_dpp v211, v207 row_shl:8 row_mask:0xf bank_mask:0x3
	v_mov_b32_dpp v216, v212 row_shl:8 row_mask:0xf bank_mask:0x3
	v_mov_b32_dpp v217, v213 row_shl:8 row_mask:0xf bank_mask:0x3
	v_mov_b32_dpp v218, v214 row_shl:8 row_mask:0xf bank_mask:0x3
	v_mov_b32_dpp v219, v215 row_shl:8 row_mask:0xf bank_mask:0x3
	v_mfma_f32_16x16x32_bf16 v[4:7], v[236:239], v[240:243], v[4:7]
	s_nop 0
	v_mfma_f32_16x16x32_bf16 v[0:3], v[208:211], v[216:219], v[0:3]
	global_load_dwordx4 v[204:207], v[244:245], off offset:2688
	global_load_dwordx4 v[208:211], v[246:247], off offset:2688
	global_load_dwordx4 v[212:215], v[248:249], off offset:2240
	global_load_dwordx4 v[216:219], v[250:251], off offset:2240
	s_waitcnt vmcnt(32)
	v_mov_b32_e32 v236, v220
	v_mov_b32_e32 v237, v221
	v_mov_b32_e32 v238, v222
	v_mov_b32_e32 v239, v223
	v_mov_b32_e32 v240, v228
	v_mov_b32_e32 v241, v229
	v_mov_b32_e32 v242, v230
	v_mov_b32_e32 v243, v231
	v_mov_b32_dpp v236, v224 row_shr:8 row_mask:0xf bank_mask:0xc
	v_mov_b32_dpp v237, v225 row_shr:8 row_mask:0xf bank_mask:0xc
	v_mov_b32_dpp v238, v226 row_shr:8 row_mask:0xf bank_mask:0xc
	v_mov_b32_dpp v239, v227 row_shr:8 row_mask:0xf bank_mask:0xc
	v_mov_b32_dpp v240, v232 row_shr:8 row_mask:0xf bank_mask:0xc
	v_mov_b32_dpp v241, v233 row_shr:8 row_mask:0xf bank_mask:0xc
	v_mov_b32_dpp v242, v234 row_shr:8 row_mask:0xf bank_mask:0xc
	v_mov_b32_dpp v243, v235 row_shr:8 row_mask:0xf bank_mask:0xc
	v_mov_b32_dpp v224, v220 row_shl:8 row_mask:0xf bank_mask:0x3
	v_mov_b32_dpp v225, v221 row_shl:8 row_mask:0xf bank_mask:0x3
	v_mov_b32_dpp v226, v222 row_shl:8 row_mask:0xf bank_mask:0x3
	v_mov_b32_dpp v227, v223 row_shl:8 row_mask:0xf bank_mask:0x3
	v_mov_b32_dpp v232, v228 row_shl:8 row_mask:0xf bank_mask:0x3
	v_mov_b32_dpp v233, v229 row_shl:8 row_mask:0xf bank_mask:0x3
	v_mov_b32_dpp v234, v230 row_shl:8 row_mask:0xf bank_mask:0x3
	v_mov_b32_dpp v235, v231 row_shl:8 row_mask:0xf bank_mask:0x3
	v_mfma_f32_16x16x32_bf16 v[4:7], v[236:239], v[240:243], v[4:7]
	s_nop 0
	v_mfma_f32_16x16x32_bf16 v[0:3], v[224:227], v[232:235], v[0:3]
	global_load_dwordx4 v[220:223], v[244:245], off offset:2816
	global_load_dwordx4 v[224:227], v[246:247], off offset:2816
	global_load_dwordx4 v[228:231], v[248:249], off offset:2368
	global_load_dwordx4 v[232:235], v[250:251], off offset:2368
	s_waitcnt vmcnt(32)
; __device__ __forceinline__ f32x4 skinny16(const bf16_t* A, int lda, const bf16_t* Bt, int ldb, int K, int lane) {
;     ...
;     for (int k = 0; k < K / 32; k += 16) {
;         bf16x8 a[16], b[16];
; #pragma unroll
;         for (int i = 0; i < 16; ++i) { a[i] = ap[(k + i) * 4]; b[i] = bp[(k + i) * 4]; }
; #pragma unroll
;         for (int i = 0; i < 16; i += 2) { acc0 = __builtin_amdgcn_mfma_f32_16x16x32_bf16(a[i], b[i], acc0, 0, 0, 0); acc1 = __builtin_amdgcn_mfma_f32_16x16x32_bf16(a[i + 1], b[i + 1], acc1, 0, 0, 0); }
;     }
	v_mov_b32_e32 v236, v68
	v_mov_b32_e32 v237, v69
	v_mov_b32_e32 v238, v70
	v_mov_b32_e32 v239, v71
	v_mov_b32_e32 v240, v76
	v_mov_b32_e32 v241, v77
	v_mov_b32_e32 v242, v78
	v_mov_b32_e32 v243, v79
	v_mov_b32_dpp v236, v72 row_shr:8 row_mask:0xf bank_mask:0xc
	v_mov_b32_dpp v237, v73 row_shr:8 row_mask:0xf bank_mask:0xc
	v_mov_b32_dpp v238, v74 row_shr:8 row_mask:0xf bank_mask:0xc
	v_mov_b32_dpp v239, v75 row_shr:8 row_mask:0xf bank_mask:0xc
	v_mov_b32_dpp v240, v80 row_shr:8 row_mask:0xf bank_mask:0xc
	v_mov_b32_dpp v241, v81 row_shr:8 row_mask:0xf bank_mask:0xc
	v_mov_b32_dpp v242, v82 row_shr:8 row_mask:0xf bank_mask:0xc
	v_mov_b32_dpp v243, v83 row_shr:8 row_mask:0xf bank_mask:0xc
	v_mov_b32_dpp v72, v68 row_shl:8 row_mask:0xf bank_mask:0x3
	v_mov_b32_dpp v73, v69 row_shl:8 row_mask:0xf bank_mask:0x3
	v_mov_b32_dpp v74, v70 row_shl:8 row_mask:0xf bank_mask:0x3
	v_mov_b32_dpp v75, v71 row_shl:8 row_mask:0xf bank_mask:0x3
	v_mov_b32_dpp v80, v76 row_shl:8 row_mask:0xf bank_mask:0x3
	v_mov_b32_dpp v81, v77 row_shl:8 row_mask:0xf bank_mask:0x3
	v_mov_b32_dpp v82, v78 row_shl:8 row_mask:0xf bank_mask:0x3
	v_mov_b32_dpp v83, v79 row_shl:8 row_mask:0xf bank_mask:0x3
	v_mfma_f32_16x16x32_bf16 v[4:7], v[236:239], v[240:243], v[4:7]
	s_nop 0
	v_mfma_f32_16x16x32_bf16 v[0:3], v[72:75], v[80:83], v[0:3]
	global_load_dwordx4 v[68:71], v[244:245], off offset:2944
	global_load_dwordx4 v[72:75], v[246:247], off offset:2944
	global_load_dwordx4 v[76:79], v[248:249], off offset:2496
	global_load_dwordx4 v[80:83], v[250:251], off offset:2496
	s_waitcnt vmcnt(32)
	v_mov_b32_e32 v236, v84
	v_mov_b32_e32 v237, v85
	v_mov_b32_e32 v238, v86
	v_mov_b32_e32 v239, v87
	v_mov_b32_e32 v240, v92
	v_mov_b32_e32 v241, v93
	v_mov_b32_e32 v242, v94
	v_mov_b32_e32 v243, v95
	v_mov_b32_dpp v236, v88 row_shr:8 row_mask:0xf bank_mask:0xc
	v_mov_b32_dpp v237, v89 row_shr:8 row_mask:0xf bank_mask:0xc
	v_mov_b32_dpp v238, v90 row_shr:8 row_mask:0xf bank_mask:0xc
	v_mov_b32_dpp v239, v91 row_shr:8 row_mask:0xf bank_mask:0xc
	v_mov_b32_dpp v240, v96 row_shr:8 row_mask:0xf bank_mask:0xc
	v_mov_b32_dpp v241, v97 row_shr:8 row_mask:0xf bank_mask:0xc
	v_mov_b32_dpp v242, v98 row_shr:8 row_mask:0xf bank_mask:0xc
	v_mov_b32_dpp v243, v99 row_shr:8 row_mask:0xf bank_mask:0xc
	v_mov_b32_dpp v88, v84 row_shl:8 row_mask:0xf bank_mask:0x3
	v_mov_b32_dpp v89, v85 row_shl:8 row_mask:0xf bank_mask:0x3
	v_mov_b32_dpp v90, v86 row_shl:8 row_mask:0xf bank_mask:0x3
	v_mov_b32_dpp v91, v87 row_shl:8 row_mask:0xf bank_mask:0x3
	v_mov_b32_dpp v96, v92 row_shl:8 row_mask:0xf bank_mask:0x3
	v_mov_b32_dpp v97, v93 row_shl:8 row_mask:0xf bank_mask:0x3
	v_mov_b32_dpp v98, v94 row_shl:8 row_mask:0xf bank_mask:0x3
	v_mov_b32_dpp v99, v95 row_shl:8 row_mask:0xf bank_mask:0x3
	v_mfma_f32_16x16x32_bf16 v[4:7], v[236:239], v[240:243], v[4:7]
	s_nop 0
	v_mfma_f32_16x16x32_bf16 v[0:3], v[88:91], v[96:99], v[0:3]
	global_load_dwordx4 v[84:87], v[244:245], off offset:3072
	global_load_dwordx4 v[88:91], v[246:247], off offset:3072
	global_load_dwordx4 v[92:95], v[248:249], off offset:2624
	global_load_dwordx4 v[96:99], v[250:251], off offset:2624
	s_waitcnt vmcnt(32)
	v_mov_b32_e32 v236, v100
	v_mov_b32_e32 v237, v101
	v_mov_b32_e32 v238, v102
	v_mov_b32_e32 v239, v103
	v_mov_b32_e32 v240, v108
	v_mov_b32_e32 v241, v109
	v_mov_b32_e32 v242, v110
	v_mov_b32_e32 v243, v111
	v_mov_b32_dpp v236, v104 row_shr:8 row_mask:0xf bank_mask:0xc
	v_mov_b32_dpp v237, v105 row_shr:8 row_mask:0xf bank_mask:0xc
	v_mov_b32_dpp v238, v106 row_shr:8 row_mask:0xf bank_mask:0xc
	v_mov_b32_dpp v239, v107 row_shr:8 row_mask:0xf bank_mask:0xc
	v_mov_b32_dpp v240, v112 row_shr:8 row_mask:0xf bank_mask:0xc
	v_mov_b32_dpp v241, v113 row_shr:8 row_mask:0xf bank_mask:0xc
	v_mov_b32_dpp v242, v114 row_shr:8 row_mask:0xf bank_mask:0xc
	v_mov_b32_dpp v243, v115 row_shr:8 row_mask:0xf bank_mask:0xc
	v_mov_b32_dpp v104, v100 row_shl:8 row_mask:0xf bank_mask:0x3
	v_mov_b32_dpp v105, v101 row_shl:8 row_mask:0xf bank_mask:0x3
	v_mov_b32_dpp v106, v102 row_shl:8 row_mask:0xf bank_mask:0x3
	v_mov_b32_dpp v107, v103 row_shl:8 row_mask:0xf bank_mask:0x3
	v_mov_b32_dpp v112, v108 row_shl:8 row_mask:0xf bank_mask:0x3
	v_mov_b32_dpp v113, v109 row_shl:8 row_mask:0xf bank_mask:0x3
	v_mov_b32_dpp v114, v110 row_shl:8 row_mask:0xf bank_mask:0x3
	v_mov_b32_dpp v115, v111 row_shl:8 row_mask:0xf bank_mask:0x3
	v_mfma_f32_16x16x32_bf16 v[4:7], v[236:239], v[240:243], v[4:7]
	s_nop 0
	v_mfma_f32_16x16x32_bf16 v[0:3], v[104:107], v[112:115], v[0:3]
	global_load_dwordx4 v[100:103], v[244:245], off offset:3200
	global_load_dwordx4 v[104:107], v[246:247], off offset:3200
	global_load_dwordx4 v[108:111], v[248:249], off offset:2752
	global_load_dwordx4 v[112:115], v[250:251], off offset:2752
	s_waitcnt vmcnt(32)
	v_mov_b32_e32 v236, v116
	v_mov_b32_e32 v237, v117
	v_mov_b32_e32 v238, v118
	v_mov_b32_e32 v239, v119
	v_mov_b32_e32 v240, v124
	v_mov_b32_e32 v241, v125
	v_mov_b32_e32 v242, v126
	v_mov_b32_e32 v243, v127
	v_mov_b32_dpp v236, v120 row_shr:8 row_mask:0xf bank_mask:0xc
	v_mov_b32_dpp v237, v121 row_shr:8 row_mask:0xf bank_mask:0xc
	v_mov_b32_dpp v238, v122 row_shr:8 row_mask:0xf bank_mask:0xc
	v_mov_b32_dpp v239, v123 row_shr:8 row_mask:0xf bank_mask:0xc
	v_mov_b32_dpp v240, v128 row_shr:8 row_mask:0xf bank_mask:0xc
	v_mov_b32_dpp v241, v129 row_shr:8 row_mask:0xf bank_mask:0xc
	v_mov_b32_dpp v242, v130 row_shr:8 row_mask:0xf bank_mask:0xc
	v_mov_b32_dpp v243, v131 row_shr:8 row_mask:0xf bank_mask:0xc
	v_mov_b32_dpp v120, v116 row_shl:8 row_mask:0xf bank_mask:0x3
	v_mov_b32_dpp v121, v117 row_shl:8 row_mask:0xf bank_mask:0x3
	v_mov_b32_dpp v122, v118 row_shl:8 row_mask:0xf bank_mask:0x3
	v_mov_b32_dpp v123, v119 row_shl:8 row_mask:0xf bank_mask:0x3
	v_mov_b32_dpp v128, v124 row_shl:8 row_mask:0xf bank_mask:0x3
	v_mov_b32_dpp v129, v125 row_shl:8 row_mask:0xf bank_mask:0x3
	v_mov_b32_dpp v130, v126 row_shl:8 row_mask:0xf bank_mask:0x3
	v_mov_b32_dpp v131, v127 row_shl:8 row_mask:0xf bank_mask:0x3
	v_mfma_f32_16x16x32_bf16 v[4:7], v[236:239], v[240:243], v[4:7]
	s_nop 0
	v_mfma_f32_16x16x32_bf16 v[0:3], v[120:123], v[128:131], v[0:3]
	global_load_dwordx4 v[116:119], v[244:245], off offset:3328
	global_load_dwordx4 v[120:123], v[246:247], off offset:3328
	global_load_dwordx4 v[124:127], v[248:249], off offset:2880
	global_load_dwordx4 v[128:131], v[250:251], off offset:2880
	s_waitcnt vmcnt(32)
; __device__ __forceinline__ f32x4 skinny16(const bf16_t* A, int lda, const bf16_t* Bt, int ldb, int K, int lane) {
;     ...
;     for (int k = 0; k < K / 32; k += 16) {
;         bf16x8 a[16], b[16];
; #pragma unroll
;         for (int i = 0; i < 16; ++i) { a[i] = ap[(k + i) * 4]; b[i] = bp[(k + i) * 4]; }
; #pragma unroll
;         for (int i = 0; i < 16; i += 2) { acc0 = __builtin_amdgcn_mfma_f32_16x16x32_bf16(a[i], b[i], acc0, 0, 0, 0); acc1 = __builtin_amdgcn_mfma_f32_16x16x32_bf16(a[i + 1], b[i + 1], acc1, 0, 0, 0); }
;     }
	v_mov_b32_e32 v236, v132
	v_mov_b32_e32 v237, v133
	v_mov_b32_e32 v238, v134
	v_mov_b32_e32 v239, v135
	v_mov_b32_e32 v240, v140
	v_mov_b32_e32 v241, v141
	v_mov_b32_e32 v242, v142
	v_mov_b32_e32 v243, v143
	v_mov_b32_dpp v236, v136 row_shr:8 row_mask:0xf bank_mask:0xc
	v_mov_b32_dpp v237, v137 row_shr:8 row_mask:0xf bank_mask:0xc
	v_mov_b32_dpp v238, v138 row_shr:8 row_mask:0xf bank_mask:0xc
	v_mov_b32_dpp v239, v139 row_shr:8 row_mask:0xf bank_mask:0xc
	v_mov_b32_dpp v240, v144 row_shr:8 row_mask:0xf bank_mask:0xc
	v_mov_b32_dpp v241, v145 row_shr:8 row_mask:0xf bank_mask:0xc
	v_mov_b32_dpp v242, v146 row_shr:8 row_mask:0xf bank_mask:0xc
	v_mov_b32_dpp v243, v147 row_shr:8 row_mask:0xf bank_mask:0xc
	v_mov_b32_dpp v136, v132 row_shl:8 row_mask:0xf bank_mask:0x3
	v_mov_b32_dpp v137, v133 row_shl:8 row_mask:0xf bank_mask:0x3
	v_mov_b32_dpp v138, v134 row_shl:8 row_mask:0xf bank_mask:0x3
	v_mov_b32_dpp v139, v135 row_shl:8 row_mask:0xf bank_mask:0x3
	v_mov_b32_dpp v144, v140 row_shl:8 row_mask:0xf bank_mask:0x3
	v_mov_b32_dpp v145, v141 row_shl:8 row_mask:0xf bank_mask:0x3
	v_mov_b32_dpp v146, v142 row_shl:8 row_mask:0xf bank_mask:0x3
	v_mov_b32_dpp v147, v143 row_shl:8 row_mask:0xf bank_mask:0x3
	v_mfma_f32_16x16x32_bf16 v[4:7], v[236:239], v[240:243], v[4:7]
	s_nop 0
	v_mfma_f32_16x16x32_bf16 v[0:3], v[136:139], v[144:147], v[0:3]
	global_load_dwordx4 v[132:135], v[244:245], off offset:3456
	global_load_dwordx4 v[136:139], v[246:247], off offset:3456
	global_load_dwordx4 v[140:143], v[248:249], off offset:3008
	global_load_dwordx4 v[144:147], v[250:251], off offset:3008
	s_waitcnt vmcnt(32)
	v_mov_b32_e32 v236, v148
	v_mov_b32_e32 v237, v149
	v_mov_b32_e32 v238, v150
	v_mov_b32_e32 v239, v151
	v_mov_b32_e32 v240, v168
	v_mov_b32_e32 v241, v169
	v_mov_b32_e32 v242, v170
	v_mov_b32_e32 v243, v171
	v_mov_b32_dpp v236, v164 row_shr:8 row_mask:0xf bank_mask:0xc
	v_mov_b32_dpp v237, v165 row_shr:8 row_mask:0xf bank_mask:0xc
	v_mov_b32_dpp v238, v166 row_shr:8 row_mask:0xf bank_mask:0xc
	v_mov_b32_dpp v239, v167 row_shr:8 row_mask:0xf bank_mask:0xc
	v_mov_b32_dpp v240, v172 row_shr:8 row_mask:0xf bank_mask:0xc
	v_mov_b32_dpp v241, v173 row_shr:8 row_mask:0xf bank_mask:0xc
	v_mov_b32_dpp v242, v174 row_shr:8 row_mask:0xf bank_mask:0xc
	v_mov_b32_dpp v243, v175 row_shr:8 row_mask:0xf bank_mask:0xc
	v_mov_b32_dpp v164, v148 row_shl:8 row_mask:0xf bank_mask:0x3
	v_mov_b32_dpp v165, v149 row_shl:8 row_mask:0xf bank_mask:0x3
	v_mov_b32_dpp v166, v150 row_shl:8 row_mask:0xf bank_mask:0x3
	v_mov_b32_dpp v167, v151 row_shl:8 row_mask:0xf bank_mask:0x3
	v_mov_b32_dpp v172, v168 row_shl:8 row_mask:0xf bank_mask:0x3
	v_mov_b32_dpp v173, v169 row_shl:8 row_mask:0xf bank_mask:0x3
	v_mov_b32_dpp v174, v170 row_shl:8 row_mask:0xf bank_mask:0x3
	v_mov_b32_dpp v175, v171 row_shl:8 row_mask:0xf bank_mask:0x3
	v_mfma_f32_16x16x32_bf16 v[4:7], v[236:239], v[240:243], v[4:7]
	s_nop 0
	v_mfma_f32_16x16x32_bf16 v[0:3], v[164:167], v[172:175], v[0:3]
	s_waitcnt vmcnt(28)
	v_mov_b32_e32 v236, v176
	v_mov_b32_e32 v237, v177
	v_mov_b32_e32 v238, v178
	v_mov_b32_e32 v239, v179
	v_mov_b32_e32 v240, v184
	v_mov_b32_e32 v241, v185
	v_mov_b32_e32 v242, v186
	v_mov_b32_e32 v243, v187
	v_mov_b32_dpp v236, v180 row_shr:8 row_mask:0xf bank_mask:0xc
	v_mov_b32_dpp v237, v181 row_shr:8 row_mask:0xf bank_mask:0xc
	v_mov_b32_dpp v238, v182 row_shr:8 row_mask:0xf bank_mask:0xc
	v_mov_b32_dpp v239, v183 row_shr:8 row_mask:0xf bank_mask:0xc
	v_mov_b32_dpp v240, v188 row_shr:8 row_mask:0xf bank_mask:0xc
	v_mov_b32_dpp v241, v189 row_shr:8 row_mask:0xf bank_mask:0xc
	v_mov_b32_dpp v242, v190 row_shr:8 row_mask:0xf bank_mask:0xc
	v_mov_b32_dpp v243, v191 row_shr:8 row_mask:0xf bank_mask:0xc
	v_mov_b32_dpp v180, v176 row_shl:8 row_mask:0xf bank_mask:0x3
	v_mov_b32_dpp v181, v177 row_shl:8 row_mask:0xf bank_mask:0x3
	v_mov_b32_dpp v182, v178 row_shl:8 row_mask:0xf bank_mask:0x3
	v_mov_b32_dpp v183, v179 row_shl:8 row_mask:0xf bank_mask:0x3
	v_mov_b32_dpp v188, v184 row_shl:8 row_mask:0xf bank_mask:0x3
	v_mov_b32_dpp v189, v185 row_shl:8 row_mask:0xf bank_mask:0x3
	v_mov_b32_dpp v190, v186 row_shl:8 row_mask:0xf bank_mask:0x3
	v_mov_b32_dpp v191, v187 row_shl:8 row_mask:0xf bank_mask:0x3
	v_mfma_f32_16x16x32_bf16 v[4:7], v[236:239], v[240:243], v[4:7]
	s_nop 0
	v_mfma_f32_16x16x32_bf16 v[0:3], v[180:183], v[188:191], v[0:3]
	s_waitcnt vmcnt(24)
	v_mov_b32_e32 v236, v204
	v_mov_b32_e32 v237, v205
	v_mov_b32_e32 v238, v206
	v_mov_b32_e32 v239, v207
	v_mov_b32_e32 v240, v212
	v_mov_b32_e32 v241, v213
	v_mov_b32_e32 v242, v214
	v_mov_b32_e32 v243, v215
	v_mov_b32_dpp v236, v208 row_shr:8 row_mask:0xf bank_mask:0xc
	v_mov_b32_dpp v237, v209 row_shr:8 row_mask:0xf bank_mask:0xc
	v_mov_b32_dpp v238, v210 row_shr:8 row_mask:0xf bank_mask:0xc
	v_mov_b32_dpp v239, v211 row_shr:8 row_mask:0xf bank_mask:0xc
	v_mov_b32_dpp v240, v216 row_shr:8 row_mask:0xf bank_mask:0xc
	v_mov_b32_dpp v241, v217 row_shr:8 row_mask:0xf bank_mask:0xc
	v_mov_b32_dpp v242, v218 row_shr:8 row_mask:0xf bank_mask:0xc
	v_mov_b32_dpp v243, v219 row_shr:8 row_mask:0xf bank_mask:0xc
	v_mov_b32_dpp v208, v204 row_shl:8 row_mask:0xf bank_mask:0x3
	v_mov_b32_dpp v209, v205 row_shl:8 row_mask:0xf bank_mask:0x3
	v_mov_b32_dpp v210, v206 row_shl:8 row_mask:0xf bank_mask:0x3
	v_mov_b32_dpp v211, v207 row_shl:8 row_mask:0xf bank_mask:0x3
	v_mov_b32_dpp v216, v212 row_shl:8 row_mask:0xf bank_mask:0x3
	v_mov_b32_dpp v217, v213 row_shl:8 row_mask:0xf bank_mask:0x3
	v_mov_b32_dpp v218, v214 row_shl:8 row_mask:0xf bank_mask:0x3
	v_mov_b32_dpp v219, v215 row_shl:8 row_mask:0xf bank_mask:0x3
	v_mfma_f32_16x16x32_bf16 v[4:7], v[236:239], v[240:243], v[4:7]
	s_nop 0
	v_mfma_f32_16x16x32_bf16 v[0:3], v[208:211], v[216:219], v[0:3]
	s_waitcnt vmcnt(20)
; __device__ __forceinline__ f32x4 skinny16(const bf16_t* A, int lda, const bf16_t* Bt, int ldb, int K, int lane) {
;     ...
;     for (int k = 0; k < K / 32; k += 16) {
;         bf16x8 a[16], b[16];
; #pragma unroll
;         for (int i = 0; i < 16; ++i) { a[i] = ap[(k + i) * 4]; b[i] = bp[(k + i) * 4]; }
; #pragma unroll
;         for (int i = 0; i < 16; i += 2) { acc0 = __builtin_amdgcn_mfma_f32_16x16x32_bf16(a[i], b[i], acc0, 0, 0, 0); acc1 = __builtin_amdgcn_mfma_f32_16x16x32_bf16(a[i + 1], b[i + 1], acc1, 0, 0, 0); }
;     }
	v_mov_b32_e32 v236, v220
	v_mov_b32_e32 v237, v221
	v_mov_b32_e32 v238, v222
	v_mov_b32_e32 v239, v223
	v_mov_b32_e32 v240, v228
	v_mov_b32_e32 v241, v229
	v_mov_b32_e32 v242, v230
	v_mov_b32_e32 v243, v231
	v_mov_b32_dpp v236, v224 row_shr:8 row_mask:0xf bank_mask:0xc
	v_mov_b32_dpp v237, v225 row_shr:8 row_mask:0xf bank_mask:0xc
	v_mov_b32_dpp v238, v226 row_shr:8 row_mask:0xf bank_mask:0xc
	v_mov_b32_dpp v239, v227 row_shr:8 row_mask:0xf bank_mask:0xc
	v_mov_b32_dpp v240, v232 row_shr:8 row_mask:0xf bank_mask:0xc
	v_mov_b32_dpp v241, v233 row_shr:8 row_mask:0xf bank_mask:0xc
	v_mov_b32_dpp v242, v234 row_shr:8 row_mask:0xf bank_mask:0xc
	v_mov_b32_dpp v243, v235 row_shr:8 row_mask:0xf bank_mask:0xc
	v_mov_b32_dpp v224, v220 row_shl:8 row_mask:0xf bank_mask:0x3
	v_mov_b32_dpp v225, v221 row_shl:8 row_mask:0xf bank_mask:0x3
	v_mov_b32_dpp v226, v222 row_shl:8 row_mask:0xf bank_mask:0x3
	v_mov_b32_dpp v227, v223 row_shl:8 row_mask:0xf bank_mask:0x3
	v_mov_b32_dpp v232, v228 row_shl:8 row_mask:0xf bank_mask:0x3
	v_mov_b32_dpp v233, v229 row_shl:8 row_mask:0xf bank_mask:0x3
	v_mov_b32_dpp v234, v230 row_shl:8 row_mask:0xf bank_mask:0x3
	v_mov_b32_dpp v235, v231 row_shl:8 row_mask:0xf bank_mask:0x3
	v_mfma_f32_16x16x32_bf16 v[4:7], v[236:239], v[240:243], v[4:7]
	s_nop 0
	v_mfma_f32_16x16x32_bf16 v[0:3], v[224:227], v[232:235], v[0:3]
	s_waitcnt vmcnt(16)
	v_mov_b32_e32 v236, v68
	v_mov_b32_e32 v237, v69
	v_mov_b32_e32 v238, v70
	v_mov_b32_e32 v239, v71
	v_mov_b32_e32 v240, v76
	v_mov_b32_e32 v241, v77
	v_mov_b32_e32 v242, v78
	v_mov_b32_e32 v243, v79
	v_mov_b32_dpp v236, v72 row_shr:8 row_mask:0xf bank_mask:0xc
	v_mov_b32_dpp v237, v73 row_shr:8 row_mask:0xf bank_mask:0xc
	v_mov_b32_dpp v238, v74 row_shr:8 row_mask:0xf bank_mask:0xc
	v_mov_b32_dpp v239, v75 row_shr:8 row_mask:0xf bank_mask:0xc
	v_mov_b32_dpp v240, v80 row_shr:8 row_mask:0xf bank_mask:0xc
	v_mov_b32_dpp v241, v81 row_shr:8 row_mask:0xf bank_mask:0xc
	v_mov_b32_dpp v242, v82 row_shr:8 row_mask:0xf bank_mask:0xc
	v_mov_b32_dpp v243, v83 row_shr:8 row_mask:0xf bank_mask:0xc
	v_mov_b32_dpp v72, v68 row_shl:8 row_mask:0xf bank_mask:0x3
	v_mov_b32_dpp v73, v69 row_shl:8 row_mask:0xf bank_mask:0x3
	v_mov_b32_dpp v74, v70 row_shl:8 row_mask:0xf bank_mask:0x3
	v_mov_b32_dpp v75, v71 row_shl:8 row_mask:0xf bank_mask:0x3
	v_mov_b32_dpp v80, v76 row_shl:8 row_mask:0xf bank_mask:0x3
	v_mov_b32_dpp v81, v77 row_shl:8 row_mask:0xf bank_mask:0x3
	v_mov_b32_dpp v82, v78 row_shl:8 row_mask:0xf bank_mask:0x3
	v_mov_b32_dpp v83, v79 row_shl:8 row_mask:0xf bank_mask:0x3
	v_mfma_f32_16x16x32_bf16 v[4:7], v[236:239], v[240:243], v[4:7]
	s_nop 0
	v_mfma_f32_16x16x32_bf16 v[0:3], v[72:75], v[80:83], v[0:3]
	s_waitcnt vmcnt(12)
	v_mov_b32_e32 v236, v84
	v_mov_b32_e32 v237, v85
	v_mov_b32_e32 v238, v86
	v_mov_b32_e32 v239, v87
	v_mov_b32_e32 v240, v92
	v_mov_b32_e32 v241, v93
	v_mov_b32_e32 v242, v94
	v_mov_b32_e32 v243, v95
	v_mov_b32_dpp v236, v88 row_shr:8 row_mask:0xf bank_mask:0xc
	v_mov_b32_dpp v237, v89 row_shr:8 row_mask:0xf bank_mask:0xc
	v_mov_b32_dpp v238, v90 row_shr:8 row_mask:0xf bank_mask:0xc
	v_mov_b32_dpp v239, v91 row_shr:8 row_mask:0xf bank_mask:0xc
	v_mov_b32_dpp v240, v96 row_shr:8 row_mask:0xf bank_mask:0xc
	v_mov_b32_dpp v241, v97 row_shr:8 row_mask:0xf bank_mask:0xc
	v_mov_b32_dpp v242, v98 row_shr:8 row_mask:0xf bank_mask:0xc
	v_mov_b32_dpp v243, v99 row_shr:8 row_mask:0xf bank_mask:0xc
	v_mov_b32_dpp v88, v84 row_shl:8 row_mask:0xf bank_mask:0x3
	v_mov_b32_dpp v89, v85 row_shl:8 row_mask:0xf bank_mask:0x3
	v_mov_b32_dpp v90, v86 row_shl:8 row_mask:0xf bank_mask:0x3
	v_mov_b32_dpp v91, v87 row_shl:8 row_mask:0xf bank_mask:0x3
	v_mov_b32_dpp v96, v92 row_shl:8 row_mask:0xf bank_mask:0x3
	v_mov_b32_dpp v97, v93 row_shl:8 row_mask:0xf bank_mask:0x3
	v_mov_b32_dpp v98, v94 row_shl:8 row_mask:0xf bank_mask:0x3
	v_mov_b32_dpp v99, v95 row_shl:8 row_mask:0xf bank_mask:0x3
	v_mfma_f32_16x16x32_bf16 v[4:7], v[236:239], v[240:243], v[4:7]
	s_nop 0
	v_mfma_f32_16x16x32_bf16 v[0:3], v[88:91], v[96:99], v[0:3]
	s_waitcnt vmcnt(8)
	v_mov_b32_e32 v236, v100
	v_mov_b32_e32 v237, v101
	v_mov_b32_e32 v238, v102
	v_mov_b32_e32 v239, v103
	v_mov_b32_e32 v240, v108
	v_mov_b32_e32 v241, v109
	v_mov_b32_e32 v242, v110
	v_mov_b32_e32 v243, v111
	v_mov_b32_dpp v236, v104 row_shr:8 row_mask:0xf bank_mask:0xc
	v_mov_b32_dpp v237, v105 row_shr:8 row_mask:0xf bank_mask:0xc
	v_mov_b32_dpp v238, v106 row_shr:8 row_mask:0xf bank_mask:0xc
	v_mov_b32_dpp v239, v107 row_shr:8 row_mask:0xf bank_mask:0xc
	v_mov_b32_dpp v240, v112 row_shr:8 row_mask:0xf bank_mask:0xc
	v_mov_b32_dpp v241, v113 row_shr:8 row_mask:0xf bank_mask:0xc
	v_mov_b32_dpp v242, v114 row_shr:8 row_mask:0xf bank_mask:0xc
	v_mov_b32_dpp v243, v115 row_shr:8 row_mask:0xf bank_mask:0xc
	v_mov_b32_dpp v104, v100 row_shl:8 row_mask:0xf bank_mask:0x3
	v_mov_b32_dpp v105, v101 row_shl:8 row_mask:0xf bank_mask:0x3
	v_mov_b32_dpp v106, v102 row_shl:8 row_mask:0xf bank_mask:0x3
	v_mov_b32_dpp v107, v103 row_shl:8 row_mask:0xf bank_mask:0x3
	v_mov_b32_dpp v112, v108 row_shl:8 row_mask:0xf bank_mask:0x3
	v_mov_b32_dpp v113, v109 row_shl:8 row_mask:0xf bank_mask:0x3
	v_mov_b32_dpp v114, v110 row_shl:8 row_mask:0xf bank_mask:0x3
	v_mov_b32_dpp v115, v111 row_shl:8 row_mask:0xf bank_mask:0x3
	v_mfma_f32_16x16x32_bf16 v[4:7], v[236:239], v[240:243], v[4:7]
	s_nop 0
	v_mfma_f32_16x16x32_bf16 v[0:3], v[104:107], v[112:115], v[0:3]
	s_waitcnt vmcnt(4)
; __device__ __forceinline__ f32x4 skinny16(const bf16_t* A, int lda, const bf16_t* Bt, int ldb, int K, int lane) {
;     ...
;         for (int i = 0; i < 16; i += 2) { acc0 = __builtin_amdgcn_mfma_f32_16x16x32_bf16(a[i], b[i], acc0, 0, 0, 0); acc1 = __builtin_amdgcn_mfma_f32_16x16x32_bf16(a[i + 1], b[i + 1], acc1, 0, 0, 0); }
;     }
;     return acc0 + acc1;
; __global__ void __launch_bounds__(512, 2) mega(Args a) {
;     ...
;                 const int task = wave * G + bx, mt = task & 7, nt = task >> 3;
;                 const f32x4 acc = skinny16(ycat + (size_t)(MP + mt * 16) * DM, DM, Wo + (size_t)nt * 16 * DM, DM, DM, lane);
; #pragma unroll
;                 for (int j = 0; j < 4; ++j) { const int row = mt * 16 + q8 * 4 + j, col = nt * 16 + r;
;                     xcur[(size_t)(MP + row) * DM + col] = xb[(size_t)row * DM + col] + modg[(size_t)(NB + row) * MODLD + col] * acc[j]; }
	v_mov_b32_e32 v236, v116
	v_mov_b32_e32 v237, v117
	v_mov_b32_e32 v238, v118
	v_mov_b32_e32 v239, v119
	v_mov_b32_e32 v240, v124
	v_mov_b32_e32 v241, v125
	v_mov_b32_e32 v242, v126
	v_mov_b32_e32 v243, v127
	v_mov_b32_dpp v236, v120 row_shr:8 row_mask:0xf bank_mask:0xc
	v_mov_b32_dpp v237, v121 row_shr:8 row_mask:0xf bank_mask:0xc
	v_mov_b32_dpp v238, v122 row_shr:8 row_mask:0xf bank_mask:0xc
	v_mov_b32_dpp v239, v123 row_shr:8 row_mask:0xf bank_mask:0xc
	v_mov_b32_dpp v240, v128 row_shr:8 row_mask:0xf bank_mask:0xc
	v_mov_b32_dpp v241, v129 row_shr:8 row_mask:0xf bank_mask:0xc
	v_mov_b32_dpp v242, v130 row_shr:8 row_mask:0xf bank_mask:0xc
	v_mov_b32_dpp v243, v131 row_shr:8 row_mask:0xf bank_mask:0xc
	v_mov_b32_dpp v120, v116 row_shl:8 row_mask:0xf bank_mask:0x3
	v_mov_b32_dpp v121, v117 row_shl:8 row_mask:0xf bank_mask:0x3
	v_mov_b32_dpp v122, v118 row_shl:8 row_mask:0xf bank_mask:0x3
	v_mov_b32_dpp v123, v119 row_shl:8 row_mask:0xf bank_mask:0x3
	v_mov_b32_dpp v128, v124 row_shl:8 row_mask:0xf bank_mask:0x3
	v_mov_b32_dpp v129, v125 row_shl:8 row_mask:0xf bank_mask:0x3
	v_mov_b32_dpp v130, v126 row_shl:8 row_mask:0xf bank_mask:0x3
	v_mov_b32_dpp v131, v127 row_shl:8 row_mask:0xf bank_mask:0x3
	v_mfma_f32_16x16x32_bf16 v[4:7], v[236:239], v[240:243], v[4:7]
	s_nop 0
	v_mfma_f32_16x16x32_bf16 v[0:3], v[120:123], v[128:131], v[0:3]
	s_waitcnt vmcnt(0)
	v_mov_b32_e32 v236, v132
	v_mov_b32_e32 v237, v133
	v_mov_b32_e32 v238, v134
	v_mov_b32_e32 v239, v135
	v_mov_b32_e32 v240, v140
	v_mov_b32_e32 v241, v141
	v_mov_b32_e32 v242, v142
	v_mov_b32_e32 v243, v143
	v_mov_b32_dpp v236, v136 row_shr:8 row_mask:0xf bank_mask:0xc
	v_mov_b32_dpp v237, v137 row_shr:8 row_mask:0xf bank_mask:0xc
	v_mov_b32_dpp v238, v138 row_shr:8 row_mask:0xf bank_mask:0xc
	v_mov_b32_dpp v239, v139 row_shr:8 row_mask:0xf bank_mask:0xc
	v_mov_b32_dpp v240, v144 row_shr:8 row_mask:0xf bank_mask:0xc
	v_mov_b32_dpp v241, v145 row_shr:8 row_mask:0xf bank_mask:0xc
	v_mov_b32_dpp v242, v146 row_shr:8 row_mask:0xf bank_mask:0xc
	v_mov_b32_dpp v243, v147 row_shr:8 row_mask:0xf bank_mask:0xc
	v_mov_b32_dpp v136, v132 row_shl:8 row_mask:0xf bank_mask:0x3
	v_mov_b32_dpp v137, v133 row_shl:8 row_mask:0xf bank_mask:0x3
	v_mov_b32_dpp v138, v134 row_shl:8 row_mask:0xf bank_mask:0x3
	v_mov_b32_dpp v139, v135 row_shl:8 row_mask:0xf bank_mask:0x3
	v_mov_b32_dpp v144, v140 row_shl:8 row_mask:0xf bank_mask:0x3
	v_mov_b32_dpp v145, v141 row_shl:8 row_mask:0xf bank_mask:0x3
	v_mov_b32_dpp v146, v142 row_shl:8 row_mask:0xf bank_mask:0x3
	v_mov_b32_dpp v147, v143 row_shl:8 row_mask:0xf bank_mask:0x3
	v_mfma_f32_16x16x32_bf16 v[4:7], v[236:239], v[240:243], v[4:7]
	s_nop 0
	v_mfma_f32_16x16x32_bf16 v[0:3], v[136:139], v[144:147], v[0:3]
	s_nop 1
	s_lshl_b32 s7, s8, 4
	s_and_b32 s7, s7, 0x70
	v_and_b32_e32 v12, 15, v14
	s_nop 3
	v_pk_add_f32 v[4:5], v[4:5], v[0:1]
	v_lshrrev_b32_e32 v0, 2, v14
	v_and_or_b32 v13, v0, 12, s7
	v_lshl_or_b32 v0, s6, 4, v12
	v_ashrrev_i32_e32 v1, 31, v0
	v_lshlrev_b64 v[0:1], 2, v[0:1]
	v_pk_add_f32 v[2:3], v[6:7], v[2:3]
	v_lshl_add_u64 v[6:7], v[8:9], 0, v[0:1]
	v_lshlrev_b32_e32 v152, 13, v13
	v_readlane_b32 s10, v254, 8
	v_lshl_add_u64 v[8:9], v[6:7], 0, v[152:153]
	v_readlane_b32 s11, v254, 9
	global_load_dword v12, v[8:9], off
	v_mul_u32_u24_e32 v8, 0x6000, v13
	v_lshl_add_u64 v[10:11], s[10:11], 2, v[28:29]
	v_lshlrev_b32_e32 v8, 2, v8
	v_mov_b32_e32 v9, v153
	v_lshl_add_u64 v[8:9], v[10:11], 0, v[8:9]
	v_lshl_add_u64 v[8:9], v[8:9], 0, v[0:1]
	s_mov_b32 s6, 0x10364000
	v_add_co_u32_e32 v10, vcc, s6, v8
	s_mov_b32 s7, 0x20200000
	s_nop 0
	v_addc_co_u32_e32 v11, vcc, 0, v9, vcc
	global_load_dword v10, v[10:11], off
	s_mov_b32 s6, 0x1037c000
	s_waitcnt vmcnt(0)
	v_fmac_f32_e32 v12, v4, v10
	v_lshl_add_u64 v[10:11], v[28:29], 0, v[152:153]
	v_lshl_add_u64 v[10:11], v[10:11], 0, v[0:1]
	v_add_co_u32_e32 v10, vcc, s7, v10
	s_nop 1
	v_addc_co_u32_e32 v11, vcc, 0, v11, vcc
	global_store_dword v[10:11], v12, off
	v_or_b32_e32 v10, 0x2000, v152
	v_mov_b32_e32 v11, v153
	v_lshl_add_u64 v[12:13], v[6:7], 0, v[10:11]
	global_load_dword v14, v[12:13], off
	v_add_co_u32_e32 v12, vcc, s6, v8
	s_mov_b32 s6, 0x10394000
	s_nop 0
	v_addc_co_u32_e32 v13, vcc, 0, v9, vcc
	global_load_dword v4, v[12:13], off
	s_waitcnt vmcnt(0)
	v_fmac_f32_e32 v14, v5, v4
	v_lshl_add_u64 v[4:5], v[28:29], 0, v[10:11]
	v_lshl_add_u64 v[4:5], v[4:5], 0, v[0:1]
	v_add_co_u32_e32 v4, vcc, s7, v4
	s_nop 1
	v_addc_co_u32_e32 v5, vcc, 0, v5, vcc
	global_store_dword v[4:5], v14, off
	v_or_b32_e32 v4, 0x4000, v152
	v_mov_b32_e32 v5, v153
	v_lshl_add_u64 v[10:11], v[6:7], 0, v[4:5]
	global_load_dword v12, v[10:11], off
	v_add_co_u32_e32 v10, vcc, s6, v8
	v_lshl_add_u64 v[4:5], v[28:29], 0, v[4:5]
	s_nop 0
	v_addc_co_u32_e32 v11, vcc, 0, v9, vcc
	global_load_dword v10, v[10:11], off
	v_lshl_add_u64 v[4:5], v[4:5], 0, v[0:1]
	v_add_co_u32_e32 v4, vcc, s7, v4
	v_or_b32_e32 v152, 0x6000, v152
	s_nop 0
	v_addc_co_u32_e32 v5, vcc, 0, v5, vcc
	s_mov_b64 s[6:7], 0
	s_waitcnt vmcnt(0)
	v_fmac_f32_e32 v12, v2, v10
	global_store_dword v[4:5], v12, off
	v_lshl_add_u64 v[4:5], v[6:7], 0, v[152:153]
	global_load_dword v6, v[4:5], off
	v_add_co_u32_e32 v4, vcc, 0x103ac000, v8
	s_nop 1
	v_addc_co_u32_e32 v5, vcc, 0, v9, vcc
	global_load_dword v2, v[4:5], off
	s_waitcnt vmcnt(0)
	v_fmac_f32_e32 v6, v3, v2
	v_lshl_add_u64 v[2:3], v[28:29], 0, v[152:153]
	v_lshl_add_u64 v[0:1], v[2:3], 0, v[0:1]
	v_add_co_u32_e32 v0, vcc, 0x20200000, v0
	s_nop 1
	v_addc_co_u32_e32 v1, vcc, 0, v1, vcc
	global_store_dword v[0:1], v6, off
